# all s_setprio around the MFMA blocks removed
# baseline (speedup 1.0000x reference)
.LBB0_92:
	s_add_u32 s8, s6, 0xfffc0080
	s_addc_u32 s9, s7, -1
	s_add_i32 s35, 0, 0x10000
	s_cmp_eq_u32 s59, 12
	s_cselect_b32 s11, s5, s9
	s_cselect_b32 s10, s24, s8
	v_add_u32_e32 v140, s35, v165
	s_cselect_b32 s9, s47, s58
	s_cselect_b32 s8, s51, s53
	s_add_i32 s74, 0, 0x14000
	ds_read_b128 v[142:145], v140
	ds_read_b128 v[146:149], v140 offset:1024
	ds_read_b128 v[150:153], v140 offset:2048
	ds_read_b128 v[154:157], v140 offset:3072
	v_add_u32_e32 v140, s74, v165
	ds_read_b128 v[158:161], v140
	ds_read_b128 v[168:171], v140 offset:1024
	ds_read_b128 v[172:175], v140 offset:2048
	ds_read_b128 v[176:179], v140 offset:3072
	v_lshl_add_u64 v[162:163], s[6:7], 0, v[136:137]
	s_add_i32 m0, s27, 0xc000
	ds_read_b128 v[180:183], v166
	ds_read_b128 v[184:187], v166 offset:1024
	ds_read_b128 v[188:191], v166 offset:2048
	ds_read_b128 v[192:195], v166 offset:3072
	ds_read_b128 v[200:203], v166 offset:4096
	ds_read_b128 v[206:209], v166 offset:5120
	ds_read_b128 v[210:213], v166 offset:6144
	ds_read_b128 v[214:217], v166 offset:7168
	global_load_lds_dwordx4 v[162:163], off
	v_lshl_add_u64 v[162:163], s[6:7], 0, v[138:139]
	s_add_i32 m0, s27, 0xe000
	s_nop 0
	global_load_lds_dwordx4 v[162:163], off
	s_waitcnt vmcnt(8)
	s_waitcnt lgkmcnt(0)
	s_barrier
	v_mfma_f32_16x16x32_bf16 v[124:127], v[142:145], v[180:183], v[124:127]
	v_mfma_f32_16x16x32_bf16 v[120:123], v[150:153], v[180:183], v[120:123]
	v_mfma_f32_16x16x32_bf16 v[108:111], v[142:145], v[188:191], v[108:111]
	v_mfma_f32_16x16x32_bf16 v[104:107], v[150:153], v[188:191], v[104:107]
	v_mfma_f32_16x16x32_bf16 v[92:95], v[142:145], v[200:203], v[92:95]
	v_mfma_f32_16x16x32_bf16 v[88:91], v[150:153], v[200:203], v[88:91]
	v_mfma_f32_16x16x32_bf16 v[76:79], v[142:145], v[210:213], v[76:79]
	v_mfma_f32_16x16x32_bf16 v[72:75], v[150:153], v[210:213], v[72:75]
	v_mfma_f32_16x16x32_bf16 v[124:127], v[146:149], v[184:187], v[124:127]
	v_mfma_f32_16x16x32_bf16 v[120:123], v[154:157], v[184:187], v[120:123]
	v_mfma_f32_16x16x32_bf16 v[108:111], v[146:149], v[192:195], v[108:111]
	v_mfma_f32_16x16x32_bf16 v[104:107], v[154:157], v[192:195], v[104:107]
	v_mfma_f32_16x16x32_bf16 v[92:95], v[146:149], v[206:209], v[92:95]
	v_mfma_f32_16x16x32_bf16 v[88:91], v[154:157], v[206:209], v[88:91]
	v_mfma_f32_16x16x32_bf16 v[76:79], v[146:149], v[214:217], v[76:79]
	v_mfma_f32_16x16x32_bf16 v[72:75], v[154:157], v[214:217], v[72:75]
	v_mfma_f32_16x16x32_bf16 v[116:119], v[158:161], v[180:183], v[116:119]
	v_mfma_f32_16x16x32_bf16 v[112:115], v[172:175], v[180:183], v[112:115]
	v_mfma_f32_16x16x32_bf16 v[100:103], v[158:161], v[188:191], v[100:103]
	v_mfma_f32_16x16x32_bf16 v[96:99], v[172:175], v[188:191], v[96:99]
	v_mfma_f32_16x16x32_bf16 v[84:87], v[158:161], v[200:203], v[84:87]
	v_mfma_f32_16x16x32_bf16 v[80:83], v[172:175], v[200:203], v[80:83]
	v_mfma_f32_16x16x32_bf16 v[68:71], v[158:161], v[210:213], v[68:71]
	v_mfma_f32_16x16x32_bf16 v[64:67], v[172:175], v[210:213], v[64:67]
	v_mfma_f32_16x16x32_bf16 v[116:119], v[168:171], v[184:187], v[116:119]
	v_mfma_f32_16x16x32_bf16 v[112:115], v[176:179], v[184:187], v[112:115]
	v_mfma_f32_16x16x32_bf16 v[100:103], v[168:171], v[192:195], v[100:103]
	v_mfma_f32_16x16x32_bf16 v[96:99], v[176:179], v[192:195], v[96:99]
	v_mfma_f32_16x16x32_bf16 v[84:87], v[168:171], v[206:209], v[84:87]
	v_mfma_f32_16x16x32_bf16 v[80:83], v[176:179], v[206:209], v[80:83]
	v_mfma_f32_16x16x32_bf16 v[68:71], v[168:171], v[214:217], v[68:71]
	v_mfma_f32_16x16x32_bf16 v[64:67], v[176:179], v[214:217], v[64:67]
	s_barrier
	s_add_i32 s35, s35, s13
	v_lshl_add_u64 v[162:163], s[8:9], 0, v[132:133]
	s_mov_b32 m0, s35
	ds_read_b128 v[180:183], v166 offset:16384
	ds_read_b128 v[184:187], v166 offset:17408
	ds_read_b128 v[188:191], v166 offset:18432
	ds_read_b128 v[192:195], v166 offset:19456
	ds_read_b128 v[200:203], v166 offset:20480
	ds_read_b128 v[206:209], v166 offset:21504
	ds_read_b128 v[210:213], v166 offset:22528
	ds_read_b128 v[214:217], v166 offset:23552
	global_load_lds_dwordx4 v[162:163], off
	s_add_i32 m0, s35, 0x2000
	s_add_u32 s60, s8, 0x40000
	v_lshl_add_u64 v[196:197], s[8:9], 0, v[128:129]
	s_addc_u32 s61, s9, 0
	s_add_i32 s35, s74, s13
	global_load_lds_dwordx4 v[196:197], off
	v_lshl_add_u64 v[198:199], s[60:61], 0, v[132:133]
	s_mov_b32 m0, s35
	v_lshl_add_u64 v[204:205], s[10:11], 0, v[130:131]
	global_load_lds_dwordx4 v[198:199], off
	v_lshl_add_u64 v[198:199], s[60:61], 0, v[128:129]
	s_add_i32 m0, s35, 0x2000
	s_nop 0
	global_load_lds_dwordx4 v[198:199], off
	v_lshl_add_u64 v[198:199], s[10:11], 0, v[134:135]
	s_mov_b32 m0, s27
	s_nop 0
	global_load_lds_dwordx4 v[198:199], off
	s_mov_b32 m0, s28
	s_nop 0
	global_load_lds_dwordx4 v[204:205], off
	s_waitcnt vmcnt(8)
	s_waitcnt lgkmcnt(0)
	s_barrier
	v_mfma_f32_16x16x32_bf16 v[60:63], v[142:145], v[180:183], v[60:63]
	v_mfma_f32_16x16x32_bf16 v[56:59], v[150:153], v[180:183], v[56:59]
	v_mfma_f32_16x16x32_bf16 v[44:47], v[142:145], v[188:191], v[44:47]
	v_mfma_f32_16x16x32_bf16 v[40:43], v[150:153], v[188:191], v[40:43]
	v_mfma_f32_16x16x32_bf16 v[28:31], v[142:145], v[200:203], v[28:31]
	v_mfma_f32_16x16x32_bf16 v[24:27], v[150:153], v[200:203], v[24:27]
	v_mfma_f32_16x16x32_bf16 v[12:15], v[142:145], v[210:213], v[12:15]
	v_mfma_f32_16x16x32_bf16 v[8:11], v[150:153], v[210:213], v[8:11]
	v_mfma_f32_16x16x32_bf16 v[60:63], v[146:149], v[184:187], v[60:63]
	v_mfma_f32_16x16x32_bf16 v[56:59], v[154:157], v[184:187], v[56:59]
	v_mfma_f32_16x16x32_bf16 v[44:47], v[146:149], v[192:195], v[44:47]
	v_mfma_f32_16x16x32_bf16 v[40:43], v[154:157], v[192:195], v[40:43]
	v_mfma_f32_16x16x32_bf16 v[28:31], v[146:149], v[206:209], v[28:31]
	v_mfma_f32_16x16x32_bf16 v[24:27], v[154:157], v[206:209], v[24:27]
	v_mfma_f32_16x16x32_bf16 v[12:15], v[146:149], v[214:217], v[12:15]
	v_mfma_f32_16x16x32_bf16 v[8:11], v[154:157], v[214:217], v[8:11]
	v_mfma_f32_16x16x32_bf16 v[52:55], v[158:161], v[180:183], v[52:55]
	v_mfma_f32_16x16x32_bf16 v[48:51], v[172:175], v[180:183], v[48:51]
	v_mfma_f32_16x16x32_bf16 v[36:39], v[158:161], v[188:191], v[36:39]
	v_mfma_f32_16x16x32_bf16 v[32:35], v[172:175], v[188:191], v[32:35]
	v_mfma_f32_16x16x32_bf16 v[20:23], v[158:161], v[200:203], v[20:23]
	v_mfma_f32_16x16x32_bf16 v[16:19], v[172:175], v[200:203], v[16:19]
	v_mfma_f32_16x16x32_bf16 v[4:7], v[158:161], v[210:213], v[4:7]
	v_mfma_f32_16x16x32_bf16 v[0:3], v[172:175], v[210:213], v[0:3]
	v_mfma_f32_16x16x32_bf16 v[52:55], v[168:171], v[184:187], v[52:55]
	v_mfma_f32_16x16x32_bf16 v[48:51], v[176:179], v[184:187], v[48:51]
	v_mfma_f32_16x16x32_bf16 v[36:39], v[168:171], v[192:195], v[36:39]
	v_mfma_f32_16x16x32_bf16 v[32:35], v[176:179], v[192:195], v[32:35]
	v_mfma_f32_16x16x32_bf16 v[20:23], v[168:171], v[206:209], v[20:23]
	v_mfma_f32_16x16x32_bf16 v[16:19], v[176:179], v[206:209], v[16:19]
	v_mfma_f32_16x16x32_bf16 v[4:7], v[168:171], v[214:217], v[4:7]
	v_mfma_f32_16x16x32_bf16 v[0:3], v[176:179], v[214:217], v[0:3]
	s_barrier
	s_add_i32 s35, 0, 0x18000
	v_add_u32_e32 v140, s35, v165
	s_add_i32 s60, 0, 0x1c000
	ds_read_b128 v[142:145], v140
	ds_read_b128 v[146:149], v140 offset:1024
	ds_read_b128 v[150:153], v140 offset:2048
	ds_read_b128 v[154:157], v140 offset:3072
	v_add_u32_e32 v140, s60, v165
	ds_read_b128 v[158:161], v140
	ds_read_b128 v[168:171], v140 offset:1024
	ds_read_b128 v[172:175], v140 offset:2048
	ds_read_b128 v[176:179], v140 offset:3072
	s_add_u32 s10, s10, 0x40000
	s_addc_u32 s11, s11, 0
	s_mov_b32 m0, s29
	v_lshl_add_u64 v[218:219], s[10:11], 0, v[134:135]
	ds_read_b128 v[180:183], v166 offset:32768
	ds_read_b128 v[184:187], v166 offset:33792
	ds_read_b128 v[188:191], v166 offset:34816
	ds_read_b128 v[192:195], v166 offset:35840
	ds_read_b128 v[200:203], v166 offset:36864
	ds_read_b128 v[206:209], v166 offset:37888
	ds_read_b128 v[210:213], v166 offset:38912
	ds_read_b128 v[214:217], v166 offset:39936
	global_load_lds_dwordx4 v[218:219], off
	v_lshl_add_u64 v[218:219], s[10:11], 0, v[130:131]
	s_mov_b32 m0, s38
	s_nop 0
	global_load_lds_dwordx4 v[218:219], off
	s_waitcnt vmcnt(8)
	s_waitcnt lgkmcnt(0)
	s_barrier
	v_mfma_f32_16x16x32_bf16 v[124:127], v[142:145], v[180:183], v[124:127]
	v_mfma_f32_16x16x32_bf16 v[120:123], v[150:153], v[180:183], v[120:123]
	v_mfma_f32_16x16x32_bf16 v[108:111], v[142:145], v[188:191], v[108:111]
	v_mfma_f32_16x16x32_bf16 v[104:107], v[150:153], v[188:191], v[104:107]
	v_mfma_f32_16x16x32_bf16 v[92:95], v[142:145], v[200:203], v[92:95]
	v_mfma_f32_16x16x32_bf16 v[88:91], v[150:153], v[200:203], v[88:91]
	v_mfma_f32_16x16x32_bf16 v[76:79], v[142:145], v[210:213], v[76:79]
	v_mfma_f32_16x16x32_bf16 v[72:75], v[150:153], v[210:213], v[72:75]
	v_mfma_f32_16x16x32_bf16 v[124:127], v[146:149], v[184:187], v[124:127]
	v_mfma_f32_16x16x32_bf16 v[120:123], v[154:157], v[184:187], v[120:123]
	v_mfma_f32_16x16x32_bf16 v[108:111], v[146:149], v[192:195], v[108:111]
	v_mfma_f32_16x16x32_bf16 v[104:107], v[154:157], v[192:195], v[104:107]
	v_mfma_f32_16x16x32_bf16 v[92:95], v[146:149], v[206:209], v[92:95]
	v_mfma_f32_16x16x32_bf16 v[88:91], v[154:157], v[206:209], v[88:91]
	v_mfma_f32_16x16x32_bf16 v[76:79], v[146:149], v[214:217], v[76:79]
	v_mfma_f32_16x16x32_bf16 v[72:75], v[154:157], v[214:217], v[72:75]
	v_mfma_f32_16x16x32_bf16 v[116:119], v[158:161], v[180:183], v[116:119]
	v_mfma_f32_16x16x32_bf16 v[112:115], v[172:175], v[180:183], v[112:115]
	v_mfma_f32_16x16x32_bf16 v[100:103], v[158:161], v[188:191], v[100:103]
	v_mfma_f32_16x16x32_bf16 v[96:99], v[172:175], v[188:191], v[96:99]
	v_mfma_f32_16x16x32_bf16 v[84:87], v[158:161], v[200:203], v[84:87]
	v_mfma_f32_16x16x32_bf16 v[80:83], v[172:175], v[200:203], v[80:83]
	v_mfma_f32_16x16x32_bf16 v[68:71], v[158:161], v[210:213], v[68:71]
	v_mfma_f32_16x16x32_bf16 v[64:67], v[172:175], v[210:213], v[64:67]
	v_mfma_f32_16x16x32_bf16 v[116:119], v[168:171], v[184:187], v[116:119]
	v_mfma_f32_16x16x32_bf16 v[112:115], v[176:179], v[184:187], v[112:115]
	v_mfma_f32_16x16x32_bf16 v[100:103], v[168:171], v[192:195], v[100:103]
	v_mfma_f32_16x16x32_bf16 v[96:99], v[176:179], v[192:195], v[96:99]
	v_mfma_f32_16x16x32_bf16 v[84:87], v[168:171], v[206:209], v[84:87]
	v_mfma_f32_16x16x32_bf16 v[80:83], v[176:179], v[206:209], v[80:83]
	v_mfma_f32_16x16x32_bf16 v[68:71], v[168:171], v[214:217], v[68:71]
	v_mfma_f32_16x16x32_bf16 v[64:67], v[176:179], v[214:217], v[64:67]
	s_barrier
	s_add_i32 s10, s35, s13
	v_lshl_add_u64 v[162:163], v[162:163], 0, s[36:37]
	s_mov_b32 m0, s10
	ds_read_b128 v[180:183], v166 offset:49152
	ds_read_b128 v[184:187], v166 offset:50176
	ds_read_b128 v[188:191], v166 offset:51200
	ds_read_b128 v[192:195], v166 offset:52224
	ds_read_b128 v[200:203], v166 offset:53248
	ds_read_b128 v[206:209], v166 offset:54272
	ds_read_b128 v[210:213], v166 offset:55296
	ds_read_b128 v[214:217], v166 offset:56320
	global_load_lds_dwordx4 v[162:163], off
	s_add_i32 m0, s10, 0x2000
	s_add_u32 s8, s8, 0x40080
	v_lshl_add_u64 v[162:163], v[196:197], 0, s[36:37]
	s_addc_u32 s9, s9, 0
	s_add_i32 s10, s60, s13
	global_load_lds_dwordx4 v[162:163], off
	v_lshl_add_u64 v[162:163], s[8:9], 0, v[132:133]
	s_mov_b32 m0, s10
	s_nop 0
	global_load_lds_dwordx4 v[162:163], off
	v_lshl_add_u64 v[162:163], s[8:9], 0, v[128:129]
	s_add_i32 m0, s10, 0x2000
	s_nop 0
	global_load_lds_dwordx4 v[162:163], off
	v_lshl_add_u64 v[162:163], v[198:199], 0, s[36:37]
	s_mov_b32 m0, s42
	s_nop 0
	global_load_lds_dwordx4 v[162:163], off
	v_lshl_add_u64 v[162:163], v[204:205], 0, s[36:37]
	s_mov_b32 m0, s43
	s_nop 0
	global_load_lds_dwordx4 v[162:163], off
	s_waitcnt vmcnt(8)
	s_waitcnt lgkmcnt(0)
	s_barrier
	v_mfma_f32_16x16x32_bf16 v[60:63], v[142:145], v[180:183], v[60:63]
	v_mfma_f32_16x16x32_bf16 v[56:59], v[150:153], v[180:183], v[56:59]
	v_mfma_f32_16x16x32_bf16 v[44:47], v[142:145], v[188:191], v[44:47]
	v_mfma_f32_16x16x32_bf16 v[40:43], v[150:153], v[188:191], v[40:43]
	v_mfma_f32_16x16x32_bf16 v[28:31], v[142:145], v[200:203], v[28:31]
	v_mfma_f32_16x16x32_bf16 v[24:27], v[150:153], v[200:203], v[24:27]
	v_mfma_f32_16x16x32_bf16 v[12:15], v[142:145], v[210:213], v[12:15]
	v_mfma_f32_16x16x32_bf16 v[8:11], v[150:153], v[210:213], v[8:11]
	v_mfma_f32_16x16x32_bf16 v[60:63], v[146:149], v[184:187], v[60:63]
	v_mfma_f32_16x16x32_bf16 v[56:59], v[154:157], v[184:187], v[56:59]
	v_mfma_f32_16x16x32_bf16 v[44:47], v[146:149], v[192:195], v[44:47]
	v_mfma_f32_16x16x32_bf16 v[40:43], v[154:157], v[192:195], v[40:43]
	v_mfma_f32_16x16x32_bf16 v[28:31], v[146:149], v[206:209], v[28:31]
	v_mfma_f32_16x16x32_bf16 v[24:27], v[154:157], v[206:209], v[24:27]
	v_mfma_f32_16x16x32_bf16 v[12:15], v[146:149], v[214:217], v[12:15]
	v_mfma_f32_16x16x32_bf16 v[8:11], v[154:157], v[214:217], v[8:11]
	v_mfma_f32_16x16x32_bf16 v[52:55], v[158:161], v[180:183], v[52:55]
	v_mfma_f32_16x16x32_bf16 v[48:51], v[172:175], v[180:183], v[48:51]
	v_mfma_f32_16x16x32_bf16 v[36:39], v[158:161], v[188:191], v[36:39]
	v_mfma_f32_16x16x32_bf16 v[32:35], v[172:175], v[188:191], v[32:35]
	v_mfma_f32_16x16x32_bf16 v[20:23], v[158:161], v[200:203], v[20:23]
	v_mfma_f32_16x16x32_bf16 v[16:19], v[172:175], v[200:203], v[16:19]
	v_mfma_f32_16x16x32_bf16 v[4:7], v[158:161], v[210:213], v[4:7]
	v_mfma_f32_16x16x32_bf16 v[0:3], v[172:175], v[210:213], v[0:3]
	v_mfma_f32_16x16x32_bf16 v[52:55], v[168:171], v[184:187], v[52:55]
	v_mfma_f32_16x16x32_bf16 v[48:51], v[176:179], v[184:187], v[48:51]
	v_mfma_f32_16x16x32_bf16 v[36:39], v[168:171], v[192:195], v[36:39]
	v_mfma_f32_16x16x32_bf16 v[32:35], v[176:179], v[192:195], v[32:35]
	v_mfma_f32_16x16x32_bf16 v[20:23], v[168:171], v[206:209], v[20:23]
	v_mfma_f32_16x16x32_bf16 v[16:19], v[176:179], v[206:209], v[16:19]
	v_mfma_f32_16x16x32_bf16 v[4:7], v[168:171], v[214:217], v[4:7]
	v_mfma_f32_16x16x32_bf16 v[0:3], v[176:179], v[214:217], v[0:3]
	s_barrier
	s_add_i32 s59, s59, 2
	s_add_u32 s6, s6, 0x100
	s_addc_u32 s7, s7, 0
	s_add_u32 s53, s53, 0x100
	s_addc_u32 s58, s58, 0
	s_cmp_gt_u32 s59, 13
	s_cbranch_scc0 .LBB0_92
	s_and_b64 vcc, exec, s[48:49]
	s_cbranch_vccz .LBB0_95
	s_barrier

.LBB0_147:
	s_add_u32 s8, s6, 0xfffc0080
	s_addc_u32 s9, s7, -1
	s_add_i32 s35, 0, 0x10000
	s_cmp_eq_u32 s74, 12
	s_cselect_b32 s11, s24, s9
	s_cselect_b32 s10, s38, s8
	s_cselect_b32 s9, s53, s61
	s_cselect_b32 s8, s55, s60
	s_add_i32 s75, 0, 0x14000
	v_add_u32_e32 v142, s35, v178
	v_add_u32_e32 v168, s75, v178
	ds_read_b128 v[128:131], v142
	ds_read_b128 v[132:135], v142 offset:1024
	ds_read_b128 v[136:139], v142 offset:2048
	ds_read_b128 v[142:145], v142 offset:3072
	ds_read_b128 v[146:149], v168
	ds_read_b128 v[150:153], v168 offset:1024
	ds_read_b128 v[154:157], v168 offset:2048
	ds_read_b128 v[168:171], v168 offset:3072
	v_lshl_add_u64 v[176:177], s[6:7], 0, v[164:165]
	s_add_i32 m0, s15, 0xc000
	ds_read_b128 v[172:175], v179
	ds_read_b128 v[180:183], v179 offset:1024
	ds_read_b128 v[184:187], v179 offset:2048
	ds_read_b128 v[188:191], v179 offset:3072
	ds_read_b128 v[192:195], v179 offset:4096
	ds_read_b128 v[200:203], v179 offset:5120
	ds_read_b128 v[206:209], v179 offset:6144
	ds_read_b128 v[210:213], v179 offset:7168
	global_load_lds_dwordx4 v[176:177], off
	v_lshl_add_u64 v[176:177], s[6:7], 0, v[166:167]
	s_add_i32 m0, s15, 0xe000
	s_nop 0
	global_load_lds_dwordx4 v[176:177], off
	s_waitcnt vmcnt(8)
	s_waitcnt lgkmcnt(0)
	s_barrier
	v_mfma_f32_16x16x32_bf16 v[124:127], v[128:131], v[172:175], v[124:127]
	v_mfma_f32_16x16x32_bf16 v[120:123], v[136:139], v[172:175], v[120:123]
	v_mfma_f32_16x16x32_bf16 v[108:111], v[128:131], v[184:187], v[108:111]
	v_mfma_f32_16x16x32_bf16 v[104:107], v[136:139], v[184:187], v[104:107]
	v_mfma_f32_16x16x32_bf16 v[92:95], v[128:131], v[192:195], v[92:95]
	v_mfma_f32_16x16x32_bf16 v[88:91], v[136:139], v[192:195], v[88:91]
	v_mfma_f32_16x16x32_bf16 v[76:79], v[128:131], v[206:209], v[76:79]
	v_mfma_f32_16x16x32_bf16 v[72:75], v[136:139], v[206:209], v[72:75]
	v_mfma_f32_16x16x32_bf16 v[124:127], v[132:135], v[180:183], v[124:127]
	v_mfma_f32_16x16x32_bf16 v[120:123], v[142:145], v[180:183], v[120:123]
	v_mfma_f32_16x16x32_bf16 v[108:111], v[132:135], v[188:191], v[108:111]
	v_mfma_f32_16x16x32_bf16 v[104:107], v[142:145], v[188:191], v[104:107]
	v_mfma_f32_16x16x32_bf16 v[92:95], v[132:135], v[200:203], v[92:95]
	v_mfma_f32_16x16x32_bf16 v[88:91], v[142:145], v[200:203], v[88:91]
	v_mfma_f32_16x16x32_bf16 v[76:79], v[132:135], v[210:213], v[76:79]
	v_mfma_f32_16x16x32_bf16 v[72:75], v[142:145], v[210:213], v[72:75]
	v_mfma_f32_16x16x32_bf16 v[116:119], v[146:149], v[172:175], v[116:119]
	v_mfma_f32_16x16x32_bf16 v[112:115], v[154:157], v[172:175], v[112:115]
	v_mfma_f32_16x16x32_bf16 v[100:103], v[146:149], v[184:187], v[100:103]
	v_mfma_f32_16x16x32_bf16 v[96:99], v[154:157], v[184:187], v[96:99]
	v_mfma_f32_16x16x32_bf16 v[84:87], v[146:149], v[192:195], v[84:87]
	v_mfma_f32_16x16x32_bf16 v[80:83], v[154:157], v[192:195], v[80:83]
	v_mfma_f32_16x16x32_bf16 v[68:71], v[146:149], v[206:209], v[68:71]
	v_mfma_f32_16x16x32_bf16 v[64:67], v[154:157], v[206:209], v[64:67]
	v_mfma_f32_16x16x32_bf16 v[116:119], v[150:153], v[180:183], v[116:119]
	v_mfma_f32_16x16x32_bf16 v[112:115], v[168:171], v[180:183], v[112:115]
	v_mfma_f32_16x16x32_bf16 v[100:103], v[150:153], v[188:191], v[100:103]
	v_mfma_f32_16x16x32_bf16 v[96:99], v[168:171], v[188:191], v[96:99]
	v_mfma_f32_16x16x32_bf16 v[84:87], v[150:153], v[200:203], v[84:87]
	v_mfma_f32_16x16x32_bf16 v[80:83], v[168:171], v[200:203], v[80:83]
	v_mfma_f32_16x16x32_bf16 v[68:71], v[150:153], v[210:213], v[68:71]
	v_mfma_f32_16x16x32_bf16 v[64:67], v[168:171], v[210:213], v[64:67]
	s_barrier
	s_add_i32 s35, s35, s13
	v_lshl_add_u64 v[176:177], s[8:9], 0, v[140:141]
	s_mov_b32 m0, s35
	ds_read_b128 v[172:175], v179 offset:16384
	ds_read_b128 v[180:183], v179 offset:17408
	ds_read_b128 v[184:187], v179 offset:18432
	ds_read_b128 v[188:191], v179 offset:19456
	ds_read_b128 v[192:195], v179 offset:20480
	ds_read_b128 v[200:203], v179 offset:21504
	ds_read_b128 v[206:209], v179 offset:22528
	ds_read_b128 v[210:213], v179 offset:23552
	global_load_lds_dwordx4 v[176:177], off
	s_add_i32 m0, s35, 0x2000
	s_add_u32 s84, s8, 0x40000
	v_lshl_add_u64 v[196:197], s[8:9], 0, v[158:159]
	s_addc_u32 s85, s9, 0
	s_add_i32 s35, s75, s13
	global_load_lds_dwordx4 v[196:197], off
	v_lshl_add_u64 v[198:199], s[84:85], 0, v[140:141]
	s_mov_b32 m0, s35
	v_lshl_add_u64 v[204:205], s[10:11], 0, v[160:161]
	global_load_lds_dwordx4 v[198:199], off
	v_lshl_add_u64 v[198:199], s[84:85], 0, v[158:159]
	s_add_i32 m0, s35, 0x2000
	s_nop 0
	global_load_lds_dwordx4 v[198:199], off
	v_lshl_add_u64 v[198:199], s[10:11], 0, v[162:163]
	s_mov_b32 m0, s15
	s_nop 0
	global_load_lds_dwordx4 v[198:199], off
	s_mov_b32 m0, s26
	s_nop 0
	global_load_lds_dwordx4 v[204:205], off
	s_waitcnt vmcnt(8)
	s_waitcnt lgkmcnt(0)
	s_barrier
	v_mfma_f32_16x16x32_bf16 v[60:63], v[128:131], v[172:175], v[60:63]
	v_mfma_f32_16x16x32_bf16 v[56:59], v[136:139], v[172:175], v[56:59]
	v_mfma_f32_16x16x32_bf16 v[44:47], v[128:131], v[184:187], v[44:47]
	v_mfma_f32_16x16x32_bf16 v[40:43], v[136:139], v[184:187], v[40:43]
	v_mfma_f32_16x16x32_bf16 v[28:31], v[128:131], v[192:195], v[28:31]
	v_mfma_f32_16x16x32_bf16 v[24:27], v[136:139], v[192:195], v[24:27]
	v_mfma_f32_16x16x32_bf16 v[12:15], v[128:131], v[206:209], v[12:15]
	v_mfma_f32_16x16x32_bf16 v[8:11], v[136:139], v[206:209], v[8:11]
	v_mfma_f32_16x16x32_bf16 v[60:63], v[132:135], v[180:183], v[60:63]
	v_mfma_f32_16x16x32_bf16 v[56:59], v[142:145], v[180:183], v[56:59]
	v_mfma_f32_16x16x32_bf16 v[44:47], v[132:135], v[188:191], v[44:47]
	v_mfma_f32_16x16x32_bf16 v[40:43], v[142:145], v[188:191], v[40:43]
	v_mfma_f32_16x16x32_bf16 v[28:31], v[132:135], v[200:203], v[28:31]
	v_mfma_f32_16x16x32_bf16 v[24:27], v[142:145], v[200:203], v[24:27]
	v_mfma_f32_16x16x32_bf16 v[12:15], v[132:135], v[210:213], v[12:15]
	v_mfma_f32_16x16x32_bf16 v[8:11], v[142:145], v[210:213], v[8:11]
	v_mfma_f32_16x16x32_bf16 v[52:55], v[146:149], v[172:175], v[52:55]
	v_mfma_f32_16x16x32_bf16 v[48:51], v[154:157], v[172:175], v[48:51]
	v_mfma_f32_16x16x32_bf16 v[36:39], v[146:149], v[184:187], v[36:39]
	v_mfma_f32_16x16x32_bf16 v[32:35], v[154:157], v[184:187], v[32:35]
	v_mfma_f32_16x16x32_bf16 v[20:23], v[146:149], v[192:195], v[20:23]
	v_mfma_f32_16x16x32_bf16 v[16:19], v[154:157], v[192:195], v[16:19]
	v_mfma_f32_16x16x32_bf16 v[4:7], v[146:149], v[206:209], v[4:7]
	v_mfma_f32_16x16x32_bf16 v[0:3], v[154:157], v[206:209], v[0:3]
	v_mfma_f32_16x16x32_bf16 v[52:55], v[150:153], v[180:183], v[52:55]
	v_mfma_f32_16x16x32_bf16 v[48:51], v[168:171], v[180:183], v[48:51]
	v_mfma_f32_16x16x32_bf16 v[36:39], v[150:153], v[188:191], v[36:39]
	v_mfma_f32_16x16x32_bf16 v[32:35], v[168:171], v[188:191], v[32:35]
	v_mfma_f32_16x16x32_bf16 v[20:23], v[150:153], v[200:203], v[20:23]
	v_mfma_f32_16x16x32_bf16 v[16:19], v[168:171], v[200:203], v[16:19]
	v_mfma_f32_16x16x32_bf16 v[4:7], v[150:153], v[210:213], v[4:7]
	v_mfma_f32_16x16x32_bf16 v[0:3], v[168:171], v[210:213], v[0:3]
	s_barrier
	s_add_i32 s35, 0, 0x18000
	s_add_i32 s75, 0, 0x1c000
	v_add_u32_e32 v142, s35, v178
	v_add_u32_e32 v168, s75, v178
	ds_read_b128 v[128:131], v142
	ds_read_b128 v[132:135], v142 offset:1024
	ds_read_b128 v[136:139], v142 offset:2048
	ds_read_b128 v[142:145], v142 offset:3072
	ds_read_b128 v[146:149], v168
	ds_read_b128 v[150:153], v168 offset:1024
	ds_read_b128 v[154:157], v168 offset:2048
	ds_read_b128 v[168:171], v168 offset:3072
	s_add_u32 s10, s10, 0x40000
	s_addc_u32 s11, s11, 0
	s_mov_b32 m0, s27
	v_lshl_add_u64 v[214:215], s[10:11], 0, v[162:163]
	ds_read_b128 v[172:175], v179 offset:32768
	ds_read_b128 v[180:183], v179 offset:33792
	ds_read_b128 v[184:187], v179 offset:34816
	ds_read_b128 v[188:191], v179 offset:35840
	ds_read_b128 v[192:195], v179 offset:36864
	ds_read_b128 v[200:203], v179 offset:37888
	ds_read_b128 v[206:209], v179 offset:38912
	ds_read_b128 v[210:213], v179 offset:39936
	global_load_lds_dwordx4 v[214:215], off
	v_lshl_add_u64 v[214:215], s[10:11], 0, v[160:161]
	s_mov_b32 m0, s28
	s_nop 0
	global_load_lds_dwordx4 v[214:215], off
	s_waitcnt vmcnt(8)
	s_waitcnt lgkmcnt(0)
	s_barrier
	v_mfma_f32_16x16x32_bf16 v[124:127], v[128:131], v[172:175], v[124:127]
	v_mfma_f32_16x16x32_bf16 v[120:123], v[136:139], v[172:175], v[120:123]
	v_mfma_f32_16x16x32_bf16 v[108:111], v[128:131], v[184:187], v[108:111]
	v_mfma_f32_16x16x32_bf16 v[104:107], v[136:139], v[184:187], v[104:107]
	v_mfma_f32_16x16x32_bf16 v[92:95], v[128:131], v[192:195], v[92:95]
	v_mfma_f32_16x16x32_bf16 v[88:91], v[136:139], v[192:195], v[88:91]
	v_mfma_f32_16x16x32_bf16 v[76:79], v[128:131], v[206:209], v[76:79]
	v_mfma_f32_16x16x32_bf16 v[72:75], v[136:139], v[206:209], v[72:75]
	v_mfma_f32_16x16x32_bf16 v[124:127], v[132:135], v[180:183], v[124:127]
	v_mfma_f32_16x16x32_bf16 v[120:123], v[142:145], v[180:183], v[120:123]
	v_mfma_f32_16x16x32_bf16 v[108:111], v[132:135], v[188:191], v[108:111]
	v_mfma_f32_16x16x32_bf16 v[104:107], v[142:145], v[188:191], v[104:107]
	v_mfma_f32_16x16x32_bf16 v[92:95], v[132:135], v[200:203], v[92:95]
	v_mfma_f32_16x16x32_bf16 v[88:91], v[142:145], v[200:203], v[88:91]
	v_mfma_f32_16x16x32_bf16 v[76:79], v[132:135], v[210:213], v[76:79]
	v_mfma_f32_16x16x32_bf16 v[72:75], v[142:145], v[210:213], v[72:75]
	v_mfma_f32_16x16x32_bf16 v[116:119], v[146:149], v[172:175], v[116:119]
	v_mfma_f32_16x16x32_bf16 v[112:115], v[154:157], v[172:175], v[112:115]
	v_mfma_f32_16x16x32_bf16 v[100:103], v[146:149], v[184:187], v[100:103]
	v_mfma_f32_16x16x32_bf16 v[96:99], v[154:157], v[184:187], v[96:99]
	v_mfma_f32_16x16x32_bf16 v[84:87], v[146:149], v[192:195], v[84:87]
	v_mfma_f32_16x16x32_bf16 v[80:83], v[154:157], v[192:195], v[80:83]
	v_mfma_f32_16x16x32_bf16 v[68:71], v[146:149], v[206:209], v[68:71]
	v_mfma_f32_16x16x32_bf16 v[64:67], v[154:157], v[206:209], v[64:67]
	v_mfma_f32_16x16x32_bf16 v[116:119], v[150:153], v[180:183], v[116:119]
	v_mfma_f32_16x16x32_bf16 v[112:115], v[168:171], v[180:183], v[112:115]
	v_mfma_f32_16x16x32_bf16 v[100:103], v[150:153], v[188:191], v[100:103]
	v_mfma_f32_16x16x32_bf16 v[96:99], v[168:171], v[188:191], v[96:99]
	v_mfma_f32_16x16x32_bf16 v[84:87], v[150:153], v[200:203], v[84:87]
	v_mfma_f32_16x16x32_bf16 v[80:83], v[168:171], v[200:203], v[80:83]
	v_mfma_f32_16x16x32_bf16 v[68:71], v[150:153], v[210:213], v[68:71]
	v_mfma_f32_16x16x32_bf16 v[64:67], v[168:171], v[210:213], v[64:67]
	s_barrier
	s_add_i32 s10, s35, s13
	v_lshl_add_u64 v[176:177], v[176:177], 0, s[36:37]
	s_mov_b32 m0, s10
	ds_read_b128 v[172:175], v179 offset:49152
	ds_read_b128 v[180:183], v179 offset:50176
	ds_read_b128 v[184:187], v179 offset:51200
	ds_read_b128 v[188:191], v179 offset:52224
	ds_read_b128 v[192:195], v179 offset:53248
	ds_read_b128 v[200:203], v179 offset:54272
	ds_read_b128 v[206:209], v179 offset:55296
	ds_read_b128 v[210:213], v179 offset:56320
	global_load_lds_dwordx4 v[176:177], off
	s_add_i32 m0, s10, 0x2000
	s_add_u32 s8, s8, 0x40080
	v_lshl_add_u64 v[176:177], v[196:197], 0, s[36:37]
	s_addc_u32 s9, s9, 0
	s_add_i32 s10, s75, s13
	global_load_lds_dwordx4 v[176:177], off
	v_lshl_add_u64 v[176:177], s[8:9], 0, v[140:141]
	s_mov_b32 m0, s10
	s_nop 0
	global_load_lds_dwordx4 v[176:177], off
	v_lshl_add_u64 v[176:177], s[8:9], 0, v[158:159]
	s_add_i32 m0, s10, 0x2000
	s_nop 0
	global_load_lds_dwordx4 v[176:177], off
	v_lshl_add_u64 v[176:177], v[198:199], 0, s[36:37]
	s_mov_b32 m0, s29
	s_nop 0
	global_load_lds_dwordx4 v[176:177], off
	v_lshl_add_u64 v[176:177], v[204:205], 0, s[36:37]
	s_mov_b32 m0, s42
	s_nop 0
	global_load_lds_dwordx4 v[176:177], off
	s_waitcnt vmcnt(8)
	s_waitcnt lgkmcnt(0)
	s_barrier
	v_mfma_f32_16x16x32_bf16 v[60:63], v[128:131], v[172:175], v[60:63]
	v_mfma_f32_16x16x32_bf16 v[56:59], v[136:139], v[172:175], v[56:59]
	v_mfma_f32_16x16x32_bf16 v[44:47], v[128:131], v[184:187], v[44:47]
	v_mfma_f32_16x16x32_bf16 v[40:43], v[136:139], v[184:187], v[40:43]
	v_mfma_f32_16x16x32_bf16 v[28:31], v[128:131], v[192:195], v[28:31]
	v_mfma_f32_16x16x32_bf16 v[24:27], v[136:139], v[192:195], v[24:27]
	v_mfma_f32_16x16x32_bf16 v[12:15], v[128:131], v[206:209], v[12:15]
	v_mfma_f32_16x16x32_bf16 v[8:11], v[136:139], v[206:209], v[8:11]
	v_mfma_f32_16x16x32_bf16 v[60:63], v[132:135], v[180:183], v[60:63]
	v_mfma_f32_16x16x32_bf16 v[56:59], v[142:145], v[180:183], v[56:59]
	v_mfma_f32_16x16x32_bf16 v[44:47], v[132:135], v[188:191], v[44:47]
	v_mfma_f32_16x16x32_bf16 v[40:43], v[142:145], v[188:191], v[40:43]
	v_mfma_f32_16x16x32_bf16 v[28:31], v[132:135], v[200:203], v[28:31]
	v_mfma_f32_16x16x32_bf16 v[24:27], v[142:145], v[200:203], v[24:27]
	v_mfma_f32_16x16x32_bf16 v[12:15], v[132:135], v[210:213], v[12:15]
	v_mfma_f32_16x16x32_bf16 v[8:11], v[142:145], v[210:213], v[8:11]
	v_mfma_f32_16x16x32_bf16 v[52:55], v[146:149], v[172:175], v[52:55]
	v_mfma_f32_16x16x32_bf16 v[48:51], v[154:157], v[172:175], v[48:51]
	v_mfma_f32_16x16x32_bf16 v[36:39], v[146:149], v[184:187], v[36:39]
	v_mfma_f32_16x16x32_bf16 v[32:35], v[154:157], v[184:187], v[32:35]
	v_mfma_f32_16x16x32_bf16 v[20:23], v[146:149], v[192:195], v[20:23]
	v_mfma_f32_16x16x32_bf16 v[16:19], v[154:157], v[192:195], v[16:19]
	v_mfma_f32_16x16x32_bf16 v[4:7], v[146:149], v[206:209], v[4:7]
	v_mfma_f32_16x16x32_bf16 v[0:3], v[154:157], v[206:209], v[0:3]
	v_mfma_f32_16x16x32_bf16 v[52:55], v[150:153], v[180:183], v[52:55]
	v_mfma_f32_16x16x32_bf16 v[48:51], v[168:171], v[180:183], v[48:51]
	v_mfma_f32_16x16x32_bf16 v[36:39], v[150:153], v[188:191], v[36:39]
	v_mfma_f32_16x16x32_bf16 v[32:35], v[168:171], v[188:191], v[32:35]
	v_mfma_f32_16x16x32_bf16 v[20:23], v[150:153], v[200:203], v[20:23]
	v_mfma_f32_16x16x32_bf16 v[16:19], v[168:171], v[200:203], v[16:19]
	v_mfma_f32_16x16x32_bf16 v[4:7], v[150:153], v[210:213], v[4:7]
	v_mfma_f32_16x16x32_bf16 v[0:3], v[168:171], v[210:213], v[0:3]
	s_barrier
	s_add_i32 s74, s74, 2
	s_add_u32 s6, s6, 0x100
	s_addc_u32 s7, s7, 0
	s_add_u32 s60, s60, 0x100
	s_addc_u32 s61, s61, 0
	s_cmp_gt_u32 s74, 13
	s_cbranch_scc0 .LBB0_147
	s_and_b64 vcc, exec, s[50:51]
	s_cbranch_vccz .LBB0_150
	s_barrier

.LBB0_234:
	s_add_u32 s8, s6, 0xfffc0080
	s_addc_u32 s9, s7, -1
	s_add_i32 s35, 0, 0x10000
	s_cmp_eq_u32 s53, 12
	s_cselect_b32 s11, s4, s9
	s_cselect_b32 s10, s5, s8
	v_add_u32_e32 v140, s35, v206
	s_cselect_b32 s9, s24, s51
	s_cselect_b32 s8, s42, s43
	s_add_i32 s76, 0, 0x14000
	ds_read_b128 v[142:145], v140
	ds_read_b128 v[146:149], v140 offset:1024
	ds_read_b128 v[150:153], v140 offset:2048
	ds_read_b128 v[154:157], v140 offset:3072
	v_add_u32_e32 v140, s76, v206
	ds_read_b128 v[158:161], v140
	ds_read_b128 v[162:165], v140 offset:1024
	ds_read_b128 v[166:169], v140 offset:2048
	ds_read_b128 v[170:173], v140 offset:3072
	v_lshl_add_u64 v[198:199], s[6:7], 0, v[136:137]
	s_add_i32 m0, s15, 0xc000
	ds_read_b128 v[174:177], v207
	ds_read_b128 v[178:181], v207 offset:1024
	ds_read_b128 v[182:185], v207 offset:2048
	ds_read_b128 v[186:189], v207 offset:3072
	ds_read_b128 v[190:193], v207 offset:4096
	ds_read_b128 v[194:197], v207 offset:5120
	ds_read_b128 v[200:203], v207 offset:6144
	ds_read_b128 v[208:211], v207 offset:7168
	global_load_lds_dwordx4 v[198:199], off
	v_lshl_add_u64 v[198:199], s[6:7], 0, v[138:139]
	s_add_i32 m0, s15, 0xe000
	s_nop 0
	global_load_lds_dwordx4 v[198:199], off
	s_waitcnt vmcnt(8)
	s_waitcnt lgkmcnt(0)
	s_barrier
	v_mfma_f32_16x16x32_bf16 v[124:127], v[142:145], v[174:177], v[124:127]
	v_mfma_f32_16x16x32_bf16 v[120:123], v[150:153], v[174:177], v[120:123]
	v_mfma_f32_16x16x32_bf16 v[108:111], v[142:145], v[182:185], v[108:111]
	v_mfma_f32_16x16x32_bf16 v[104:107], v[150:153], v[182:185], v[104:107]
	v_mfma_f32_16x16x32_bf16 v[92:95], v[142:145], v[190:193], v[92:95]
	v_mfma_f32_16x16x32_bf16 v[88:91], v[150:153], v[190:193], v[88:91]
	v_mfma_f32_16x16x32_bf16 v[76:79], v[142:145], v[200:203], v[76:79]
	v_mfma_f32_16x16x32_bf16 v[72:75], v[150:153], v[200:203], v[72:75]
	v_mfma_f32_16x16x32_bf16 v[124:127], v[146:149], v[178:181], v[124:127]
	v_mfma_f32_16x16x32_bf16 v[120:123], v[154:157], v[178:181], v[120:123]
	v_mfma_f32_16x16x32_bf16 v[108:111], v[146:149], v[186:189], v[108:111]
	v_mfma_f32_16x16x32_bf16 v[104:107], v[154:157], v[186:189], v[104:107]
	v_mfma_f32_16x16x32_bf16 v[92:95], v[146:149], v[194:197], v[92:95]
	v_mfma_f32_16x16x32_bf16 v[88:91], v[154:157], v[194:197], v[88:91]
	v_mfma_f32_16x16x32_bf16 v[76:79], v[146:149], v[208:211], v[76:79]
	v_mfma_f32_16x16x32_bf16 v[72:75], v[154:157], v[208:211], v[72:75]
	v_mfma_f32_16x16x32_bf16 v[116:119], v[158:161], v[174:177], v[116:119]
	v_mfma_f32_16x16x32_bf16 v[112:115], v[166:169], v[174:177], v[112:115]
	v_mfma_f32_16x16x32_bf16 v[100:103], v[158:161], v[182:185], v[100:103]
	v_mfma_f32_16x16x32_bf16 v[96:99], v[166:169], v[182:185], v[96:99]
	v_mfma_f32_16x16x32_bf16 v[84:87], v[158:161], v[190:193], v[84:87]
	v_mfma_f32_16x16x32_bf16 v[80:83], v[166:169], v[190:193], v[80:83]
	v_mfma_f32_16x16x32_bf16 v[68:71], v[158:161], v[200:203], v[68:71]
	v_mfma_f32_16x16x32_bf16 v[64:67], v[166:169], v[200:203], v[64:67]
	v_mfma_f32_16x16x32_bf16 v[116:119], v[162:165], v[178:181], v[116:119]
	v_mfma_f32_16x16x32_bf16 v[112:115], v[170:173], v[178:181], v[112:115]
	v_mfma_f32_16x16x32_bf16 v[100:103], v[162:165], v[186:189], v[100:103]
	v_mfma_f32_16x16x32_bf16 v[96:99], v[170:173], v[186:189], v[96:99]
	v_mfma_f32_16x16x32_bf16 v[84:87], v[162:165], v[194:197], v[84:87]
	v_mfma_f32_16x16x32_bf16 v[80:83], v[170:173], v[194:197], v[80:83]
	v_mfma_f32_16x16x32_bf16 v[68:71], v[162:165], v[208:211], v[68:71]
	v_mfma_f32_16x16x32_bf16 v[64:67], v[170:173], v[208:211], v[64:67]
	s_barrier
	s_add_i32 s35, s35, s13
	v_lshl_add_u64 v[198:199], s[8:9], 0, v[132:133]
	s_mov_b32 m0, s35
	ds_read_b128 v[174:177], v207 offset:16384
	ds_read_b128 v[178:181], v207 offset:17408
	ds_read_b128 v[182:185], v207 offset:18432
	ds_read_b128 v[186:189], v207 offset:19456
	ds_read_b128 v[190:193], v207 offset:20480
	ds_read_b128 v[194:197], v207 offset:21504
	ds_read_b128 v[200:203], v207 offset:22528
	ds_read_b128 v[208:211], v207 offset:23552
	global_load_lds_dwordx4 v[198:199], off
	s_add_i32 m0, s35, 0x2000
	s_add_u32 s60, s8, 0x40000
	v_lshl_add_u64 v[204:205], s[8:9], 0, v[128:129]
	s_addc_u32 s61, s9, 0
	s_add_i32 s35, s76, s13
	global_load_lds_dwordx4 v[204:205], off
	v_lshl_add_u64 v[212:213], s[60:61], 0, v[132:133]
	s_mov_b32 m0, s35
	v_lshl_add_u64 v[214:215], s[10:11], 0, v[130:131]
	global_load_lds_dwordx4 v[212:213], off
	v_lshl_add_u64 v[212:213], s[60:61], 0, v[128:129]
	s_add_i32 m0, s35, 0x2000
	s_nop 0
	global_load_lds_dwordx4 v[212:213], off
	v_lshl_add_u64 v[212:213], s[10:11], 0, v[134:135]
	s_mov_b32 m0, s15
	s_nop 0
	global_load_lds_dwordx4 v[212:213], off
	s_mov_b32 m0, s26
	s_nop 0
	global_load_lds_dwordx4 v[214:215], off
	s_waitcnt vmcnt(8)
	s_waitcnt lgkmcnt(0)
	s_barrier
	v_mfma_f32_16x16x32_bf16 v[60:63], v[142:145], v[174:177], v[60:63]
	v_mfma_f32_16x16x32_bf16 v[56:59], v[150:153], v[174:177], v[56:59]
	v_mfma_f32_16x16x32_bf16 v[44:47], v[142:145], v[182:185], v[44:47]
	v_mfma_f32_16x16x32_bf16 v[40:43], v[150:153], v[182:185], v[40:43]
	v_mfma_f32_16x16x32_bf16 v[28:31], v[142:145], v[190:193], v[28:31]
	v_mfma_f32_16x16x32_bf16 v[24:27], v[150:153], v[190:193], v[24:27]
	v_mfma_f32_16x16x32_bf16 v[12:15], v[142:145], v[200:203], v[12:15]
	v_mfma_f32_16x16x32_bf16 v[8:11], v[150:153], v[200:203], v[8:11]
	v_mfma_f32_16x16x32_bf16 v[60:63], v[146:149], v[178:181], v[60:63]
	v_mfma_f32_16x16x32_bf16 v[56:59], v[154:157], v[178:181], v[56:59]
	v_mfma_f32_16x16x32_bf16 v[44:47], v[146:149], v[186:189], v[44:47]
	v_mfma_f32_16x16x32_bf16 v[40:43], v[154:157], v[186:189], v[40:43]
	v_mfma_f32_16x16x32_bf16 v[28:31], v[146:149], v[194:197], v[28:31]
	v_mfma_f32_16x16x32_bf16 v[24:27], v[154:157], v[194:197], v[24:27]
	v_mfma_f32_16x16x32_bf16 v[12:15], v[146:149], v[208:211], v[12:15]
	v_mfma_f32_16x16x32_bf16 v[8:11], v[154:157], v[208:211], v[8:11]
	v_mfma_f32_16x16x32_bf16 v[52:55], v[158:161], v[174:177], v[52:55]
	v_mfma_f32_16x16x32_bf16 v[48:51], v[166:169], v[174:177], v[48:51]
	v_mfma_f32_16x16x32_bf16 v[36:39], v[158:161], v[182:185], v[36:39]
	v_mfma_f32_16x16x32_bf16 v[32:35], v[166:169], v[182:185], v[32:35]
	v_mfma_f32_16x16x32_bf16 v[20:23], v[158:161], v[190:193], v[20:23]
	v_mfma_f32_16x16x32_bf16 v[16:19], v[166:169], v[190:193], v[16:19]
	v_mfma_f32_16x16x32_bf16 v[4:7], v[158:161], v[200:203], v[4:7]
	v_mfma_f32_16x16x32_bf16 v[0:3], v[166:169], v[200:203], v[0:3]
	v_mfma_f32_16x16x32_bf16 v[52:55], v[162:165], v[178:181], v[52:55]
	v_mfma_f32_16x16x32_bf16 v[48:51], v[170:173], v[178:181], v[48:51]
	v_mfma_f32_16x16x32_bf16 v[36:39], v[162:165], v[186:189], v[36:39]
	v_mfma_f32_16x16x32_bf16 v[32:35], v[170:173], v[186:189], v[32:35]
	v_mfma_f32_16x16x32_bf16 v[20:23], v[162:165], v[194:197], v[20:23]
	v_mfma_f32_16x16x32_bf16 v[16:19], v[170:173], v[194:197], v[16:19]
	v_mfma_f32_16x16x32_bf16 v[4:7], v[162:165], v[208:211], v[4:7]
	v_mfma_f32_16x16x32_bf16 v[0:3], v[170:173], v[208:211], v[0:3]
	s_barrier
	s_add_i32 s35, 0, 0x18000
	v_add_u32_e32 v140, s35, v206
	s_add_i32 s60, 0, 0x1c000
	ds_read_b128 v[142:145], v140
	ds_read_b128 v[146:149], v140 offset:1024
	ds_read_b128 v[150:153], v140 offset:2048
	ds_read_b128 v[154:157], v140 offset:3072
	v_add_u32_e32 v140, s60, v206
	ds_read_b128 v[158:161], v140
	ds_read_b128 v[162:165], v140 offset:1024
	ds_read_b128 v[166:169], v140 offset:2048
	ds_read_b128 v[170:173], v140 offset:3072
	s_add_u32 s10, s10, 0x40000
	s_addc_u32 s11, s11, 0
	s_mov_b32 m0, s27
	v_lshl_add_u64 v[216:217], s[10:11], 0, v[134:135]
	ds_read_b128 v[174:177], v207 offset:32768
	ds_read_b128 v[178:181], v207 offset:33792
	ds_read_b128 v[182:185], v207 offset:34816
	ds_read_b128 v[186:189], v207 offset:35840
	ds_read_b128 v[190:193], v207 offset:36864
	ds_read_b128 v[194:197], v207 offset:37888
	ds_read_b128 v[200:203], v207 offset:38912
	ds_read_b128 v[208:211], v207 offset:39936
	global_load_lds_dwordx4 v[216:217], off
	v_lshl_add_u64 v[216:217], s[10:11], 0, v[130:131]
	s_mov_b32 m0, s28
	s_nop 0
	global_load_lds_dwordx4 v[216:217], off
	s_waitcnt vmcnt(8)
	s_waitcnt lgkmcnt(0)
	s_barrier
	v_mfma_f32_16x16x32_bf16 v[124:127], v[142:145], v[174:177], v[124:127]
	v_mfma_f32_16x16x32_bf16 v[120:123], v[150:153], v[174:177], v[120:123]
	v_mfma_f32_16x16x32_bf16 v[108:111], v[142:145], v[182:185], v[108:111]
	v_mfma_f32_16x16x32_bf16 v[104:107], v[150:153], v[182:185], v[104:107]
	v_mfma_f32_16x16x32_bf16 v[92:95], v[142:145], v[190:193], v[92:95]
	v_mfma_f32_16x16x32_bf16 v[88:91], v[150:153], v[190:193], v[88:91]
	v_mfma_f32_16x16x32_bf16 v[76:79], v[142:145], v[200:203], v[76:79]
	v_mfma_f32_16x16x32_bf16 v[72:75], v[150:153], v[200:203], v[72:75]
	v_mfma_f32_16x16x32_bf16 v[124:127], v[146:149], v[178:181], v[124:127]
	v_mfma_f32_16x16x32_bf16 v[120:123], v[154:157], v[178:181], v[120:123]
	v_mfma_f32_16x16x32_bf16 v[108:111], v[146:149], v[186:189], v[108:111]
	v_mfma_f32_16x16x32_bf16 v[104:107], v[154:157], v[186:189], v[104:107]
	v_mfma_f32_16x16x32_bf16 v[92:95], v[146:149], v[194:197], v[92:95]
	v_mfma_f32_16x16x32_bf16 v[88:91], v[154:157], v[194:197], v[88:91]
	v_mfma_f32_16x16x32_bf16 v[76:79], v[146:149], v[208:211], v[76:79]
	v_mfma_f32_16x16x32_bf16 v[72:75], v[154:157], v[208:211], v[72:75]
	v_mfma_f32_16x16x32_bf16 v[116:119], v[158:161], v[174:177], v[116:119]
	v_mfma_f32_16x16x32_bf16 v[112:115], v[166:169], v[174:177], v[112:115]
	v_mfma_f32_16x16x32_bf16 v[100:103], v[158:161], v[182:185], v[100:103]
	v_mfma_f32_16x16x32_bf16 v[96:99], v[166:169], v[182:185], v[96:99]
	v_mfma_f32_16x16x32_bf16 v[84:87], v[158:161], v[190:193], v[84:87]
	v_mfma_f32_16x16x32_bf16 v[80:83], v[166:169], v[190:193], v[80:83]
	v_mfma_f32_16x16x32_bf16 v[68:71], v[158:161], v[200:203], v[68:71]
	v_mfma_f32_16x16x32_bf16 v[64:67], v[166:169], v[200:203], v[64:67]
	v_mfma_f32_16x16x32_bf16 v[116:119], v[162:165], v[178:181], v[116:119]
	v_mfma_f32_16x16x32_bf16 v[112:115], v[170:173], v[178:181], v[112:115]
	v_mfma_f32_16x16x32_bf16 v[100:103], v[162:165], v[186:189], v[100:103]
	v_mfma_f32_16x16x32_bf16 v[96:99], v[170:173], v[186:189], v[96:99]
	v_mfma_f32_16x16x32_bf16 v[84:87], v[162:165], v[194:197], v[84:87]
	v_mfma_f32_16x16x32_bf16 v[80:83], v[170:173], v[194:197], v[80:83]
	v_mfma_f32_16x16x32_bf16 v[68:71], v[162:165], v[208:211], v[68:71]
	v_mfma_f32_16x16x32_bf16 v[64:67], v[170:173], v[208:211], v[64:67]
	s_barrier
	s_add_i32 s10, s35, s13
	v_lshl_add_u64 v[198:199], v[198:199], 0, s[36:37]
	s_mov_b32 m0, s10
	ds_read_b128 v[174:177], v207 offset:49152
	ds_read_b128 v[178:181], v207 offset:50176
	ds_read_b128 v[182:185], v207 offset:51200
	ds_read_b128 v[186:189], v207 offset:52224
	ds_read_b128 v[190:193], v207 offset:53248
	ds_read_b128 v[194:197], v207 offset:54272
	ds_read_b128 v[200:203], v207 offset:55296
	ds_read_b128 v[208:211], v207 offset:56320
	global_load_lds_dwordx4 v[198:199], off
	s_add_i32 m0, s10, 0x2000
	s_add_u32 s8, s8, 0x40080
	v_lshl_add_u64 v[198:199], v[204:205], 0, s[36:37]
	s_addc_u32 s9, s9, 0
	s_add_i32 s10, s60, s13
	global_load_lds_dwordx4 v[198:199], off
	v_lshl_add_u64 v[198:199], s[8:9], 0, v[132:133]
	s_mov_b32 m0, s10
	s_nop 0
	global_load_lds_dwordx4 v[198:199], off
	v_lshl_add_u64 v[198:199], s[8:9], 0, v[128:129]
	s_add_i32 m0, s10, 0x2000
	s_nop 0
	global_load_lds_dwordx4 v[198:199], off
	v_lshl_add_u64 v[198:199], v[212:213], 0, s[36:37]
	s_mov_b32 m0, s29
	s_nop 0
	global_load_lds_dwordx4 v[198:199], off
	v_lshl_add_u64 v[198:199], v[214:215], 0, s[36:37]
	s_mov_b32 m0, s38
	s_nop 0
	global_load_lds_dwordx4 v[198:199], off
	s_waitcnt vmcnt(8)
	s_waitcnt lgkmcnt(0)
	s_barrier
	v_mfma_f32_16x16x32_bf16 v[60:63], v[142:145], v[174:177], v[60:63]
	v_mfma_f32_16x16x32_bf16 v[56:59], v[150:153], v[174:177], v[56:59]
	v_mfma_f32_16x16x32_bf16 v[44:47], v[142:145], v[182:185], v[44:47]
	v_mfma_f32_16x16x32_bf16 v[40:43], v[150:153], v[182:185], v[40:43]
	v_mfma_f32_16x16x32_bf16 v[28:31], v[142:145], v[190:193], v[28:31]
	v_mfma_f32_16x16x32_bf16 v[24:27], v[150:153], v[190:193], v[24:27]
	v_mfma_f32_16x16x32_bf16 v[12:15], v[142:145], v[200:203], v[12:15]
	v_mfma_f32_16x16x32_bf16 v[8:11], v[150:153], v[200:203], v[8:11]
	v_mfma_f32_16x16x32_bf16 v[60:63], v[146:149], v[178:181], v[60:63]
	v_mfma_f32_16x16x32_bf16 v[56:59], v[154:157], v[178:181], v[56:59]
	v_mfma_f32_16x16x32_bf16 v[44:47], v[146:149], v[186:189], v[44:47]
	v_mfma_f32_16x16x32_bf16 v[40:43], v[154:157], v[186:189], v[40:43]
	v_mfma_f32_16x16x32_bf16 v[28:31], v[146:149], v[194:197], v[28:31]
	v_mfma_f32_16x16x32_bf16 v[24:27], v[154:157], v[194:197], v[24:27]
	v_mfma_f32_16x16x32_bf16 v[12:15], v[146:149], v[208:211], v[12:15]
	v_mfma_f32_16x16x32_bf16 v[8:11], v[154:157], v[208:211], v[8:11]
	v_mfma_f32_16x16x32_bf16 v[52:55], v[158:161], v[174:177], v[52:55]
	v_mfma_f32_16x16x32_bf16 v[48:51], v[166:169], v[174:177], v[48:51]
	v_mfma_f32_16x16x32_bf16 v[36:39], v[158:161], v[182:185], v[36:39]
	v_mfma_f32_16x16x32_bf16 v[32:35], v[166:169], v[182:185], v[32:35]
	v_mfma_f32_16x16x32_bf16 v[20:23], v[158:161], v[190:193], v[20:23]
	v_mfma_f32_16x16x32_bf16 v[16:19], v[166:169], v[190:193], v[16:19]
	v_mfma_f32_16x16x32_bf16 v[4:7], v[158:161], v[200:203], v[4:7]
	v_mfma_f32_16x16x32_bf16 v[0:3], v[166:169], v[200:203], v[0:3]
	v_mfma_f32_16x16x32_bf16 v[52:55], v[162:165], v[178:181], v[52:55]
	v_mfma_f32_16x16x32_bf16 v[48:51], v[170:173], v[178:181], v[48:51]
	v_mfma_f32_16x16x32_bf16 v[36:39], v[162:165], v[186:189], v[36:39]
	v_mfma_f32_16x16x32_bf16 v[32:35], v[170:173], v[186:189], v[32:35]
	v_mfma_f32_16x16x32_bf16 v[20:23], v[162:165], v[194:197], v[20:23]
	v_mfma_f32_16x16x32_bf16 v[16:19], v[170:173], v[194:197], v[16:19]
	v_mfma_f32_16x16x32_bf16 v[4:7], v[162:165], v[208:211], v[4:7]
	v_mfma_f32_16x16x32_bf16 v[0:3], v[170:173], v[208:211], v[0:3]
	s_barrier
	s_add_i32 s53, s53, 2
	s_add_u32 s6, s6, 0x100
	s_addc_u32 s7, s7, 0
	s_add_u32 s43, s43, 0x100
	s_addc_u32 s51, s51, 0
	s_cmp_gt_u32 s53, 13
	s_cbranch_scc0 .LBB0_234
	s_and_b64 vcc, exec, s[48:49]
	s_cbranch_vccz .LBB0_237
	s_barrier

.LBB0_333:
	s_add_i32 s56, s8, 2
	s_add_u32 s9, s6, 0x8000
	s_addc_u32 s10, s7, 0
	s_cmp_eq_u32 s94, s8
	s_cselect_b32 s11, s43, s10
	s_cselect_b32 s10, s42, s9
	s_cselect_b32 s60, s54, s24
	s_cselect_b32 s61, s55, s38
	s_add_u32 s8, s10, 0x8000
	s_addc_u32 s9, s11, 0
	s_add_i32 s35, 0, 0x10000
	s_add_i32 s57, 0, 0x14000
	v_add_u32_e32 v142, s35, v178
	v_add_u32_e32 v168, s57, v178
	ds_read_b128 v[128:131], v142
	ds_read_b128 v[132:135], v142 offset:1024
	ds_read_b128 v[136:139], v142 offset:2048
	ds_read_b128 v[142:145], v142 offset:3072
	ds_read_b128 v[146:149], v168
	ds_read_b128 v[150:153], v168 offset:1024
	ds_read_b128 v[154:157], v168 offset:2048
	ds_read_b128 v[168:171], v168 offset:3072
	v_lshl_add_u64 v[176:177], s[6:7], 0, v[164:165]
	s_add_i32 m0, s75, 0xc000
	ds_read_b128 v[172:175], v179
	ds_read_b128 v[180:183], v179 offset:1024
	ds_read_b128 v[184:187], v179 offset:2048
	ds_read_b128 v[188:191], v179 offset:3072
	ds_read_b128 v[192:195], v179 offset:4096
	ds_read_b128 v[200:203], v179 offset:5120
	ds_read_b128 v[206:209], v179 offset:6144
	ds_read_b128 v[210:213], v179 offset:7168
	global_load_lds_dwordx4 v[176:177], off
	v_lshl_add_u64 v[176:177], s[6:7], 0, v[166:167]
	s_add_i32 m0, s75, 0xe000
	s_nop 0
	global_load_lds_dwordx4 v[176:177], off
	s_waitcnt vmcnt(8)
	s_waitcnt lgkmcnt(0)
	s_barrier
	v_mfma_f32_16x16x32_bf16 v[124:127], v[128:131], v[172:175], v[124:127]
	v_mfma_f32_16x16x32_bf16 v[120:123], v[136:139], v[172:175], v[120:123]
	v_mfma_f32_16x16x32_bf16 v[108:111], v[128:131], v[184:187], v[108:111]
	v_mfma_f32_16x16x32_bf16 v[104:107], v[136:139], v[184:187], v[104:107]
	v_mfma_f32_16x16x32_bf16 v[92:95], v[128:131], v[192:195], v[92:95]
	v_mfma_f32_16x16x32_bf16 v[88:91], v[136:139], v[192:195], v[88:91]
	v_mfma_f32_16x16x32_bf16 v[76:79], v[128:131], v[206:209], v[76:79]
	v_mfma_f32_16x16x32_bf16 v[72:75], v[136:139], v[206:209], v[72:75]
	v_mfma_f32_16x16x32_bf16 v[124:127], v[132:135], v[180:183], v[124:127]
	v_mfma_f32_16x16x32_bf16 v[120:123], v[142:145], v[180:183], v[120:123]
	v_mfma_f32_16x16x32_bf16 v[108:111], v[132:135], v[188:191], v[108:111]
	v_mfma_f32_16x16x32_bf16 v[104:107], v[142:145], v[188:191], v[104:107]
	v_mfma_f32_16x16x32_bf16 v[92:95], v[132:135], v[200:203], v[92:95]
	v_mfma_f32_16x16x32_bf16 v[88:91], v[142:145], v[200:203], v[88:91]
	v_mfma_f32_16x16x32_bf16 v[76:79], v[132:135], v[210:213], v[76:79]
	v_mfma_f32_16x16x32_bf16 v[72:75], v[142:145], v[210:213], v[72:75]
	v_mfma_f32_16x16x32_bf16 v[116:119], v[146:149], v[172:175], v[116:119]
	v_mfma_f32_16x16x32_bf16 v[112:115], v[154:157], v[172:175], v[112:115]
	v_mfma_f32_16x16x32_bf16 v[100:103], v[146:149], v[184:187], v[100:103]
	v_mfma_f32_16x16x32_bf16 v[96:99], v[154:157], v[184:187], v[96:99]
	v_mfma_f32_16x16x32_bf16 v[84:87], v[146:149], v[192:195], v[84:87]
	v_mfma_f32_16x16x32_bf16 v[80:83], v[154:157], v[192:195], v[80:83]
	v_mfma_f32_16x16x32_bf16 v[68:71], v[146:149], v[206:209], v[68:71]
	v_mfma_f32_16x16x32_bf16 v[64:67], v[154:157], v[206:209], v[64:67]
	v_mfma_f32_16x16x32_bf16 v[116:119], v[150:153], v[180:183], v[116:119]
	v_mfma_f32_16x16x32_bf16 v[112:115], v[168:171], v[180:183], v[112:115]
	v_mfma_f32_16x16x32_bf16 v[100:103], v[150:153], v[188:191], v[100:103]
	v_mfma_f32_16x16x32_bf16 v[96:99], v[168:171], v[188:191], v[96:99]
	v_mfma_f32_16x16x32_bf16 v[84:87], v[150:153], v[200:203], v[84:87]
	v_mfma_f32_16x16x32_bf16 v[80:83], v[168:171], v[200:203], v[80:83]
	v_mfma_f32_16x16x32_bf16 v[68:71], v[150:153], v[210:213], v[68:71]
	v_mfma_f32_16x16x32_bf16 v[64:67], v[168:171], v[210:213], v[64:67]
	s_barrier
	s_add_i32 s35, s35, s74
	v_lshl_add_u64 v[176:177], s[60:61], 0, v[140:141]
	s_mov_b32 m0, s35
	ds_read_b128 v[172:175], v179 offset:16384
	ds_read_b128 v[180:183], v179 offset:17408
	ds_read_b128 v[184:187], v179 offset:18432
	ds_read_b128 v[188:191], v179 offset:19456
	ds_read_b128 v[192:195], v179 offset:20480
	ds_read_b128 v[200:203], v179 offset:21504
	ds_read_b128 v[206:209], v179 offset:22528
	ds_read_b128 v[210:213], v179 offset:23552
	global_load_lds_dwordx4 v[176:177], off
	s_add_i32 m0, s35, 0x2000
	v_lshl_add_u64 v[196:197], s[60:61], 0, v[158:159]
	s_add_u32 s60, s60, s13
	s_addc_u32 s61, s61, 0
	s_add_i32 s35, s57, s74
	global_load_lds_dwordx4 v[196:197], off
	v_lshl_add_u64 v[198:199], s[60:61], 0, v[140:141]
	s_mov_b32 m0, s35
	v_lshl_add_u64 v[204:205], s[60:61], 0, v[158:159]
	global_load_lds_dwordx4 v[198:199], off
	s_add_i32 m0, s35, 0x2000
	v_lshl_add_u64 v[214:215], s[10:11], 0, v[162:163]
	global_load_lds_dwordx4 v[204:205], off
	s_mov_b32 m0, s75
	s_nop 0
	global_load_lds_dwordx4 v[214:215], off
	v_lshl_add_u64 v[214:215], s[10:11], 0, v[160:161]
	s_mov_b32 m0, s26
	s_nop 0
	global_load_lds_dwordx4 v[214:215], off
	s_waitcnt vmcnt(8)
	s_waitcnt lgkmcnt(0)
	s_barrier
	v_mfma_f32_16x16x32_bf16 v[60:63], v[128:131], v[172:175], v[60:63]
	v_mfma_f32_16x16x32_bf16 v[56:59], v[136:139], v[172:175], v[56:59]
	v_mfma_f32_16x16x32_bf16 v[44:47], v[128:131], v[184:187], v[44:47]
	v_mfma_f32_16x16x32_bf16 v[40:43], v[136:139], v[184:187], v[40:43]
	v_mfma_f32_16x16x32_bf16 v[28:31], v[128:131], v[192:195], v[28:31]
	v_mfma_f32_16x16x32_bf16 v[24:27], v[136:139], v[192:195], v[24:27]
	v_mfma_f32_16x16x32_bf16 v[12:15], v[128:131], v[206:209], v[12:15]
	v_mfma_f32_16x16x32_bf16 v[8:11], v[136:139], v[206:209], v[8:11]
	v_mfma_f32_16x16x32_bf16 v[60:63], v[132:135], v[180:183], v[60:63]
	v_mfma_f32_16x16x32_bf16 v[56:59], v[142:145], v[180:183], v[56:59]
	v_mfma_f32_16x16x32_bf16 v[44:47], v[132:135], v[188:191], v[44:47]
	v_mfma_f32_16x16x32_bf16 v[40:43], v[142:145], v[188:191], v[40:43]
	v_mfma_f32_16x16x32_bf16 v[28:31], v[132:135], v[200:203], v[28:31]
	v_mfma_f32_16x16x32_bf16 v[24:27], v[142:145], v[200:203], v[24:27]
	v_mfma_f32_16x16x32_bf16 v[12:15], v[132:135], v[210:213], v[12:15]
	v_mfma_f32_16x16x32_bf16 v[8:11], v[142:145], v[210:213], v[8:11]
	v_mfma_f32_16x16x32_bf16 v[52:55], v[146:149], v[172:175], v[52:55]
	v_mfma_f32_16x16x32_bf16 v[48:51], v[154:157], v[172:175], v[48:51]
	v_mfma_f32_16x16x32_bf16 v[36:39], v[146:149], v[184:187], v[36:39]
	v_mfma_f32_16x16x32_bf16 v[32:35], v[154:157], v[184:187], v[32:35]
	v_mfma_f32_16x16x32_bf16 v[20:23], v[146:149], v[192:195], v[20:23]
	v_mfma_f32_16x16x32_bf16 v[16:19], v[154:157], v[192:195], v[16:19]
	v_mfma_f32_16x16x32_bf16 v[4:7], v[146:149], v[206:209], v[4:7]
	v_mfma_f32_16x16x32_bf16 v[0:3], v[154:157], v[206:209], v[0:3]
	v_mfma_f32_16x16x32_bf16 v[52:55], v[150:153], v[180:183], v[52:55]
	v_mfma_f32_16x16x32_bf16 v[48:51], v[168:171], v[180:183], v[48:51]
	v_mfma_f32_16x16x32_bf16 v[36:39], v[150:153], v[188:191], v[36:39]
	v_mfma_f32_16x16x32_bf16 v[32:35], v[168:171], v[188:191], v[32:35]
	v_mfma_f32_16x16x32_bf16 v[20:23], v[150:153], v[200:203], v[20:23]
	v_mfma_f32_16x16x32_bf16 v[16:19], v[168:171], v[200:203], v[16:19]
	v_mfma_f32_16x16x32_bf16 v[4:7], v[150:153], v[210:213], v[4:7]
	v_mfma_f32_16x16x32_bf16 v[0:3], v[168:171], v[210:213], v[0:3]
	s_barrier
	s_add_i32 s35, 0, 0x18000
	s_add_i32 s57, 0, 0x1c000
	v_add_u32_e32 v142, s35, v178
	v_add_u32_e32 v168, s57, v178
	ds_read_b128 v[128:131], v142
	ds_read_b128 v[132:135], v142 offset:1024
	ds_read_b128 v[136:139], v142 offset:2048
	ds_read_b128 v[142:145], v142 offset:3072
	ds_read_b128 v[146:149], v168
	ds_read_b128 v[150:153], v168 offset:1024
	ds_read_b128 v[154:157], v168 offset:2048
	ds_read_b128 v[168:171], v168 offset:3072
	s_add_u32 s10, s10, s48
	s_addc_u32 s11, s11, 0
	s_mov_b32 m0, s27
	v_lshl_add_u64 v[214:215], s[10:11], 0, v[162:163]
	ds_read_b128 v[172:175], v179 offset:32768
	ds_read_b128 v[180:183], v179 offset:33792
	ds_read_b128 v[184:187], v179 offset:34816
	ds_read_b128 v[188:191], v179 offset:35840
	ds_read_b128 v[192:195], v179 offset:36864
	ds_read_b128 v[200:203], v179 offset:37888
	ds_read_b128 v[206:209], v179 offset:38912
	ds_read_b128 v[210:213], v179 offset:39936
	global_load_lds_dwordx4 v[214:215], off
	v_lshl_add_u64 v[214:215], s[10:11], 0, v[160:161]
	s_mov_b32 m0, s15
	s_nop 0
	global_load_lds_dwordx4 v[214:215], off
	s_waitcnt vmcnt(8)
	s_waitcnt lgkmcnt(0)
	s_barrier
	v_mfma_f32_16x16x32_bf16 v[124:127], v[128:131], v[172:175], v[124:127]
	v_mfma_f32_16x16x32_bf16 v[120:123], v[136:139], v[172:175], v[120:123]
	v_mfma_f32_16x16x32_bf16 v[108:111], v[128:131], v[184:187], v[108:111]
	v_mfma_f32_16x16x32_bf16 v[104:107], v[136:139], v[184:187], v[104:107]
	v_mfma_f32_16x16x32_bf16 v[92:95], v[128:131], v[192:195], v[92:95]
	v_mfma_f32_16x16x32_bf16 v[88:91], v[136:139], v[192:195], v[88:91]
	v_mfma_f32_16x16x32_bf16 v[76:79], v[128:131], v[206:209], v[76:79]
	v_mfma_f32_16x16x32_bf16 v[72:75], v[136:139], v[206:209], v[72:75]
	v_mfma_f32_16x16x32_bf16 v[124:127], v[132:135], v[180:183], v[124:127]
	v_mfma_f32_16x16x32_bf16 v[120:123], v[142:145], v[180:183], v[120:123]
	v_mfma_f32_16x16x32_bf16 v[108:111], v[132:135], v[188:191], v[108:111]
	v_mfma_f32_16x16x32_bf16 v[104:107], v[142:145], v[188:191], v[104:107]
	v_mfma_f32_16x16x32_bf16 v[92:95], v[132:135], v[200:203], v[92:95]
	v_mfma_f32_16x16x32_bf16 v[88:91], v[142:145], v[200:203], v[88:91]
	v_mfma_f32_16x16x32_bf16 v[76:79], v[132:135], v[210:213], v[76:79]
	v_mfma_f32_16x16x32_bf16 v[72:75], v[142:145], v[210:213], v[72:75]
	v_mfma_f32_16x16x32_bf16 v[116:119], v[146:149], v[172:175], v[116:119]
	v_mfma_f32_16x16x32_bf16 v[112:115], v[154:157], v[172:175], v[112:115]
	v_mfma_f32_16x16x32_bf16 v[100:103], v[146:149], v[184:187], v[100:103]
	v_mfma_f32_16x16x32_bf16 v[96:99], v[154:157], v[184:187], v[96:99]
	v_mfma_f32_16x16x32_bf16 v[84:87], v[146:149], v[192:195], v[84:87]
	v_mfma_f32_16x16x32_bf16 v[80:83], v[154:157], v[192:195], v[80:83]
	v_mfma_f32_16x16x32_bf16 v[68:71], v[146:149], v[206:209], v[68:71]
	v_mfma_f32_16x16x32_bf16 v[64:67], v[154:157], v[206:209], v[64:67]
	v_mfma_f32_16x16x32_bf16 v[116:119], v[150:153], v[180:183], v[116:119]
	v_mfma_f32_16x16x32_bf16 v[112:115], v[168:171], v[180:183], v[112:115]
	v_mfma_f32_16x16x32_bf16 v[100:103], v[150:153], v[188:191], v[100:103]
	v_mfma_f32_16x16x32_bf16 v[96:99], v[168:171], v[188:191], v[96:99]
	v_mfma_f32_16x16x32_bf16 v[84:87], v[150:153], v[200:203], v[84:87]
	v_mfma_f32_16x16x32_bf16 v[80:83], v[168:171], v[200:203], v[80:83]
	v_mfma_f32_16x16x32_bf16 v[68:71], v[150:153], v[210:213], v[68:71]
	v_mfma_f32_16x16x32_bf16 v[64:67], v[168:171], v[210:213], v[64:67]
	s_barrier
	s_add_i32 s10, s35, s74
	v_lshl_add_u64 v[176:177], v[176:177], 0, s[36:37]
	s_mov_b32 m0, s10
	ds_read_b128 v[172:175], v179 offset:49152
	ds_read_b128 v[180:183], v179 offset:50176
	ds_read_b128 v[184:187], v179 offset:51200
	ds_read_b128 v[188:191], v179 offset:52224
	ds_read_b128 v[192:195], v179 offset:53248
	ds_read_b128 v[200:203], v179 offset:54272
	ds_read_b128 v[206:209], v179 offset:55296
	ds_read_b128 v[210:213], v179 offset:56320
	global_load_lds_dwordx4 v[176:177], off
	v_lshl_add_u64 v[176:177], v[196:197], 0, s[36:37]
	s_add_i32 m0, s10, 0x2000
	s_add_i32 s10, s57, s74
	global_load_lds_dwordx4 v[176:177], off
	v_lshl_add_u64 v[176:177], v[198:199], 0, s[36:37]
	s_mov_b32 m0, s10
	s_nop 0
	global_load_lds_dwordx4 v[176:177], off
	v_lshl_add_u64 v[176:177], v[204:205], 0, s[36:37]
	s_add_i32 m0, s10, 0x2000
	s_nop 0
	global_load_lds_dwordx4 v[176:177], off
	v_lshl_add_u64 v[176:177], s[8:9], 0, v[162:163]
	s_mov_b32 m0, s28
	s_nop 0
	global_load_lds_dwordx4 v[176:177], off
	v_lshl_add_u64 v[176:177], s[8:9], 0, v[160:161]
	s_mov_b32 m0, s29
	s_nop 0
	global_load_lds_dwordx4 v[176:177], off
	s_waitcnt vmcnt(8)
	s_waitcnt lgkmcnt(0)
	s_barrier
	v_mfma_f32_16x16x32_bf16 v[60:63], v[128:131], v[172:175], v[60:63]
	v_mfma_f32_16x16x32_bf16 v[56:59], v[136:139], v[172:175], v[56:59]
	v_mfma_f32_16x16x32_bf16 v[44:47], v[128:131], v[184:187], v[44:47]
	v_mfma_f32_16x16x32_bf16 v[40:43], v[136:139], v[184:187], v[40:43]
	v_mfma_f32_16x16x32_bf16 v[28:31], v[128:131], v[192:195], v[28:31]
	v_mfma_f32_16x16x32_bf16 v[24:27], v[136:139], v[192:195], v[24:27]
	v_mfma_f32_16x16x32_bf16 v[12:15], v[128:131], v[206:209], v[12:15]
	v_mfma_f32_16x16x32_bf16 v[8:11], v[136:139], v[206:209], v[8:11]
	v_mfma_f32_16x16x32_bf16 v[60:63], v[132:135], v[180:183], v[60:63]
	v_mfma_f32_16x16x32_bf16 v[56:59], v[142:145], v[180:183], v[56:59]
	v_mfma_f32_16x16x32_bf16 v[44:47], v[132:135], v[188:191], v[44:47]
	v_mfma_f32_16x16x32_bf16 v[40:43], v[142:145], v[188:191], v[40:43]
	v_mfma_f32_16x16x32_bf16 v[28:31], v[132:135], v[200:203], v[28:31]
	v_mfma_f32_16x16x32_bf16 v[24:27], v[142:145], v[200:203], v[24:27]
	v_mfma_f32_16x16x32_bf16 v[12:15], v[132:135], v[210:213], v[12:15]
	v_mfma_f32_16x16x32_bf16 v[8:11], v[142:145], v[210:213], v[8:11]
	v_mfma_f32_16x16x32_bf16 v[52:55], v[146:149], v[172:175], v[52:55]
	v_mfma_f32_16x16x32_bf16 v[48:51], v[154:157], v[172:175], v[48:51]
	v_mfma_f32_16x16x32_bf16 v[36:39], v[146:149], v[184:187], v[36:39]
	v_mfma_f32_16x16x32_bf16 v[32:35], v[154:157], v[184:187], v[32:35]
	v_mfma_f32_16x16x32_bf16 v[20:23], v[146:149], v[192:195], v[20:23]
	v_mfma_f32_16x16x32_bf16 v[16:19], v[154:157], v[192:195], v[16:19]
	v_mfma_f32_16x16x32_bf16 v[4:7], v[146:149], v[206:209], v[4:7]
	v_mfma_f32_16x16x32_bf16 v[0:3], v[154:157], v[206:209], v[0:3]
	v_mfma_f32_16x16x32_bf16 v[52:55], v[150:153], v[180:183], v[52:55]
	v_mfma_f32_16x16x32_bf16 v[48:51], v[168:171], v[180:183], v[48:51]
	v_mfma_f32_16x16x32_bf16 v[36:39], v[150:153], v[188:191], v[36:39]
	v_mfma_f32_16x16x32_bf16 v[32:35], v[168:171], v[188:191], v[32:35]
	v_mfma_f32_16x16x32_bf16 v[20:23], v[150:153], v[200:203], v[20:23]
	v_mfma_f32_16x16x32_bf16 v[16:19], v[168:171], v[200:203], v[16:19]
	v_mfma_f32_16x16x32_bf16 v[4:7], v[150:153], v[210:213], v[4:7]
	v_mfma_f32_16x16x32_bf16 v[0:3], v[168:171], v[210:213], v[0:3]
	s_barrier
	s_add_u32 s24, s24, 0x100
	s_addc_u32 s38, s38, 0
	s_add_u32 s6, s6, 0x10000
	s_addc_u32 s7, s7, 0
	s_cmp_ge_u32 s56, s12
	s_mov_b32 s8, s56
	s_cbranch_scc0 .LBB0_333
	s_and_b64 vcc, exec, s[52:53]
	s_cbranch_vccz .LBB0_336
	s_barrier

.LBB0_375:
	s_add_i32 s24, s8, 2
	s_add_u32 s35, s6, 0x80
	s_addc_u32 s9, s7, 0
	s_add_i32 s38, 0, 0x10000
	s_cmp_eq_u32 s94, s8
	s_cselect_b32 s9, s43, s9
	s_cselect_b32 s8, s42, s35
	s_cselect_b32 s57, s55, s11
	s_cselect_b32 s56, s54, s10
	s_add_i32 s35, 0, 0x14000
	v_add_u32_e32 v142, s38, v178
	v_add_u32_e32 v168, s35, v178
	ds_read_b128 v[128:131], v142
	ds_read_b128 v[132:135], v142 offset:1024
	ds_read_b128 v[136:139], v142 offset:2048
	ds_read_b128 v[142:145], v142 offset:3072
	ds_read_b128 v[146:149], v168
	ds_read_b128 v[150:153], v168 offset:1024
	ds_read_b128 v[154:157], v168 offset:2048
	ds_read_b128 v[168:171], v168 offset:3072
	v_lshl_add_u64 v[176:177], s[6:7], 0, v[164:165]
	s_add_i32 m0, s15, 0xc000
	ds_read_b128 v[172:175], v179
	ds_read_b128 v[180:183], v179 offset:1024
	ds_read_b128 v[184:187], v179 offset:2048
	ds_read_b128 v[188:191], v179 offset:3072
	ds_read_b128 v[192:195], v179 offset:4096
	ds_read_b128 v[200:203], v179 offset:5120
	ds_read_b128 v[206:209], v179 offset:6144
	ds_read_b128 v[210:213], v179 offset:7168
	global_load_lds_dwordx4 v[176:177], off
	v_lshl_add_u64 v[176:177], s[6:7], 0, v[166:167]
	s_add_i32 m0, s15, 0xe000
	s_nop 0
	global_load_lds_dwordx4 v[176:177], off
	s_waitcnt vmcnt(8)
	s_waitcnt lgkmcnt(0)
	s_barrier
	v_mfma_f32_16x16x32_bf16 v[124:127], v[128:131], v[172:175], v[124:127]
	v_mfma_f32_16x16x32_bf16 v[120:123], v[136:139], v[172:175], v[120:123]
	v_mfma_f32_16x16x32_bf16 v[108:111], v[128:131], v[184:187], v[108:111]
	v_mfma_f32_16x16x32_bf16 v[104:107], v[136:139], v[184:187], v[104:107]
	v_mfma_f32_16x16x32_bf16 v[92:95], v[128:131], v[192:195], v[92:95]
	v_mfma_f32_16x16x32_bf16 v[88:91], v[136:139], v[192:195], v[88:91]
	v_mfma_f32_16x16x32_bf16 v[76:79], v[128:131], v[206:209], v[76:79]
	v_mfma_f32_16x16x32_bf16 v[72:75], v[136:139], v[206:209], v[72:75]
	v_mfma_f32_16x16x32_bf16 v[124:127], v[132:135], v[180:183], v[124:127]
	v_mfma_f32_16x16x32_bf16 v[120:123], v[142:145], v[180:183], v[120:123]
	v_mfma_f32_16x16x32_bf16 v[108:111], v[132:135], v[188:191], v[108:111]
	v_mfma_f32_16x16x32_bf16 v[104:107], v[142:145], v[188:191], v[104:107]
	v_mfma_f32_16x16x32_bf16 v[92:95], v[132:135], v[200:203], v[92:95]
	v_mfma_f32_16x16x32_bf16 v[88:91], v[142:145], v[200:203], v[88:91]
	v_mfma_f32_16x16x32_bf16 v[76:79], v[132:135], v[210:213], v[76:79]
	v_mfma_f32_16x16x32_bf16 v[72:75], v[142:145], v[210:213], v[72:75]
	v_mfma_f32_16x16x32_bf16 v[116:119], v[146:149], v[172:175], v[116:119]
	v_mfma_f32_16x16x32_bf16 v[112:115], v[154:157], v[172:175], v[112:115]
	v_mfma_f32_16x16x32_bf16 v[100:103], v[146:149], v[184:187], v[100:103]
	v_mfma_f32_16x16x32_bf16 v[96:99], v[154:157], v[184:187], v[96:99]
	v_mfma_f32_16x16x32_bf16 v[84:87], v[146:149], v[192:195], v[84:87]
	v_mfma_f32_16x16x32_bf16 v[80:83], v[154:157], v[192:195], v[80:83]
	v_mfma_f32_16x16x32_bf16 v[68:71], v[146:149], v[206:209], v[68:71]
	v_mfma_f32_16x16x32_bf16 v[64:67], v[154:157], v[206:209], v[64:67]
	v_mfma_f32_16x16x32_bf16 v[116:119], v[150:153], v[180:183], v[116:119]
	v_mfma_f32_16x16x32_bf16 v[112:115], v[168:171], v[180:183], v[112:115]
	v_mfma_f32_16x16x32_bf16 v[100:103], v[150:153], v[188:191], v[100:103]
	v_mfma_f32_16x16x32_bf16 v[96:99], v[168:171], v[188:191], v[96:99]
	v_mfma_f32_16x16x32_bf16 v[84:87], v[150:153], v[200:203], v[84:87]
	v_mfma_f32_16x16x32_bf16 v[80:83], v[168:171], v[200:203], v[80:83]
	v_mfma_f32_16x16x32_bf16 v[68:71], v[150:153], v[210:213], v[68:71]
	v_mfma_f32_16x16x32_bf16 v[64:67], v[168:171], v[210:213], v[64:67]
	s_barrier
	s_add_i32 s38, s38, s75
	v_lshl_add_u64 v[176:177], s[56:57], 0, v[140:141]
	s_mov_b32 m0, s38
	ds_read_b128 v[172:175], v179 offset:16384
	ds_read_b128 v[180:183], v179 offset:17408
	ds_read_b128 v[184:187], v179 offset:18432
	ds_read_b128 v[188:191], v179 offset:19456
	ds_read_b128 v[192:195], v179 offset:20480
	ds_read_b128 v[200:203], v179 offset:21504
	ds_read_b128 v[206:209], v179 offset:22528
	ds_read_b128 v[210:213], v179 offset:23552
	global_load_lds_dwordx4 v[176:177], off
	s_add_i32 m0, s38, 0x2000
	v_lshl_add_u64 v[196:197], s[56:57], 0, v[158:159]
	s_add_u32 s56, s56, s13
	s_addc_u32 s57, s57, 0
	s_add_i32 s35, s35, s75
	global_load_lds_dwordx4 v[196:197], off
	v_lshl_add_u64 v[198:199], s[56:57], 0, v[140:141]
	s_mov_b32 m0, s35
	v_lshl_add_u64 v[204:205], s[56:57], 0, v[158:159]
	global_load_lds_dwordx4 v[198:199], off
	s_add_i32 m0, s35, 0x2000
	v_lshl_add_u64 v[214:215], s[8:9], 0, v[162:163]
	global_load_lds_dwordx4 v[204:205], off
	s_mov_b32 m0, s15
	v_lshl_add_u64 v[216:217], s[8:9], 0, v[160:161]
	global_load_lds_dwordx4 v[214:215], off
	s_mov_b32 m0, s26
	s_nop 0
	global_load_lds_dwordx4 v[216:217], off
	s_waitcnt vmcnt(8)
	s_waitcnt lgkmcnt(0)
	s_barrier
	v_mfma_f32_16x16x32_bf16 v[60:63], v[128:131], v[172:175], v[60:63]
	v_mfma_f32_16x16x32_bf16 v[56:59], v[136:139], v[172:175], v[56:59]
	v_mfma_f32_16x16x32_bf16 v[44:47], v[128:131], v[184:187], v[44:47]
	v_mfma_f32_16x16x32_bf16 v[40:43], v[136:139], v[184:187], v[40:43]
	v_mfma_f32_16x16x32_bf16 v[28:31], v[128:131], v[192:195], v[28:31]
	v_mfma_f32_16x16x32_bf16 v[24:27], v[136:139], v[192:195], v[24:27]
	v_mfma_f32_16x16x32_bf16 v[12:15], v[128:131], v[206:209], v[12:15]
	v_mfma_f32_16x16x32_bf16 v[8:11], v[136:139], v[206:209], v[8:11]
	v_mfma_f32_16x16x32_bf16 v[60:63], v[132:135], v[180:183], v[60:63]
	v_mfma_f32_16x16x32_bf16 v[56:59], v[142:145], v[180:183], v[56:59]
	v_mfma_f32_16x16x32_bf16 v[44:47], v[132:135], v[188:191], v[44:47]
	v_mfma_f32_16x16x32_bf16 v[40:43], v[142:145], v[188:191], v[40:43]
	v_mfma_f32_16x16x32_bf16 v[28:31], v[132:135], v[200:203], v[28:31]
	v_mfma_f32_16x16x32_bf16 v[24:27], v[142:145], v[200:203], v[24:27]
	v_mfma_f32_16x16x32_bf16 v[12:15], v[132:135], v[210:213], v[12:15]
	v_mfma_f32_16x16x32_bf16 v[8:11], v[142:145], v[210:213], v[8:11]
	v_mfma_f32_16x16x32_bf16 v[52:55], v[146:149], v[172:175], v[52:55]
	v_mfma_f32_16x16x32_bf16 v[48:51], v[154:157], v[172:175], v[48:51]
	v_mfma_f32_16x16x32_bf16 v[36:39], v[146:149], v[184:187], v[36:39]
	v_mfma_f32_16x16x32_bf16 v[32:35], v[154:157], v[184:187], v[32:35]
	v_mfma_f32_16x16x32_bf16 v[20:23], v[146:149], v[192:195], v[20:23]
	v_mfma_f32_16x16x32_bf16 v[16:19], v[154:157], v[192:195], v[16:19]
	v_mfma_f32_16x16x32_bf16 v[4:7], v[146:149], v[206:209], v[4:7]
	v_mfma_f32_16x16x32_bf16 v[0:3], v[154:157], v[206:209], v[0:3]
	v_mfma_f32_16x16x32_bf16 v[52:55], v[150:153], v[180:183], v[52:55]
	v_mfma_f32_16x16x32_bf16 v[48:51], v[168:171], v[180:183], v[48:51]
	v_mfma_f32_16x16x32_bf16 v[36:39], v[150:153], v[188:191], v[36:39]
	v_mfma_f32_16x16x32_bf16 v[32:35], v[168:171], v[188:191], v[32:35]
	v_mfma_f32_16x16x32_bf16 v[20:23], v[150:153], v[200:203], v[20:23]
	v_mfma_f32_16x16x32_bf16 v[16:19], v[168:171], v[200:203], v[16:19]
	v_mfma_f32_16x16x32_bf16 v[4:7], v[150:153], v[210:213], v[4:7]
	v_mfma_f32_16x16x32_bf16 v[0:3], v[168:171], v[210:213], v[0:3]
	s_barrier
	s_add_i32 s35, 0, 0x18000
	s_add_i32 s38, 0, 0x1c000
	v_add_u32_e32 v142, s35, v178
	v_add_u32_e32 v168, s38, v178
	ds_read_b128 v[128:131], v142
	ds_read_b128 v[132:135], v142 offset:1024
	ds_read_b128 v[136:139], v142 offset:2048
	ds_read_b128 v[142:145], v142 offset:3072
	ds_read_b128 v[146:149], v168
	ds_read_b128 v[150:153], v168 offset:1024
	ds_read_b128 v[154:157], v168 offset:2048
	ds_read_b128 v[168:171], v168 offset:3072
	s_add_u32 s8, s8, s48
	s_addc_u32 s9, s9, 0
	s_mov_b32 m0, s27
	v_lshl_add_u64 v[218:219], s[8:9], 0, v[162:163]
	ds_read_b128 v[172:175], v179 offset:32768
	ds_read_b128 v[180:183], v179 offset:33792
	ds_read_b128 v[184:187], v179 offset:34816
	ds_read_b128 v[188:191], v179 offset:35840
	ds_read_b128 v[192:195], v179 offset:36864
	ds_read_b128 v[200:203], v179 offset:37888
	ds_read_b128 v[206:209], v179 offset:38912
	ds_read_b128 v[210:213], v179 offset:39936
	global_load_lds_dwordx4 v[218:219], off
	v_lshl_add_u64 v[218:219], s[8:9], 0, v[160:161]
	s_mov_b32 m0, s28
	s_nop 0
	global_load_lds_dwordx4 v[218:219], off
	s_waitcnt vmcnt(8)
	s_waitcnt lgkmcnt(0)
	s_barrier
	v_mfma_f32_16x16x32_bf16 v[124:127], v[128:131], v[172:175], v[124:127]
	v_mfma_f32_16x16x32_bf16 v[120:123], v[136:139], v[172:175], v[120:123]
	v_mfma_f32_16x16x32_bf16 v[108:111], v[128:131], v[184:187], v[108:111]
	v_mfma_f32_16x16x32_bf16 v[104:107], v[136:139], v[184:187], v[104:107]
	v_mfma_f32_16x16x32_bf16 v[92:95], v[128:131], v[192:195], v[92:95]
	v_mfma_f32_16x16x32_bf16 v[88:91], v[136:139], v[192:195], v[88:91]
	v_mfma_f32_16x16x32_bf16 v[76:79], v[128:131], v[206:209], v[76:79]
	v_mfma_f32_16x16x32_bf16 v[72:75], v[136:139], v[206:209], v[72:75]
	v_mfma_f32_16x16x32_bf16 v[124:127], v[132:135], v[180:183], v[124:127]
	v_mfma_f32_16x16x32_bf16 v[120:123], v[142:145], v[180:183], v[120:123]
	v_mfma_f32_16x16x32_bf16 v[108:111], v[132:135], v[188:191], v[108:111]
	v_mfma_f32_16x16x32_bf16 v[104:107], v[142:145], v[188:191], v[104:107]
	v_mfma_f32_16x16x32_bf16 v[92:95], v[132:135], v[200:203], v[92:95]
	v_mfma_f32_16x16x32_bf16 v[88:91], v[142:145], v[200:203], v[88:91]
	v_mfma_f32_16x16x32_bf16 v[76:79], v[132:135], v[210:213], v[76:79]
	v_mfma_f32_16x16x32_bf16 v[72:75], v[142:145], v[210:213], v[72:75]
	v_mfma_f32_16x16x32_bf16 v[116:119], v[146:149], v[172:175], v[116:119]
	v_mfma_f32_16x16x32_bf16 v[112:115], v[154:157], v[172:175], v[112:115]
	v_mfma_f32_16x16x32_bf16 v[100:103], v[146:149], v[184:187], v[100:103]
	v_mfma_f32_16x16x32_bf16 v[96:99], v[154:157], v[184:187], v[96:99]
	v_mfma_f32_16x16x32_bf16 v[84:87], v[146:149], v[192:195], v[84:87]
	v_mfma_f32_16x16x32_bf16 v[80:83], v[154:157], v[192:195], v[80:83]
	v_mfma_f32_16x16x32_bf16 v[68:71], v[146:149], v[206:209], v[68:71]
	v_mfma_f32_16x16x32_bf16 v[64:67], v[154:157], v[206:209], v[64:67]
	v_mfma_f32_16x16x32_bf16 v[116:119], v[150:153], v[180:183], v[116:119]
	v_mfma_f32_16x16x32_bf16 v[112:115], v[168:171], v[180:183], v[112:115]
	v_mfma_f32_16x16x32_bf16 v[100:103], v[150:153], v[188:191], v[100:103]
	v_mfma_f32_16x16x32_bf16 v[96:99], v[168:171], v[188:191], v[96:99]
	v_mfma_f32_16x16x32_bf16 v[84:87], v[150:153], v[200:203], v[84:87]
	v_mfma_f32_16x16x32_bf16 v[80:83], v[168:171], v[200:203], v[80:83]
	v_mfma_f32_16x16x32_bf16 v[68:71], v[150:153], v[210:213], v[68:71]
	v_mfma_f32_16x16x32_bf16 v[64:67], v[168:171], v[210:213], v[64:67]
	s_barrier
	s_add_i32 s8, s35, s75
	v_lshl_add_u64 v[176:177], v[176:177], 0, s[36:37]
	s_mov_b32 m0, s8
	ds_read_b128 v[172:175], v179 offset:49152
	ds_read_b128 v[180:183], v179 offset:50176
	ds_read_b128 v[184:187], v179 offset:51200
	ds_read_b128 v[188:191], v179 offset:52224
	ds_read_b128 v[192:195], v179 offset:53248
	ds_read_b128 v[200:203], v179 offset:54272
	ds_read_b128 v[206:209], v179 offset:55296
	ds_read_b128 v[210:213], v179 offset:56320
	global_load_lds_dwordx4 v[176:177], off
	v_lshl_add_u64 v[176:177], v[196:197], 0, s[36:37]
	s_add_i32 m0, s8, 0x2000
	s_add_i32 s8, s38, s75
	global_load_lds_dwordx4 v[176:177], off
	v_lshl_add_u64 v[176:177], v[198:199], 0, s[36:37]
	s_mov_b32 m0, s8
	s_nop 0
	global_load_lds_dwordx4 v[176:177], off
	v_lshl_add_u64 v[176:177], v[204:205], 0, s[36:37]
	s_add_i32 m0, s8, 0x2000
	s_nop 0
	global_load_lds_dwordx4 v[176:177], off
	v_lshl_add_u64 v[176:177], v[214:215], 0, s[36:37]
	s_mov_b32 m0, s29
	s_nop 0
	global_load_lds_dwordx4 v[176:177], off
	v_lshl_add_u64 v[176:177], v[216:217], 0, s[36:37]
	s_mov_b32 m0, s58
	s_nop 0
	global_load_lds_dwordx4 v[176:177], off
	s_waitcnt vmcnt(8)
	s_waitcnt lgkmcnt(0)
	s_barrier
	v_mfma_f32_16x16x32_bf16 v[60:63], v[128:131], v[172:175], v[60:63]
	v_mfma_f32_16x16x32_bf16 v[56:59], v[136:139], v[172:175], v[56:59]
	v_mfma_f32_16x16x32_bf16 v[44:47], v[128:131], v[184:187], v[44:47]
	v_mfma_f32_16x16x32_bf16 v[40:43], v[136:139], v[184:187], v[40:43]
	v_mfma_f32_16x16x32_bf16 v[28:31], v[128:131], v[192:195], v[28:31]
	v_mfma_f32_16x16x32_bf16 v[24:27], v[136:139], v[192:195], v[24:27]
	v_mfma_f32_16x16x32_bf16 v[12:15], v[128:131], v[206:209], v[12:15]
	v_mfma_f32_16x16x32_bf16 v[8:11], v[136:139], v[206:209], v[8:11]
	v_mfma_f32_16x16x32_bf16 v[60:63], v[132:135], v[180:183], v[60:63]
	v_mfma_f32_16x16x32_bf16 v[56:59], v[142:145], v[180:183], v[56:59]
	v_mfma_f32_16x16x32_bf16 v[44:47], v[132:135], v[188:191], v[44:47]
	v_mfma_f32_16x16x32_bf16 v[40:43], v[142:145], v[188:191], v[40:43]
	v_mfma_f32_16x16x32_bf16 v[28:31], v[132:135], v[200:203], v[28:31]
	v_mfma_f32_16x16x32_bf16 v[24:27], v[142:145], v[200:203], v[24:27]
	v_mfma_f32_16x16x32_bf16 v[12:15], v[132:135], v[210:213], v[12:15]
	v_mfma_f32_16x16x32_bf16 v[8:11], v[142:145], v[210:213], v[8:11]
	v_mfma_f32_16x16x32_bf16 v[52:55], v[146:149], v[172:175], v[52:55]
	v_mfma_f32_16x16x32_bf16 v[48:51], v[154:157], v[172:175], v[48:51]
	v_mfma_f32_16x16x32_bf16 v[36:39], v[146:149], v[184:187], v[36:39]
	v_mfma_f32_16x16x32_bf16 v[32:35], v[154:157], v[184:187], v[32:35]
	v_mfma_f32_16x16x32_bf16 v[20:23], v[146:149], v[192:195], v[20:23]
	v_mfma_f32_16x16x32_bf16 v[16:19], v[154:157], v[192:195], v[16:19]
	v_mfma_f32_16x16x32_bf16 v[4:7], v[146:149], v[206:209], v[4:7]
	v_mfma_f32_16x16x32_bf16 v[0:3], v[154:157], v[206:209], v[0:3]
	v_mfma_f32_16x16x32_bf16 v[52:55], v[150:153], v[180:183], v[52:55]
	v_mfma_f32_16x16x32_bf16 v[48:51], v[168:171], v[180:183], v[48:51]
	v_mfma_f32_16x16x32_bf16 v[36:39], v[150:153], v[188:191], v[36:39]
	v_mfma_f32_16x16x32_bf16 v[32:35], v[168:171], v[188:191], v[32:35]
	v_mfma_f32_16x16x32_bf16 v[20:23], v[150:153], v[200:203], v[20:23]
	v_mfma_f32_16x16x32_bf16 v[16:19], v[168:171], v[200:203], v[16:19]
	v_mfma_f32_16x16x32_bf16 v[4:7], v[150:153], v[210:213], v[4:7]
	v_mfma_f32_16x16x32_bf16 v[0:3], v[168:171], v[210:213], v[0:3]
	s_barrier
	s_add_u32 s6, s6, 0x100
	s_addc_u32 s7, s7, 0
	s_add_u32 s10, s10, 0x100
	s_addc_u32 s11, s11, 0
	s_cmp_ge_u32 s24, s12
	s_mov_b32 s8, s24
	s_cbranch_scc0 .LBB0_375
	s_and_b64 vcc, exec, s[52:53]
	s_cbranch_vccz .LBB0_378
	s_barrier

.LBB0_417:
	s_lshl_b64 s[10:11], s[52:53], 17
	s_add_u32 s56, s12, s10
	s_addc_u32 s57, s13, s11
	s_and_b64 s[10:11], s[40:41], exec
	s_cselect_b32 s11, s57, s9
	s_cselect_b32 s10, s56, s8
	s_add_i32 s55, 0, 0x10000
	s_add_i32 s38, 0, 0x14000
	v_add_u32_e32 v212, s55, v174
	v_add_u32_e32 v213, s38, v174
	ds_read_b128 v[0:3], v212
	ds_read_b128 v[4:7], v212 offset:1024
	ds_read_b128 v[8:11], v212 offset:2048
	ds_read_b128 v[12:15], v212 offset:3072
	ds_read_b128 v[16:19], v213
	ds_read_b128 v[20:23], v213 offset:1024
	ds_read_b128 v[24:27], v213 offset:2048
	ds_read_b128 v[28:31], v213 offset:3072
	s_add_u32 s60, s6, 0x40080
	s_addc_u32 s61, s7, 0
	s_add_i32 s59, s26, 0xc000
	v_lshl_add_u64 v[64:65], s[60:61], 0, v[162:163]
	s_mov_b32 m0, s59
	s_add_i32 s24, s26, 0xe000
	ds_read_b128 v[32:35], v175
	ds_read_b128 v[36:39], v175 offset:1024
	ds_read_b128 v[40:43], v175 offset:2048
	ds_read_b128 v[44:47], v175 offset:3072
	ds_read_b128 v[48:51], v175 offset:4096
	ds_read_b128 v[52:55], v175 offset:5120
	ds_read_b128 v[56:59], v175 offset:6144
	ds_read_b128 v[60:63], v175 offset:7168
	global_load_lds_dwordx4 v[64:65], off
	v_lshl_add_u64 v[64:65], s[60:61], 0, v[160:161]
	s_mov_b32 m0, s24
	s_nop 0
	global_load_lds_dwordx4 v[64:65], off
	s_waitcnt vmcnt(8)
	s_waitcnt lgkmcnt(0)
	s_barrier
	v_mfma_f32_16x16x32_bf16 v[64:67], v[0:3], v[32:35], 0
	v_mfma_f32_16x16x32_bf16 v[68:71], v[8:11], v[32:35], 0
	v_mfma_f32_16x16x32_bf16 v[72:75], v[0:3], v[40:43], 0
	v_mfma_f32_16x16x32_bf16 v[76:79], v[8:11], v[40:43], 0
	v_mfma_f32_16x16x32_bf16 v[80:83], v[0:3], v[48:51], 0
	v_mfma_f32_16x16x32_bf16 v[84:87], v[8:11], v[48:51], 0
	v_mfma_f32_16x16x32_bf16 v[88:91], v[0:3], v[56:59], 0
	v_mfma_f32_16x16x32_bf16 v[92:95], v[8:11], v[56:59], 0
	v_mfma_f32_16x16x32_bf16 v[64:67], v[4:7], v[36:39], v[64:67]
	v_mfma_f32_16x16x32_bf16 v[68:71], v[12:15], v[36:39], v[68:71]
	v_mfma_f32_16x16x32_bf16 v[72:75], v[4:7], v[44:47], v[72:75]
	v_mfma_f32_16x16x32_bf16 v[76:79], v[12:15], v[44:47], v[76:79]
	v_mfma_f32_16x16x32_bf16 v[80:83], v[4:7], v[52:55], v[80:83]
	v_mfma_f32_16x16x32_bf16 v[84:87], v[12:15], v[52:55], v[84:87]
	v_mfma_f32_16x16x32_bf16 v[88:91], v[4:7], v[60:63], v[88:91]
	v_mfma_f32_16x16x32_bf16 v[92:95], v[12:15], v[60:63], v[92:95]
	v_mfma_f32_16x16x32_bf16 v[96:99], v[16:19], v[32:35], 0
	v_mfma_f32_16x16x32_bf16 v[32:35], v[24:27], v[32:35], 0
	v_mfma_f32_16x16x32_bf16 v[96:99], v[20:23], v[36:39], v[96:99]
	v_mfma_f32_16x16x32_bf16 v[32:35], v[28:31], v[36:39], v[32:35]
	v_mfma_f32_16x16x32_bf16 v[36:39], v[16:19], v[40:43], 0
	v_mfma_f32_16x16x32_bf16 v[40:43], v[24:27], v[40:43], 0
	v_mfma_f32_16x16x32_bf16 v[36:39], v[20:23], v[44:47], v[36:39]
	v_mfma_f32_16x16x32_bf16 v[40:43], v[28:31], v[44:47], v[40:43]
	v_mfma_f32_16x16x32_bf16 v[44:47], v[16:19], v[48:51], 0
	v_mfma_f32_16x16x32_bf16 v[48:51], v[24:27], v[48:51], 0
	v_mfma_f32_16x16x32_bf16 v[44:47], v[20:23], v[52:55], v[44:47]
	v_mfma_f32_16x16x32_bf16 v[48:51], v[28:31], v[52:55], v[48:51]
	v_mfma_f32_16x16x32_bf16 v[52:55], v[16:19], v[56:59], 0
	v_mfma_f32_16x16x32_bf16 v[56:59], v[24:27], v[56:59], 0
	v_mfma_f32_16x16x32_bf16 v[52:55], v[20:23], v[60:63], v[52:55]
	v_mfma_f32_16x16x32_bf16 v[56:59], v[28:31], v[60:63], v[56:59]
	s_barrier
	s_add_i32 s55, s55, s15
	v_lshl_add_u64 v[172:173], s[8:9], 0, v[140:141]
	s_mov_b64 s[2:3], 0x100
	s_add_i32 s35, s55, 0x2000
	v_lshl_add_u64 v[128:129], v[172:173], 0, s[2:3]
	s_mov_b32 m0, s55
	v_lshl_add_u64 v[196:197], s[8:9], 0, v[158:159]
	s_add_u32 s60, s8, 0x10100
	ds_read_b128 v[60:63], v175 offset:16384
	ds_read_b128 v[100:103], v175 offset:17408
	ds_read_b128 v[104:107], v175 offset:18432
	ds_read_b128 v[108:111], v175 offset:19456
	ds_read_b128 v[112:115], v175 offset:20480
	ds_read_b128 v[116:119], v175 offset:21504
	ds_read_b128 v[120:123], v175 offset:22528
	ds_read_b128 v[124:127], v175 offset:23552
	global_load_lds_dwordx4 v[128:129], off
	v_lshl_add_u64 v[128:129], v[196:197], 0, s[2:3]
	s_mov_b32 m0, s35
	s_addc_u32 s61, s9, 0
	s_add_i32 s38, s38, s15
	global_load_lds_dwordx4 v[128:129], off
	v_lshl_add_u64 v[128:129], s[60:61], 0, v[140:141]
	s_mov_b32 m0, s38
	s_add_i32 s53, s38, 0x2000
	global_load_lds_dwordx4 v[128:129], off
	v_lshl_add_u64 v[128:129], s[60:61], 0, v[158:159]
	s_mov_b32 m0, s53
	v_lshl_add_u64 v[198:199], s[6:7], 0, v[162:163]
	global_load_lds_dwordx4 v[128:129], off
	v_lshl_add_u64 v[128:129], v[198:199], 0, s[2:3]
	s_mov_b32 m0, s26
	v_lshl_add_u64 v[204:205], s[6:7], 0, v[160:161]
	global_load_lds_dwordx4 v[128:129], off
	v_lshl_add_u64 v[128:129], v[204:205], 0, s[2:3]
	s_mov_b32 m0, s27
	s_nop 0
	global_load_lds_dwordx4 v[128:129], off
	s_waitcnt vmcnt(8)
	s_waitcnt lgkmcnt(0)
	s_barrier
	v_mfma_f32_16x16x32_bf16 v[128:131], v[0:3], v[60:63], 0
	v_mfma_f32_16x16x32_bf16 v[136:139], v[0:3], v[104:107], 0
	v_mfma_f32_16x16x32_bf16 v[146:149], v[0:3], v[112:115], 0
	v_mfma_f32_16x16x32_bf16 v[0:3], v[0:3], v[120:123], 0
	v_mfma_f32_16x16x32_bf16 v[128:131], v[4:7], v[100:103], v[128:131]
	v_mfma_f32_16x16x32_bf16 v[132:135], v[8:11], v[60:63], 0
	v_mfma_f32_16x16x32_bf16 v[136:139], v[4:7], v[108:111], v[136:139]
	v_mfma_f32_16x16x32_bf16 v[146:149], v[4:7], v[116:119], v[146:149]
	v_mfma_f32_16x16x32_bf16 v[0:3], v[4:7], v[124:127], v[0:3]
	v_mfma_f32_16x16x32_bf16 v[4:7], v[8:11], v[120:123], 0
	v_mfma_f32_16x16x32_bf16 v[132:135], v[12:15], v[100:103], v[132:135]
	v_mfma_f32_16x16x32_bf16 v[142:145], v[8:11], v[104:107], 0
	v_mfma_f32_16x16x32_bf16 v[150:153], v[8:11], v[112:115], 0
	v_mfma_f32_16x16x32_bf16 v[4:7], v[12:15], v[124:127], v[4:7]
	v_mfma_f32_16x16x32_bf16 v[142:145], v[12:15], v[108:111], v[142:145]
	v_mfma_f32_16x16x32_bf16 v[150:153], v[12:15], v[116:119], v[150:153]
	v_mfma_f32_16x16x32_bf16 v[8:11], v[16:19], v[60:63], 0
	v_mfma_f32_16x16x32_bf16 v[12:15], v[24:27], v[60:63], 0
	v_mfma_f32_16x16x32_bf16 v[8:11], v[20:23], v[100:103], v[8:11]
	v_mfma_f32_16x16x32_bf16 v[12:15], v[28:31], v[100:103], v[12:15]
	v_mfma_f32_16x16x32_bf16 v[60:63], v[16:19], v[104:107], 0
	v_mfma_f32_16x16x32_bf16 v[100:103], v[24:27], v[104:107], 0
	v_mfma_f32_16x16x32_bf16 v[104:107], v[16:19], v[112:115], 0
	v_mfma_f32_16x16x32_bf16 v[16:19], v[16:19], v[120:123], 0
	v_mfma_f32_16x16x32_bf16 v[60:63], v[20:23], v[108:111], v[60:63]
	v_mfma_f32_16x16x32_bf16 v[100:103], v[28:31], v[108:111], v[100:103]
	v_mfma_f32_16x16x32_bf16 v[104:107], v[20:23], v[116:119], v[104:107]
	v_mfma_f32_16x16x32_bf16 v[108:111], v[24:27], v[112:115], 0
	v_mfma_f32_16x16x32_bf16 v[16:19], v[20:23], v[124:127], v[16:19]
	v_mfma_f32_16x16x32_bf16 v[20:23], v[24:27], v[120:123], 0
	v_mfma_f32_16x16x32_bf16 v[108:111], v[28:31], v[116:119], v[108:111]
	v_mfma_f32_16x16x32_bf16 v[20:23], v[28:31], v[124:127], v[20:23]
	s_barrier
	s_add_i32 s58, 0, 0x18000
	s_add_i32 s76, 0, 0x1c000
	v_add_u32_e32 v222, s58, v174
	v_add_u32_e32 v223, s76, v174
	ds_read_b128 v[24:27], v222
	ds_read_b128 v[28:31], v222 offset:1024
	ds_read_b128 v[112:115], v222 offset:2048
	ds_read_b128 v[116:119], v222 offset:3072
	ds_read_b128 v[120:123], v223
	ds_read_b128 v[124:127], v223 offset:1024
	ds_read_b128 v[154:157], v223 offset:2048
	ds_read_b128 v[164:167], v223 offset:3072
	s_add_u32 s60, s6, 0x40100
	s_addc_u32 s61, s7, 0
	s_mov_b32 m0, s28
	v_lshl_add_u64 v[210:211], s[60:61], 0, v[162:163]
	ds_read_b128 v[168:171], v175 offset:32768
	ds_read_b128 v[176:179], v175 offset:33792
	ds_read_b128 v[180:183], v175 offset:34816
	ds_read_b128 v[184:187], v175 offset:35840
	ds_read_b128 v[188:191], v175 offset:36864
	ds_read_b128 v[192:195], v175 offset:37888
	ds_read_b128 v[200:203], v175 offset:38912
	ds_read_b128 v[206:209], v175 offset:39936
	global_load_lds_dwordx4 v[210:211], off
	v_lshl_add_u64 v[210:211], s[60:61], 0, v[160:161]
	s_mov_b32 m0, s29
	s_nop 0
	global_load_lds_dwordx4 v[210:211], off
	s_waitcnt vmcnt(8)
	s_waitcnt lgkmcnt(0)
	s_barrier
	v_mfma_f32_16x16x32_bf16 v[64:67], v[24:27], v[168:171], v[64:67]
	v_mfma_f32_16x16x32_bf16 v[68:71], v[112:115], v[168:171], v[68:71]
	v_mfma_f32_16x16x32_bf16 v[72:75], v[24:27], v[180:183], v[72:75]
	v_mfma_f32_16x16x32_bf16 v[76:79], v[112:115], v[180:183], v[76:79]
	v_mfma_f32_16x16x32_bf16 v[80:83], v[24:27], v[188:191], v[80:83]
	v_mfma_f32_16x16x32_bf16 v[84:87], v[112:115], v[188:191], v[84:87]
	v_mfma_f32_16x16x32_bf16 v[88:91], v[24:27], v[200:203], v[88:91]
	v_mfma_f32_16x16x32_bf16 v[92:95], v[112:115], v[200:203], v[92:95]
	v_mfma_f32_16x16x32_bf16 v[64:67], v[28:31], v[176:179], v[64:67]
	v_mfma_f32_16x16x32_bf16 v[68:71], v[116:119], v[176:179], v[68:71]
	v_mfma_f32_16x16x32_bf16 v[72:75], v[28:31], v[184:187], v[72:75]
	v_mfma_f32_16x16x32_bf16 v[76:79], v[116:119], v[184:187], v[76:79]
	v_mfma_f32_16x16x32_bf16 v[80:83], v[28:31], v[192:195], v[80:83]
	v_mfma_f32_16x16x32_bf16 v[84:87], v[116:119], v[192:195], v[84:87]
	v_mfma_f32_16x16x32_bf16 v[88:91], v[28:31], v[206:209], v[88:91]
	v_mfma_f32_16x16x32_bf16 v[92:95], v[116:119], v[206:209], v[92:95]
	v_mfma_f32_16x16x32_bf16 v[96:99], v[120:123], v[168:171], v[96:99]
	v_mfma_f32_16x16x32_bf16 v[32:35], v[154:157], v[168:171], v[32:35]
	v_mfma_f32_16x16x32_bf16 v[36:39], v[120:123], v[180:183], v[36:39]
	v_mfma_f32_16x16x32_bf16 v[40:43], v[154:157], v[180:183], v[40:43]
	v_mfma_f32_16x16x32_bf16 v[44:47], v[120:123], v[188:191], v[44:47]
	v_mfma_f32_16x16x32_bf16 v[48:51], v[154:157], v[188:191], v[48:51]
	v_mfma_f32_16x16x32_bf16 v[52:55], v[120:123], v[200:203], v[52:55]
	v_mfma_f32_16x16x32_bf16 v[56:59], v[154:157], v[200:203], v[56:59]
	v_mfma_f32_16x16x32_bf16 v[96:99], v[124:127], v[176:179], v[96:99]
	v_mfma_f32_16x16x32_bf16 v[32:35], v[164:167], v[176:179], v[32:35]
	v_mfma_f32_16x16x32_bf16 v[36:39], v[124:127], v[184:187], v[36:39]
	v_mfma_f32_16x16x32_bf16 v[40:43], v[164:167], v[184:187], v[40:43]
	v_mfma_f32_16x16x32_bf16 v[44:47], v[124:127], v[192:195], v[44:47]
	v_mfma_f32_16x16x32_bf16 v[48:51], v[164:167], v[192:195], v[48:51]
	v_mfma_f32_16x16x32_bf16 v[52:55], v[124:127], v[206:209], v[52:55]
	v_mfma_f32_16x16x32_bf16 v[56:59], v[164:167], v[206:209], v[56:59]
	s_barrier
	s_add_i32 s60, s58, s15
	s_mov_b64 s[2:3], 0x180
	s_add_i32 s58, s60, 0x2000
	v_lshl_add_u64 v[172:173], v[172:173], 0, s[2:3]
	s_mov_b32 m0, s60
	s_add_u32 s84, s8, 0x10180
	ds_read_b128 v[168:171], v175 offset:49152
	ds_read_b128 v[176:179], v175 offset:50176
	ds_read_b128 v[180:183], v175 offset:51200
	ds_read_b128 v[184:187], v175 offset:52224
	ds_read_b128 v[188:191], v175 offset:53248
	ds_read_b128 v[192:195], v175 offset:54272
	ds_read_b128 v[200:203], v175 offset:55296
	ds_read_b128 v[206:209], v175 offset:56320
	global_load_lds_dwordx4 v[172:173], off
	v_lshl_add_u64 v[172:173], v[196:197], 0, s[2:3]
	s_mov_b32 m0, s58
	s_addc_u32 s85, s9, 0
	s_add_i32 s8, s76, s15
	global_load_lds_dwordx4 v[172:173], off
	v_lshl_add_u64 v[172:173], s[84:85], 0, v[140:141]
	s_mov_b32 m0, s8
	s_add_i32 s9, s8, 0x2000
	global_load_lds_dwordx4 v[172:173], off
	v_lshl_add_u64 v[172:173], s[84:85], 0, v[158:159]
	s_mov_b32 m0, s9
	s_nop 0
	global_load_lds_dwordx4 v[172:173], off
	v_lshl_add_u64 v[172:173], v[198:199], 0, s[2:3]
	s_mov_b32 m0, s74
	s_nop 0
	global_load_lds_dwordx4 v[172:173], off
	v_lshl_add_u64 v[172:173], v[204:205], 0, s[2:3]
	s_mov_b32 m0, s75
	s_nop 0
	global_load_lds_dwordx4 v[172:173], off
	s_waitcnt vmcnt(8)
	s_waitcnt lgkmcnt(0)
	s_barrier
	v_mfma_f32_16x16x32_bf16 v[132:135], v[112:115], v[168:171], v[132:135]
	v_mfma_f32_16x16x32_bf16 v[136:139], v[24:27], v[180:183], v[136:139]
	v_mfma_f32_16x16x32_bf16 v[0:3], v[24:27], v[200:203], v[0:3]
	v_mfma_f32_16x16x32_bf16 v[4:7], v[112:115], v[200:203], v[4:7]
	v_mfma_f32_16x16x32_bf16 v[128:131], v[24:27], v[168:171], v[128:131]
	v_mfma_f32_16x16x32_bf16 v[132:135], v[116:119], v[176:179], v[132:135]
	v_mfma_f32_16x16x32_bf16 v[136:139], v[28:31], v[184:187], v[136:139]
	v_mfma_f32_16x16x32_bf16 v[142:145], v[112:115], v[180:183], v[142:145]
	v_mfma_f32_16x16x32_bf16 v[146:149], v[24:27], v[188:191], v[146:149]
	v_mfma_f32_16x16x32_bf16 v[150:153], v[112:115], v[188:191], v[150:153]
	v_mfma_f32_16x16x32_bf16 v[0:3], v[28:31], v[206:209], v[0:3]
	v_mfma_f32_16x16x32_bf16 v[4:7], v[116:119], v[206:209], v[4:7]
	v_mfma_f32_16x16x32_bf16 v[128:131], v[28:31], v[176:179], v[128:131]
	v_mfma_f32_16x16x32_bf16 v[142:145], v[116:119], v[184:187], v[142:145]
	v_mfma_f32_16x16x32_bf16 v[146:149], v[28:31], v[192:195], v[146:149]
	v_mfma_f32_16x16x32_bf16 v[150:153], v[116:119], v[192:195], v[150:153]
	v_mfma_f32_16x16x32_bf16 v[8:11], v[120:123], v[168:171], v[8:11]
	v_mfma_f32_16x16x32_bf16 v[12:15], v[154:157], v[168:171], v[12:15]
	v_mfma_f32_16x16x32_bf16 v[24:27], v[120:123], v[180:183], v[60:63]
	v_mfma_f32_16x16x32_bf16 v[28:31], v[154:157], v[180:183], v[100:103]
	v_mfma_f32_16x16x32_bf16 v[60:63], v[120:123], v[188:191], v[104:107]
	v_mfma_f32_16x16x32_bf16 v[100:103], v[154:157], v[188:191], v[108:111]
	v_mfma_f32_16x16x32_bf16 v[16:19], v[120:123], v[200:203], v[16:19]
	v_mfma_f32_16x16x32_bf16 v[20:23], v[154:157], v[200:203], v[20:23]
	v_mfma_f32_16x16x32_bf16 v[8:11], v[124:127], v[176:179], v[8:11]
	v_mfma_f32_16x16x32_bf16 v[12:15], v[164:167], v[176:179], v[12:15]
	v_mfma_f32_16x16x32_bf16 v[24:27], v[124:127], v[184:187], v[24:27]
	v_mfma_f32_16x16x32_bf16 v[28:31], v[164:167], v[184:187], v[28:31]
	v_mfma_f32_16x16x32_bf16 v[60:63], v[124:127], v[192:195], v[60:63]
	v_mfma_f32_16x16x32_bf16 v[100:103], v[164:167], v[192:195], v[100:103]
	v_mfma_f32_16x16x32_bf16 v[16:19], v[124:127], v[206:209], v[16:19]
	v_mfma_f32_16x16x32_bf16 v[20:23], v[164:167], v[206:209], v[20:23]
	s_barrier
	ds_read_b128 v[104:107], v212
	ds_read_b128 v[108:111], v212 offset:1024
	ds_read_b128 v[112:115], v212 offset:2048
	ds_read_b128 v[116:119], v212 offset:3072
	ds_read_b128 v[120:123], v213
	ds_read_b128 v[124:127], v213 offset:1024
	ds_read_b128 v[154:157], v213 offset:2048
	ds_read_b128 v[164:167], v213 offset:3072
	s_add_u32 s6, s6, 0x40180
	s_addc_u32 s7, s7, 0
	s_mov_b32 m0, s59
	v_lshl_add_u64 v[172:173], s[6:7], 0, v[162:163]
	ds_read_b128 v[168:171], v175
	ds_read_b128 v[176:179], v175 offset:1024
	ds_read_b128 v[180:183], v175 offset:2048
	ds_read_b128 v[184:187], v175 offset:3072
	ds_read_b128 v[188:191], v175 offset:4096
	ds_read_b128 v[192:195], v175 offset:5120
	ds_read_b128 v[200:203], v175 offset:6144
	ds_read_b128 v[206:209], v175 offset:7168
	global_load_lds_dwordx4 v[172:173], off
	v_lshl_add_u64 v[172:173], s[6:7], 0, v[160:161]
	s_mov_b32 m0, s24
	s_nop 0
	global_load_lds_dwordx4 v[172:173], off
	s_waitcnt vmcnt(8)
	s_waitcnt lgkmcnt(0)
	s_barrier
	v_mfma_f32_16x16x32_bf16 v[64:67], v[104:107], v[168:171], v[64:67]
	v_mfma_f32_16x16x32_bf16 v[68:71], v[112:115], v[168:171], v[68:71]
	v_mfma_f32_16x16x32_bf16 v[72:75], v[104:107], v[180:183], v[72:75]
	v_mfma_f32_16x16x32_bf16 v[76:79], v[112:115], v[180:183], v[76:79]
	v_mfma_f32_16x16x32_bf16 v[80:83], v[104:107], v[188:191], v[80:83]
	v_mfma_f32_16x16x32_bf16 v[84:87], v[112:115], v[188:191], v[84:87]
	v_mfma_f32_16x16x32_bf16 v[88:91], v[104:107], v[200:203], v[88:91]
	v_mfma_f32_16x16x32_bf16 v[64:67], v[108:111], v[176:179], v[64:67]
	v_mfma_f32_16x16x32_bf16 v[68:71], v[116:119], v[176:179], v[68:71]
	v_mfma_f32_16x16x32_bf16 v[72:75], v[108:111], v[184:187], v[72:75]
	v_mfma_f32_16x16x32_bf16 v[76:79], v[116:119], v[184:187], v[76:79]
	v_mfma_f32_16x16x32_bf16 v[80:83], v[108:111], v[192:195], v[80:83]
	v_mfma_f32_16x16x32_bf16 v[84:87], v[116:119], v[192:195], v[84:87]
	v_mfma_f32_16x16x32_bf16 v[210:213], v[108:111], v[206:209], v[88:91]
	v_mfma_f32_16x16x32_bf16 v[88:91], v[112:115], v[200:203], v[92:95]
	v_mfma_f32_16x16x32_bf16 v[214:217], v[116:119], v[206:209], v[88:91]
	v_mfma_f32_16x16x32_bf16 v[88:91], v[120:123], v[168:171], v[96:99]
	v_mfma_f32_16x16x32_bf16 v[32:35], v[154:157], v[168:171], v[32:35]
	v_mfma_f32_16x16x32_bf16 v[36:39], v[120:123], v[180:183], v[36:39]
	v_mfma_f32_16x16x32_bf16 v[40:43], v[154:157], v[180:183], v[40:43]
	v_mfma_f32_16x16x32_bf16 v[44:47], v[120:123], v[188:191], v[44:47]
	v_mfma_f32_16x16x32_bf16 v[48:51], v[154:157], v[188:191], v[48:51]
	v_mfma_f32_16x16x32_bf16 v[52:55], v[120:123], v[200:203], v[52:55]
	v_mfma_f32_16x16x32_bf16 v[56:59], v[154:157], v[200:203], v[56:59]
	v_mfma_f32_16x16x32_bf16 v[96:99], v[124:127], v[176:179], v[88:91]
	v_mfma_f32_16x16x32_bf16 v[32:35], v[164:167], v[176:179], v[32:35]
	v_mfma_f32_16x16x32_bf16 v[36:39], v[124:127], v[184:187], v[36:39]
	v_mfma_f32_16x16x32_bf16 v[40:43], v[164:167], v[184:187], v[40:43]
	v_mfma_f32_16x16x32_bf16 v[44:47], v[124:127], v[192:195], v[44:47]
	v_mfma_f32_16x16x32_bf16 v[48:51], v[164:167], v[192:195], v[48:51]
	v_mfma_f32_16x16x32_bf16 v[52:55], v[124:127], v[206:209], v[52:55]
	v_mfma_f32_16x16x32_bf16 v[56:59], v[164:167], v[206:209], v[56:59]
	s_barrier
	s_mov_b32 m0, s55
	v_lshl_add_u64 v[172:173], s[10:11], 0, v[140:141]
	s_add_u32 s6, s10, 0x10000
	ds_read_b128 v[88:91], v175 offset:16384
	ds_read_b128 v[92:95], v175 offset:17408
	ds_read_b128 v[168:171], v175 offset:18432
	ds_read_b128 v[176:179], v175 offset:19456
	ds_read_b128 v[180:183], v175 offset:20480
	ds_read_b128 v[184:187], v175 offset:21504
	ds_read_b128 v[188:191], v175 offset:22528
	ds_read_b128 v[192:195], v175 offset:23552
	global_load_lds_dwordx4 v[172:173], off
	v_lshl_add_u64 v[196:197], s[10:11], 0, v[158:159]
	s_mov_b32 m0, s35
	s_addc_u32 s7, s11, 0
	global_load_lds_dwordx4 v[196:197], off
	v_lshl_add_u64 v[198:199], s[6:7], 0, v[140:141]
	s_mov_b32 m0, s38
	v_lshl_add_u64 v[204:205], s[42:43], 0, v[160:161]
	global_load_lds_dwordx4 v[198:199], off
	v_lshl_add_u64 v[198:199], s[6:7], 0, v[158:159]
	s_mov_b32 m0, s53
	s_nop 0
	global_load_lds_dwordx4 v[198:199], off
	v_lshl_add_u64 v[198:199], s[42:43], 0, v[162:163]
	s_mov_b32 m0, s26
	s_nop 0
	global_load_lds_dwordx4 v[198:199], off
	s_mov_b32 m0, s27
	s_nop 0
	global_load_lds_dwordx4 v[204:205], off
	s_waitcnt vmcnt(8)
	s_waitcnt lgkmcnt(0)
	s_barrier
	v_mfma_f32_16x16x32_bf16 v[132:135], v[112:115], v[88:91], v[132:135]
	v_mfma_f32_16x16x32_bf16 v[200:203], v[116:119], v[92:95], v[132:135]
	v_mfma_f32_16x16x32_bf16 v[132:135], v[104:107], v[168:171], v[136:139]
	v_mfma_f32_16x16x32_bf16 v[206:209], v[108:111], v[176:179], v[132:135]
	v_mfma_f32_16x16x32_bf16 v[132:135], v[112:115], v[168:171], v[142:145]
	v_mfma_f32_16x16x32_bf16 v[142:145], v[116:119], v[176:179], v[132:135]
	v_mfma_f32_16x16x32_bf16 v[132:135], v[104:107], v[180:183], v[146:149]
	v_mfma_f32_16x16x32_bf16 v[0:3], v[104:107], v[188:191], v[0:3]
	v_mfma_f32_16x16x32_bf16 v[4:7], v[112:115], v[188:191], v[4:7]
	v_mfma_f32_16x16x32_bf16 v[128:131], v[104:107], v[88:91], v[128:131]
	v_mfma_f32_16x16x32_bf16 v[146:149], v[108:111], v[184:187], v[132:135]
	v_mfma_f32_16x16x32_bf16 v[132:135], v[112:115], v[180:183], v[150:153]
	v_mfma_f32_16x16x32_bf16 v[0:3], v[108:111], v[192:195], v[0:3]
	v_mfma_f32_16x16x32_bf16 v[4:7], v[116:119], v[192:195], v[4:7]
	v_mfma_f32_16x16x32_bf16 v[128:131], v[108:111], v[92:95], v[128:131]
	v_mfma_f32_16x16x32_bf16 v[150:153], v[116:119], v[184:187], v[132:135]
	v_mfma_f32_16x16x32_bf16 v[8:11], v[120:123], v[88:91], v[8:11]
	v_mfma_f32_16x16x32_bf16 v[112:115], v[124:127], v[92:95], v[8:11]
	v_mfma_f32_16x16x32_bf16 v[8:11], v[154:157], v[88:91], v[12:15]
	v_mfma_f32_16x16x32_bf16 v[116:119], v[164:167], v[92:95], v[8:11]
	v_mfma_f32_16x16x32_bf16 v[8:11], v[120:123], v[168:171], v[24:27]
	v_mfma_f32_16x16x32_bf16 v[218:221], v[124:127], v[176:179], v[8:11]
	v_mfma_f32_16x16x32_bf16 v[8:11], v[154:157], v[168:171], v[28:31]
	v_mfma_f32_16x16x32_bf16 v[168:171], v[164:167], v[176:179], v[8:11]
	v_mfma_f32_16x16x32_bf16 v[8:11], v[120:123], v[180:183], v[60:63]
	v_mfma_f32_16x16x32_bf16 v[176:179], v[124:127], v[184:187], v[8:11]
	v_mfma_f32_16x16x32_bf16 v[8:11], v[154:157], v[180:183], v[100:103]
	v_mfma_f32_16x16x32_bf16 v[180:183], v[164:167], v[184:187], v[8:11]
	v_mfma_f32_16x16x32_bf16 v[8:11], v[120:123], v[188:191], v[16:19]
	v_mfma_f32_16x16x32_bf16 v[184:187], v[124:127], v[192:195], v[8:11]
	v_mfma_f32_16x16x32_bf16 v[8:11], v[154:157], v[188:191], v[20:23]
	v_mfma_f32_16x16x32_bf16 v[154:157], v[164:167], v[192:195], v[8:11]
	s_barrier
	s_nop 4
	ds_read_b128 v[8:11], v222
	ds_read_b128 v[12:15], v222 offset:1024
	ds_read_b128 v[16:19], v222 offset:2048
	ds_read_b128 v[20:23], v222 offset:3072
	ds_read_b128 v[164:167], v223
	ds_read_b128 v[188:191], v223 offset:1024
	ds_read_b128 v[192:195], v223 offset:2048
	ds_read_b128 v[222:225], v223 offset:3072
	s_add_u32 s6, s42, 0x40000
	s_addc_u32 s7, s43, 0
	s_mov_b32 m0, s28
	v_lshl_add_u64 v[88:89], s[6:7], 0, v[162:163]
	ds_read_b128 v[24:27], v175 offset:32768
	ds_read_b128 v[28:31], v175 offset:33792
	ds_read_b128 v[60:63], v175 offset:34816
	ds_read_b128 v[226:229], v175 offset:35840
	ds_read_b128 v[230:233], v175 offset:36864
	ds_read_b128 v[234:237], v175 offset:37888
	ds_read_b128 v[238:241], v175 offset:38912
	ds_read_b128 v[242:245], v175 offset:39936
	global_load_lds_dwordx4 v[88:89], off
	v_lshl_add_u64 v[88:89], s[6:7], 0, v[160:161]
	s_mov_b32 m0, s29
	s_nop 0
	global_load_lds_dwordx4 v[88:89], off
	s_waitcnt vmcnt(8)
	s_waitcnt lgkmcnt(0)
	s_barrier
	v_mfma_f32_16x16x32_bf16 v[64:67], v[8:11], v[24:27], v[64:67]
	v_mfma_f32_16x16x32_bf16 v[132:135], v[12:15], v[28:31], v[64:67]
	v_mfma_f32_16x16x32_bf16 v[64:67], v[16:19], v[24:27], v[68:71]
	v_mfma_f32_16x16x32_bf16 v[136:139], v[20:23], v[28:31], v[64:67]
	v_mfma_f32_16x16x32_bf16 v[64:67], v[8:11], v[60:63], v[72:75]
	v_mfma_f32_16x16x32_bf16 v[108:111], v[12:15], v[226:229], v[64:67]
	v_mfma_f32_16x16x32_bf16 v[64:67], v[16:19], v[60:63], v[76:79]
	v_mfma_f32_16x16x32_bf16 v[104:107], v[20:23], v[226:229], v[64:67]
	v_mfma_f32_16x16x32_bf16 v[64:67], v[8:11], v[230:233], v[80:83]
	v_mfma_f32_16x16x32_bf16 v[88:91], v[12:15], v[234:237], v[64:67]
	v_mfma_f32_16x16x32_bf16 v[64:67], v[16:19], v[230:233], v[84:87]
	v_mfma_f32_16x16x32_bf16 v[92:95], v[20:23], v[234:237], v[64:67]
	v_mfma_f32_16x16x32_bf16 v[64:67], v[8:11], v[238:241], v[210:213]
	v_mfma_f32_16x16x32_bf16 v[76:79], v[12:15], v[242:245], v[64:67]
	v_mfma_f32_16x16x32_bf16 v[64:67], v[16:19], v[238:241], v[214:217]
	v_mfma_f32_16x16x32_bf16 v[72:75], v[20:23], v[242:245], v[64:67]
	v_mfma_f32_16x16x32_bf16 v[64:67], v[164:167], v[24:27], v[96:99]
	v_mfma_f32_16x16x32_bf16 v[24:27], v[192:195], v[24:27], v[32:35]
	v_mfma_f32_16x16x32_bf16 v[120:123], v[222:225], v[28:31], v[24:27]
	v_mfma_f32_16x16x32_bf16 v[24:27], v[164:167], v[60:63], v[36:39]
	v_mfma_f32_16x16x32_bf16 v[100:103], v[188:191], v[226:229], v[24:27]
	v_mfma_f32_16x16x32_bf16 v[24:27], v[192:195], v[60:63], v[40:43]
	v_mfma_f32_16x16x32_bf16 v[96:99], v[222:225], v[226:229], v[24:27]
	v_mfma_f32_16x16x32_bf16 v[24:27], v[164:167], v[230:233], v[44:47]
	v_mfma_f32_16x16x32_bf16 v[84:87], v[188:191], v[234:237], v[24:27]
	v_mfma_f32_16x16x32_bf16 v[24:27], v[192:195], v[230:233], v[48:51]
	v_mfma_f32_16x16x32_bf16 v[80:83], v[222:225], v[234:237], v[24:27]
	v_mfma_f32_16x16x32_bf16 v[24:27], v[164:167], v[238:241], v[52:55]
	v_mfma_f32_16x16x32_bf16 v[68:71], v[188:191], v[242:245], v[24:27]
	v_mfma_f32_16x16x32_bf16 v[24:27], v[192:195], v[238:241], v[56:59]
	v_mfma_f32_16x16x32_bf16 v[124:127], v[188:191], v[28:31], v[64:67]
	v_mfma_f32_16x16x32_bf16 v[64:67], v[222:225], v[242:245], v[24:27]
	s_barrier
	s_mov_b32 m0, s60
	s_nop 2
	v_lshl_add_u64 v[24:25], v[172:173], 0, s[36:37]
	s_add_u32 s6, s10, 0x10080
	ds_read_b128 v[32:35], v175 offset:49152
	ds_read_b128 v[36:39], v175 offset:50176
	ds_read_b128 v[210:213], v175 offset:51200
	ds_read_b128 v[214:217], v175 offset:52224
	ds_read_b128 v[226:229], v175 offset:53248
	ds_read_b128 v[230:233], v175 offset:54272
	ds_read_b128 v[234:237], v175 offset:55296
	ds_read_b128 v[238:241], v175 offset:56320
	global_load_lds_dwordx4 v[24:25], off
	v_lshl_add_u64 v[24:25], v[196:197], 0, s[36:37]
	s_mov_b32 m0, s58
	s_addc_u32 s7, s11, 0
	global_load_lds_dwordx4 v[24:25], off
	v_lshl_add_u64 v[24:25], s[6:7], 0, v[140:141]
	s_mov_b32 m0, s8
	s_nop 0
	global_load_lds_dwordx4 v[24:25], off
	v_lshl_add_u64 v[24:25], s[6:7], 0, v[158:159]
	s_mov_b32 m0, s9
	s_nop 0
	global_load_lds_dwordx4 v[24:25], off
	v_lshl_add_u64 v[24:25], v[198:199], 0, s[36:37]
	s_mov_b32 m0, s74
	s_nop 0
	global_load_lds_dwordx4 v[24:25], off
	v_lshl_add_u64 v[24:25], v[204:205], 0, s[36:37]
	s_mov_b32 m0, s75
	s_nop 0
	global_load_lds_dwordx4 v[24:25], off
	s_waitcnt vmcnt(8)
	s_waitcnt lgkmcnt(0)
	s_barrier
	v_mfma_f32_16x16x32_bf16 v[24:27], v[8:11], v[32:35], v[128:131]
	v_mfma_f32_16x16x32_bf16 v[56:59], v[12:15], v[36:39], v[24:27]
	v_mfma_f32_16x16x32_bf16 v[24:27], v[16:19], v[32:35], v[200:203]
	v_mfma_f32_16x16x32_bf16 v[60:63], v[20:23], v[36:39], v[24:27]
	v_mfma_f32_16x16x32_bf16 v[24:27], v[8:11], v[210:213], v[206:209]
	v_mfma_f32_16x16x32_bf16 v[44:47], v[12:15], v[214:217], v[24:27]
	v_mfma_f32_16x16x32_bf16 v[24:27], v[16:19], v[210:213], v[142:145]
	v_mfma_f32_16x16x32_bf16 v[40:43], v[20:23], v[214:217], v[24:27]
	v_mfma_f32_16x16x32_bf16 v[24:27], v[8:11], v[226:229], v[146:149]
	v_mfma_f32_16x16x32_bf16 v[0:3], v[8:11], v[234:237], v[0:3]
	v_mfma_f32_16x16x32_bf16 v[24:27], v[12:15], v[230:233], v[24:27]
	v_mfma_f32_16x16x32_bf16 v[28:31], v[16:19], v[226:229], v[150:153]
	v_mfma_f32_16x16x32_bf16 v[12:15], v[12:15], v[238:241], v[0:3]
	v_mfma_f32_16x16x32_bf16 v[0:3], v[16:19], v[234:237], v[4:7]
	v_mfma_f32_16x16x32_bf16 v[28:31], v[20:23], v[230:233], v[28:31]
	v_mfma_f32_16x16x32_bf16 v[8:11], v[20:23], v[238:241], v[0:3]
	v_mfma_f32_16x16x32_bf16 v[0:3], v[164:167], v[32:35], v[112:115]
	v_mfma_f32_16x16x32_bf16 v[52:55], v[188:191], v[36:39], v[0:3]
	v_mfma_f32_16x16x32_bf16 v[0:3], v[192:195], v[32:35], v[116:119]
	v_mfma_f32_16x16x32_bf16 v[48:51], v[222:225], v[36:39], v[0:3]
	v_mfma_f32_16x16x32_bf16 v[0:3], v[164:167], v[210:213], v[218:221]
	v_mfma_f32_16x16x32_bf16 v[36:39], v[188:191], v[214:217], v[0:3]
	v_mfma_f32_16x16x32_bf16 v[0:3], v[192:195], v[210:213], v[168:171]
	v_mfma_f32_16x16x32_bf16 v[32:35], v[222:225], v[214:217], v[0:3]
	v_mfma_f32_16x16x32_bf16 v[0:3], v[164:167], v[226:229], v[176:179]
	v_mfma_f32_16x16x32_bf16 v[20:23], v[188:191], v[230:233], v[0:3]
	v_mfma_f32_16x16x32_bf16 v[0:3], v[192:195], v[226:229], v[180:183]
	v_mfma_f32_16x16x32_bf16 v[16:19], v[222:225], v[230:233], v[0:3]
	v_mfma_f32_16x16x32_bf16 v[0:3], v[164:167], v[234:237], v[184:187]
	v_mfma_f32_16x16x32_bf16 v[4:7], v[188:191], v[238:241], v[0:3]
	v_mfma_f32_16x16x32_bf16 v[0:3], v[192:195], v[234:237], v[154:157]
	v_mfma_f32_16x16x32_bf16 v[0:3], v[222:225], v[238:241], v[0:3]
	s_barrier
	s_andn2_b64 vcc, exec, s[48:49]
	s_cbranch_vccnz .LBB0_419
	s_barrier

.LBB0_457:
	s_lshl_b64 s[10:11], s[52:53], 17
	s_add_u32 s56, s12, s10
	s_addc_u32 s57, s13, s11
	s_and_b64 s[10:11], s[40:41], exec
	s_cselect_b32 s11, s57, s9
	s_cselect_b32 s10, s56, s8
	s_add_i32 s55, 0, 0x10000
	s_add_i32 s38, 0, 0x14000
	v_add_u32_e32 v212, s55, v138
	v_add_u32_e32 v213, s38, v138
	ds_read_b128 v[0:3], v212
	ds_read_b128 v[4:7], v212 offset:1024
	ds_read_b128 v[8:11], v212 offset:2048
	ds_read_b128 v[12:15], v212 offset:3072
	ds_read_b128 v[16:19], v213
	ds_read_b128 v[20:23], v213 offset:1024
	ds_read_b128 v[24:27], v213 offset:2048
	ds_read_b128 v[28:31], v213 offset:3072
	s_add_u32 s74, s6, 0x40080
	s_addc_u32 s75, s7, 0
	s_add_i32 s61, s26, 0xc000
	v_lshl_add_u64 v[64:65], s[74:75], 0, v[132:133]
	s_mov_b32 m0, s61
	s_add_i32 s24, s26, 0xe000
	ds_read_b128 v[32:35], v139
	ds_read_b128 v[36:39], v139 offset:1024
	ds_read_b128 v[40:43], v139 offset:2048
	ds_read_b128 v[44:47], v139 offset:3072
	ds_read_b128 v[48:51], v139 offset:4096
	ds_read_b128 v[52:55], v139 offset:5120
	ds_read_b128 v[56:59], v139 offset:6144
	ds_read_b128 v[60:63], v139 offset:7168
	global_load_lds_dwordx4 v[64:65], off
	v_lshl_add_u64 v[64:65], s[74:75], 0, v[130:131]
	s_mov_b32 m0, s24
	s_nop 0
	global_load_lds_dwordx4 v[64:65], off
	s_waitcnt vmcnt(8)
	s_waitcnt lgkmcnt(0)
	s_barrier
	v_mfma_f32_16x16x32_bf16 v[64:67], v[0:3], v[32:35], 0
	v_mfma_f32_16x16x32_bf16 v[68:71], v[8:11], v[32:35], 0
	v_mfma_f32_16x16x32_bf16 v[72:75], v[0:3], v[40:43], 0
	v_mfma_f32_16x16x32_bf16 v[76:79], v[8:11], v[40:43], 0
	v_mfma_f32_16x16x32_bf16 v[80:83], v[0:3], v[48:51], 0
	v_mfma_f32_16x16x32_bf16 v[84:87], v[8:11], v[48:51], 0
	v_mfma_f32_16x16x32_bf16 v[88:91], v[0:3], v[56:59], 0
	v_mfma_f32_16x16x32_bf16 v[92:95], v[8:11], v[56:59], 0
	v_mfma_f32_16x16x32_bf16 v[64:67], v[4:7], v[36:39], v[64:67]
	v_mfma_f32_16x16x32_bf16 v[68:71], v[12:15], v[36:39], v[68:71]
	v_mfma_f32_16x16x32_bf16 v[72:75], v[4:7], v[44:47], v[72:75]
	v_mfma_f32_16x16x32_bf16 v[76:79], v[12:15], v[44:47], v[76:79]
	v_mfma_f32_16x16x32_bf16 v[80:83], v[4:7], v[52:55], v[80:83]
	v_mfma_f32_16x16x32_bf16 v[84:87], v[12:15], v[52:55], v[84:87]
	v_mfma_f32_16x16x32_bf16 v[88:91], v[4:7], v[60:63], v[88:91]
	v_mfma_f32_16x16x32_bf16 v[92:95], v[12:15], v[60:63], v[92:95]
	v_mfma_f32_16x16x32_bf16 v[96:99], v[16:19], v[32:35], 0
	v_mfma_f32_16x16x32_bf16 v[32:35], v[24:27], v[32:35], 0
	v_mfma_f32_16x16x32_bf16 v[96:99], v[20:23], v[36:39], v[96:99]
	v_mfma_f32_16x16x32_bf16 v[32:35], v[28:31], v[36:39], v[32:35]
	v_mfma_f32_16x16x32_bf16 v[36:39], v[16:19], v[40:43], 0
	v_mfma_f32_16x16x32_bf16 v[40:43], v[24:27], v[40:43], 0
	v_mfma_f32_16x16x32_bf16 v[36:39], v[20:23], v[44:47], v[36:39]
	v_mfma_f32_16x16x32_bf16 v[40:43], v[28:31], v[44:47], v[40:43]
	v_mfma_f32_16x16x32_bf16 v[44:47], v[16:19], v[48:51], 0
	v_mfma_f32_16x16x32_bf16 v[48:51], v[24:27], v[48:51], 0
	v_mfma_f32_16x16x32_bf16 v[44:47], v[20:23], v[52:55], v[44:47]
	v_mfma_f32_16x16x32_bf16 v[48:51], v[28:31], v[52:55], v[48:51]
	v_mfma_f32_16x16x32_bf16 v[52:55], v[16:19], v[56:59], 0
	v_mfma_f32_16x16x32_bf16 v[56:59], v[24:27], v[56:59], 0
	v_mfma_f32_16x16x32_bf16 v[52:55], v[20:23], v[60:63], v[52:55]
	v_mfma_f32_16x16x32_bf16 v[56:59], v[28:31], v[60:63], v[56:59]
	s_barrier
	s_add_i32 s55, s55, s15
	v_lshl_add_u64 v[198:199], s[8:9], 0, v[140:141]
	s_mov_b64 s[2:3], 0x100
	s_add_i32 s35, s55, 0x2000
	v_lshl_add_u64 v[134:135], v[198:199], 0, s[2:3]
	s_mov_b32 m0, s55
	v_lshl_add_u64 v[204:205], s[8:9], 0, v[128:129]
	s_add_u32 s74, s8, 0x10100
	ds_read_b128 v[60:63], v139 offset:16384
	ds_read_b128 v[100:103], v139 offset:17408
	ds_read_b128 v[104:107], v139 offset:18432
	ds_read_b128 v[108:111], v139 offset:19456
	ds_read_b128 v[112:115], v139 offset:20480
	ds_read_b128 v[116:119], v139 offset:21504
	ds_read_b128 v[120:123], v139 offset:22528
	ds_read_b128 v[124:127], v139 offset:23552
	global_load_lds_dwordx4 v[134:135], off
	v_lshl_add_u64 v[134:135], v[204:205], 0, s[2:3]
	s_mov_b32 m0, s35
	s_addc_u32 s75, s9, 0
	s_add_i32 s38, s38, s15
	global_load_lds_dwordx4 v[134:135], off
	v_lshl_add_u64 v[134:135], s[74:75], 0, v[140:141]
	s_mov_b32 m0, s38
	s_add_i32 s53, s38, 0x2000
	global_load_lds_dwordx4 v[134:135], off
	v_lshl_add_u64 v[134:135], s[74:75], 0, v[128:129]
	s_mov_b32 m0, s53
	v_lshl_add_u64 v[206:207], s[6:7], 0, v[132:133]
	global_load_lds_dwordx4 v[134:135], off
	v_lshl_add_u64 v[134:135], v[206:207], 0, s[2:3]
	s_mov_b32 m0, s26
	v_lshl_add_u64 v[208:209], s[6:7], 0, v[130:131]
	global_load_lds_dwordx4 v[134:135], off
	v_lshl_add_u64 v[134:135], v[208:209], 0, s[2:3]
	s_mov_b32 m0, s27
	s_nop 0
	global_load_lds_dwordx4 v[134:135], off
	s_waitcnt vmcnt(8)
	s_waitcnt lgkmcnt(0)
	s_barrier
	v_mfma_f32_16x16x32_bf16 v[134:137], v[0:3], v[60:63], 0
	v_mfma_f32_16x16x32_bf16 v[146:149], v[0:3], v[104:107], 0
	v_mfma_f32_16x16x32_bf16 v[154:157], v[0:3], v[112:115], 0
	v_mfma_f32_16x16x32_bf16 v[0:3], v[0:3], v[120:123], 0
	v_mfma_f32_16x16x32_bf16 v[134:137], v[4:7], v[100:103], v[134:137]
	v_mfma_f32_16x16x32_bf16 v[146:149], v[4:7], v[108:111], v[146:149]
	v_mfma_f32_16x16x32_bf16 v[154:157], v[4:7], v[116:119], v[154:157]
	v_mfma_f32_16x16x32_bf16 v[0:3], v[4:7], v[124:127], v[0:3]
	v_mfma_f32_16x16x32_bf16 v[4:7], v[8:11], v[120:123], 0
	v_mfma_f32_16x16x32_bf16 v[142:145], v[8:11], v[60:63], 0
	v_mfma_f32_16x16x32_bf16 v[150:153], v[8:11], v[104:107], 0
	v_mfma_f32_16x16x32_bf16 v[158:161], v[8:11], v[112:115], 0
	v_mfma_f32_16x16x32_bf16 v[4:7], v[12:15], v[124:127], v[4:7]
	v_mfma_f32_16x16x32_bf16 v[142:145], v[12:15], v[100:103], v[142:145]
	v_mfma_f32_16x16x32_bf16 v[150:153], v[12:15], v[108:111], v[150:153]
	v_mfma_f32_16x16x32_bf16 v[158:161], v[12:15], v[116:119], v[158:161]
	v_mfma_f32_16x16x32_bf16 v[8:11], v[16:19], v[60:63], 0
	v_mfma_f32_16x16x32_bf16 v[12:15], v[24:27], v[60:63], 0
	v_mfma_f32_16x16x32_bf16 v[8:11], v[20:23], v[100:103], v[8:11]
	v_mfma_f32_16x16x32_bf16 v[12:15], v[28:31], v[100:103], v[12:15]
	v_mfma_f32_16x16x32_bf16 v[60:63], v[16:19], v[104:107], 0
	v_mfma_f32_16x16x32_bf16 v[100:103], v[24:27], v[104:107], 0
	v_mfma_f32_16x16x32_bf16 v[104:107], v[16:19], v[112:115], 0
	v_mfma_f32_16x16x32_bf16 v[16:19], v[16:19], v[120:123], 0
	v_mfma_f32_16x16x32_bf16 v[60:63], v[20:23], v[108:111], v[60:63]
	v_mfma_f32_16x16x32_bf16 v[100:103], v[28:31], v[108:111], v[100:103]
	v_mfma_f32_16x16x32_bf16 v[104:107], v[20:23], v[116:119], v[104:107]
	v_mfma_f32_16x16x32_bf16 v[108:111], v[24:27], v[112:115], 0
	v_mfma_f32_16x16x32_bf16 v[16:19], v[20:23], v[124:127], v[16:19]
	v_mfma_f32_16x16x32_bf16 v[20:23], v[24:27], v[120:123], 0
	v_mfma_f32_16x16x32_bf16 v[108:111], v[28:31], v[116:119], v[108:111]
	v_mfma_f32_16x16x32_bf16 v[20:23], v[28:31], v[124:127], v[20:23]
	s_barrier
	s_add_i32 s60, 0, 0x18000
	s_add_i32 s76, 0, 0x1c000
	v_add_u32_e32 v218, s60, v138
	v_add_u32_e32 v219, s76, v138
	ds_read_b128 v[24:27], v218
	ds_read_b128 v[28:31], v218 offset:1024
	ds_read_b128 v[112:115], v218 offset:2048
	ds_read_b128 v[116:119], v218 offset:3072
	ds_read_b128 v[120:123], v219
	ds_read_b128 v[124:127], v219 offset:1024
	ds_read_b128 v[162:165], v219 offset:2048
	ds_read_b128 v[166:169], v219 offset:3072
	s_add_u32 s74, s6, 0x40100
	s_addc_u32 s75, s7, 0
	s_mov_b32 m0, s28
	v_lshl_add_u64 v[210:211], s[74:75], 0, v[132:133]
	ds_read_b128 v[170:173], v139 offset:32768
	ds_read_b128 v[174:177], v139 offset:33792
	ds_read_b128 v[178:181], v139 offset:34816
	ds_read_b128 v[182:185], v139 offset:35840
	ds_read_b128 v[186:189], v139 offset:36864
	ds_read_b128 v[190:193], v139 offset:37888
	ds_read_b128 v[194:197], v139 offset:38912
	ds_read_b128 v[200:203], v139 offset:39936
	global_load_lds_dwordx4 v[210:211], off
	v_lshl_add_u64 v[210:211], s[74:75], 0, v[130:131]
	s_mov_b32 m0, s29
	s_nop 0
	global_load_lds_dwordx4 v[210:211], off
	s_waitcnt vmcnt(8)
	s_waitcnt lgkmcnt(0)
	s_barrier
	v_mfma_f32_16x16x32_bf16 v[64:67], v[24:27], v[170:173], v[64:67]
	v_mfma_f32_16x16x32_bf16 v[68:71], v[112:115], v[170:173], v[68:71]
	v_mfma_f32_16x16x32_bf16 v[72:75], v[24:27], v[178:181], v[72:75]
	v_mfma_f32_16x16x32_bf16 v[76:79], v[112:115], v[178:181], v[76:79]
	v_mfma_f32_16x16x32_bf16 v[80:83], v[24:27], v[186:189], v[80:83]
	v_mfma_f32_16x16x32_bf16 v[84:87], v[112:115], v[186:189], v[84:87]
	v_mfma_f32_16x16x32_bf16 v[88:91], v[24:27], v[194:197], v[88:91]
	v_mfma_f32_16x16x32_bf16 v[92:95], v[112:115], v[194:197], v[92:95]
	v_mfma_f32_16x16x32_bf16 v[64:67], v[28:31], v[174:177], v[64:67]
	v_mfma_f32_16x16x32_bf16 v[68:71], v[116:119], v[174:177], v[68:71]
	v_mfma_f32_16x16x32_bf16 v[72:75], v[28:31], v[182:185], v[72:75]
	v_mfma_f32_16x16x32_bf16 v[76:79], v[116:119], v[182:185], v[76:79]
	v_mfma_f32_16x16x32_bf16 v[80:83], v[28:31], v[190:193], v[80:83]
	v_mfma_f32_16x16x32_bf16 v[84:87], v[116:119], v[190:193], v[84:87]
	v_mfma_f32_16x16x32_bf16 v[88:91], v[28:31], v[200:203], v[88:91]
	v_mfma_f32_16x16x32_bf16 v[92:95], v[116:119], v[200:203], v[92:95]
	v_mfma_f32_16x16x32_bf16 v[96:99], v[120:123], v[170:173], v[96:99]
	v_mfma_f32_16x16x32_bf16 v[32:35], v[162:165], v[170:173], v[32:35]
	v_mfma_f32_16x16x32_bf16 v[36:39], v[120:123], v[178:181], v[36:39]
	v_mfma_f32_16x16x32_bf16 v[40:43], v[162:165], v[178:181], v[40:43]
	v_mfma_f32_16x16x32_bf16 v[44:47], v[120:123], v[186:189], v[44:47]
	v_mfma_f32_16x16x32_bf16 v[48:51], v[162:165], v[186:189], v[48:51]
	v_mfma_f32_16x16x32_bf16 v[52:55], v[120:123], v[194:197], v[52:55]
	v_mfma_f32_16x16x32_bf16 v[56:59], v[162:165], v[194:197], v[56:59]
	v_mfma_f32_16x16x32_bf16 v[96:99], v[124:127], v[174:177], v[96:99]
	v_mfma_f32_16x16x32_bf16 v[32:35], v[166:169], v[174:177], v[32:35]
	v_mfma_f32_16x16x32_bf16 v[36:39], v[124:127], v[182:185], v[36:39]
	v_mfma_f32_16x16x32_bf16 v[40:43], v[166:169], v[182:185], v[40:43]
	v_mfma_f32_16x16x32_bf16 v[44:47], v[124:127], v[190:193], v[44:47]
	v_mfma_f32_16x16x32_bf16 v[48:51], v[166:169], v[190:193], v[48:51]
	v_mfma_f32_16x16x32_bf16 v[52:55], v[124:127], v[200:203], v[52:55]
	v_mfma_f32_16x16x32_bf16 v[56:59], v[166:169], v[200:203], v[56:59]
	s_barrier
	s_add_i32 s74, s60, s15
	s_mov_b64 s[2:3], 0x180
	s_add_i32 s60, s74, 0x2000
	v_lshl_add_u64 v[198:199], v[198:199], 0, s[2:3]
	s_mov_b32 m0, s74
	s_add_u32 s84, s8, 0x10180
	ds_read_b128 v[170:173], v139 offset:49152
	ds_read_b128 v[174:177], v139 offset:50176
	ds_read_b128 v[178:181], v139 offset:51200
	ds_read_b128 v[182:185], v139 offset:52224
	ds_read_b128 v[186:189], v139 offset:53248
	ds_read_b128 v[190:193], v139 offset:54272
	ds_read_b128 v[194:197], v139 offset:55296
	ds_read_b128 v[200:203], v139 offset:56320
	global_load_lds_dwordx4 v[198:199], off
	v_lshl_add_u64 v[198:199], v[204:205], 0, s[2:3]
	s_mov_b32 m0, s60
	s_addc_u32 s85, s9, 0
	s_add_i32 s8, s76, s15
	global_load_lds_dwordx4 v[198:199], off
	v_lshl_add_u64 v[198:199], s[84:85], 0, v[140:141]
	s_mov_b32 m0, s8
	s_add_i32 s9, s8, 0x2000
	global_load_lds_dwordx4 v[198:199], off
	v_lshl_add_u64 v[198:199], s[84:85], 0, v[128:129]
	s_mov_b32 m0, s9
	s_nop 0
	global_load_lds_dwordx4 v[198:199], off
	v_lshl_add_u64 v[198:199], v[206:207], 0, s[2:3]
	s_mov_b32 m0, s58
	s_nop 0
	global_load_lds_dwordx4 v[198:199], off
	v_lshl_add_u64 v[198:199], v[208:209], 0, s[2:3]
	s_mov_b32 m0, s59
	s_nop 0
	global_load_lds_dwordx4 v[198:199], off
	s_waitcnt vmcnt(8)
	s_waitcnt lgkmcnt(0)
	s_barrier
	v_mfma_f32_16x16x32_bf16 v[0:3], v[24:27], v[194:197], v[0:3]
	v_mfma_f32_16x16x32_bf16 v[4:7], v[112:115], v[194:197], v[4:7]
	v_mfma_f32_16x16x32_bf16 v[134:137], v[24:27], v[170:173], v[134:137]
	v_mfma_f32_16x16x32_bf16 v[142:145], v[112:115], v[170:173], v[142:145]
	v_mfma_f32_16x16x32_bf16 v[146:149], v[24:27], v[178:181], v[146:149]
	v_mfma_f32_16x16x32_bf16 v[150:153], v[112:115], v[178:181], v[150:153]
	v_mfma_f32_16x16x32_bf16 v[154:157], v[24:27], v[186:189], v[154:157]
	v_mfma_f32_16x16x32_bf16 v[158:161], v[112:115], v[186:189], v[158:161]
	v_mfma_f32_16x16x32_bf16 v[0:3], v[28:31], v[200:203], v[0:3]
	v_mfma_f32_16x16x32_bf16 v[4:7], v[116:119], v[200:203], v[4:7]
	v_mfma_f32_16x16x32_bf16 v[134:137], v[28:31], v[174:177], v[134:137]
	v_mfma_f32_16x16x32_bf16 v[142:145], v[116:119], v[174:177], v[142:145]
	v_mfma_f32_16x16x32_bf16 v[146:149], v[28:31], v[182:185], v[146:149]
	v_mfma_f32_16x16x32_bf16 v[150:153], v[116:119], v[182:185], v[150:153]
	v_mfma_f32_16x16x32_bf16 v[154:157], v[28:31], v[190:193], v[154:157]
	v_mfma_f32_16x16x32_bf16 v[158:161], v[116:119], v[190:193], v[158:161]
	v_mfma_f32_16x16x32_bf16 v[8:11], v[120:123], v[170:173], v[8:11]
	v_mfma_f32_16x16x32_bf16 v[12:15], v[162:165], v[170:173], v[12:15]
	v_mfma_f32_16x16x32_bf16 v[24:27], v[120:123], v[178:181], v[60:63]
	v_mfma_f32_16x16x32_bf16 v[28:31], v[162:165], v[178:181], v[100:103]
	v_mfma_f32_16x16x32_bf16 v[60:63], v[120:123], v[186:189], v[104:107]
	v_mfma_f32_16x16x32_bf16 v[100:103], v[162:165], v[186:189], v[108:111]
	v_mfma_f32_16x16x32_bf16 v[16:19], v[120:123], v[194:197], v[16:19]
	v_mfma_f32_16x16x32_bf16 v[20:23], v[162:165], v[194:197], v[20:23]
	v_mfma_f32_16x16x32_bf16 v[8:11], v[124:127], v[174:177], v[8:11]
	v_mfma_f32_16x16x32_bf16 v[12:15], v[166:169], v[174:177], v[12:15]
	v_mfma_f32_16x16x32_bf16 v[24:27], v[124:127], v[182:185], v[24:27]
	v_mfma_f32_16x16x32_bf16 v[28:31], v[166:169], v[182:185], v[28:31]
	v_mfma_f32_16x16x32_bf16 v[60:63], v[124:127], v[190:193], v[60:63]
	v_mfma_f32_16x16x32_bf16 v[100:103], v[166:169], v[190:193], v[100:103]
	v_mfma_f32_16x16x32_bf16 v[16:19], v[124:127], v[200:203], v[16:19]
	v_mfma_f32_16x16x32_bf16 v[20:23], v[166:169], v[200:203], v[20:23]
	s_barrier
	ds_read_b128 v[104:107], v212
	ds_read_b128 v[108:111], v212 offset:1024
	ds_read_b128 v[112:115], v212 offset:2048
	ds_read_b128 v[116:119], v212 offset:3072
	ds_read_b128 v[120:123], v213
	ds_read_b128 v[124:127], v213 offset:1024
	ds_read_b128 v[162:165], v213 offset:2048
	ds_read_b128 v[166:169], v213 offset:3072
	s_add_u32 s6, s6, 0x40180
	s_addc_u32 s7, s7, 0
	s_mov_b32 m0, s61
	v_lshl_add_u64 v[198:199], s[6:7], 0, v[132:133]
	ds_read_b128 v[170:173], v139
	ds_read_b128 v[174:177], v139 offset:1024
	ds_read_b128 v[178:181], v139 offset:2048
	ds_read_b128 v[182:185], v139 offset:3072
	ds_read_b128 v[186:189], v139 offset:4096
	ds_read_b128 v[190:193], v139 offset:5120
	ds_read_b128 v[194:197], v139 offset:6144
	ds_read_b128 v[200:203], v139 offset:7168
	global_load_lds_dwordx4 v[198:199], off
	v_lshl_add_u64 v[198:199], s[6:7], 0, v[130:131]
	s_mov_b32 m0, s24
	s_nop 0
	global_load_lds_dwordx4 v[198:199], off
	s_waitcnt vmcnt(8)
	s_waitcnt lgkmcnt(0)
	s_barrier
	v_mfma_f32_16x16x32_bf16 v[64:67], v[104:107], v[170:173], v[64:67]
	v_mfma_f32_16x16x32_bf16 v[68:71], v[112:115], v[170:173], v[68:71]
	v_mfma_f32_16x16x32_bf16 v[72:75], v[104:107], v[178:181], v[72:75]
	v_mfma_f32_16x16x32_bf16 v[76:79], v[112:115], v[178:181], v[76:79]
	v_mfma_f32_16x16x32_bf16 v[80:83], v[104:107], v[186:189], v[80:83]
	v_mfma_f32_16x16x32_bf16 v[84:87], v[112:115], v[186:189], v[84:87]
	v_mfma_f32_16x16x32_bf16 v[88:91], v[104:107], v[194:197], v[88:91]
	v_mfma_f32_16x16x32_bf16 v[64:67], v[108:111], v[174:177], v[64:67]
	v_mfma_f32_16x16x32_bf16 v[68:71], v[116:119], v[174:177], v[68:71]
	v_mfma_f32_16x16x32_bf16 v[72:75], v[108:111], v[182:185], v[72:75]
	v_mfma_f32_16x16x32_bf16 v[76:79], v[116:119], v[182:185], v[76:79]
	v_mfma_f32_16x16x32_bf16 v[80:83], v[108:111], v[190:193], v[80:83]
	v_mfma_f32_16x16x32_bf16 v[84:87], v[116:119], v[190:193], v[84:87]
	v_mfma_f32_16x16x32_bf16 v[206:209], v[108:111], v[200:203], v[88:91]
	v_mfma_f32_16x16x32_bf16 v[88:91], v[112:115], v[194:197], v[92:95]
	v_mfma_f32_16x16x32_bf16 v[210:213], v[116:119], v[200:203], v[88:91]
	v_mfma_f32_16x16x32_bf16 v[88:91], v[120:123], v[170:173], v[96:99]
	v_mfma_f32_16x16x32_bf16 v[32:35], v[162:165], v[170:173], v[32:35]
	v_mfma_f32_16x16x32_bf16 v[36:39], v[120:123], v[178:181], v[36:39]
	v_mfma_f32_16x16x32_bf16 v[40:43], v[162:165], v[178:181], v[40:43]
	v_mfma_f32_16x16x32_bf16 v[44:47], v[120:123], v[186:189], v[44:47]
	v_mfma_f32_16x16x32_bf16 v[48:51], v[162:165], v[186:189], v[48:51]
	v_mfma_f32_16x16x32_bf16 v[52:55], v[120:123], v[194:197], v[52:55]
	v_mfma_f32_16x16x32_bf16 v[56:59], v[162:165], v[194:197], v[56:59]
	v_mfma_f32_16x16x32_bf16 v[96:99], v[124:127], v[174:177], v[88:91]
	v_mfma_f32_16x16x32_bf16 v[32:35], v[166:169], v[174:177], v[32:35]
	v_mfma_f32_16x16x32_bf16 v[36:39], v[124:127], v[182:185], v[36:39]
	v_mfma_f32_16x16x32_bf16 v[40:43], v[166:169], v[182:185], v[40:43]
	v_mfma_f32_16x16x32_bf16 v[44:47], v[124:127], v[190:193], v[44:47]
	v_mfma_f32_16x16x32_bf16 v[48:51], v[166:169], v[190:193], v[48:51]
	v_mfma_f32_16x16x32_bf16 v[52:55], v[124:127], v[200:203], v[52:55]
	v_mfma_f32_16x16x32_bf16 v[56:59], v[166:169], v[200:203], v[56:59]
	s_barrier
	s_mov_b32 m0, s55
	v_lshl_add_u64 v[198:199], s[10:11], 0, v[140:141]
	s_add_u32 s6, s10, 0x10000
	ds_read_b128 v[88:91], v139 offset:16384
	ds_read_b128 v[92:95], v139 offset:17408
	ds_read_b128 v[170:173], v139 offset:18432
	ds_read_b128 v[174:177], v139 offset:19456
	ds_read_b128 v[178:181], v139 offset:20480
	ds_read_b128 v[182:185], v139 offset:21504
	ds_read_b128 v[186:189], v139 offset:22528
	ds_read_b128 v[190:193], v139 offset:23552
	global_load_lds_dwordx4 v[198:199], off
	v_lshl_add_u64 v[204:205], s[10:11], 0, v[128:129]
	s_mov_b32 m0, s35
	s_addc_u32 s7, s11, 0
	global_load_lds_dwordx4 v[204:205], off
	v_lshl_add_u64 v[194:195], s[6:7], 0, v[140:141]
	s_mov_b32 m0, s38
	v_lshl_add_u64 v[242:243], s[42:43], 0, v[132:133]
	global_load_lds_dwordx4 v[194:195], off
	v_lshl_add_u64 v[194:195], s[6:7], 0, v[128:129]
	s_mov_b32 m0, s53
	v_lshl_add_u64 v[244:245], s[42:43], 0, v[130:131]
	global_load_lds_dwordx4 v[194:195], off
	s_mov_b32 m0, s26
	s_nop 0
	global_load_lds_dwordx4 v[242:243], off
	s_mov_b32 m0, s27
	s_nop 0
	global_load_lds_dwordx4 v[244:245], off
	s_waitcnt vmcnt(8)
	s_waitcnt lgkmcnt(0)
	s_barrier
	v_mfma_f32_16x16x32_bf16 v[0:3], v[104:107], v[186:189], v[0:3]
	v_mfma_f32_16x16x32_bf16 v[4:7], v[112:115], v[186:189], v[4:7]
	v_mfma_f32_16x16x32_bf16 v[134:137], v[104:107], v[88:91], v[134:137]
	v_mfma_f32_16x16x32_bf16 v[142:145], v[112:115], v[88:91], v[142:145]
	v_mfma_f32_16x16x32_bf16 v[146:149], v[104:107], v[170:173], v[146:149]
	v_mfma_f32_16x16x32_bf16 v[150:153], v[112:115], v[170:173], v[150:153]
	v_mfma_f32_16x16x32_bf16 v[154:157], v[104:107], v[178:181], v[154:157]
	v_mfma_f32_16x16x32_bf16 v[158:161], v[112:115], v[178:181], v[158:161]
	v_mfma_f32_16x16x32_bf16 v[0:3], v[108:111], v[190:193], v[0:3]
	v_mfma_f32_16x16x32_bf16 v[4:7], v[116:119], v[190:193], v[4:7]
	v_mfma_f32_16x16x32_bf16 v[134:137], v[108:111], v[92:95], v[134:137]
	v_mfma_f32_16x16x32_bf16 v[142:145], v[116:119], v[92:95], v[142:145]
	v_mfma_f32_16x16x32_bf16 v[146:149], v[108:111], v[174:177], v[146:149]
	v_mfma_f32_16x16x32_bf16 v[150:153], v[116:119], v[174:177], v[150:153]
	v_mfma_f32_16x16x32_bf16 v[154:157], v[108:111], v[182:185], v[154:157]
	v_mfma_f32_16x16x32_bf16 v[158:161], v[116:119], v[182:185], v[158:161]
	v_mfma_f32_16x16x32_bf16 v[8:11], v[120:123], v[88:91], v[8:11]
	v_mfma_f32_16x16x32_bf16 v[194:197], v[124:127], v[92:95], v[8:11]
	v_mfma_f32_16x16x32_bf16 v[8:11], v[162:165], v[88:91], v[12:15]
	v_mfma_f32_16x16x32_bf16 v[200:203], v[166:169], v[92:95], v[8:11]
	v_mfma_f32_16x16x32_bf16 v[8:11], v[120:123], v[170:173], v[24:27]
	v_mfma_f32_16x16x32_bf16 v[214:217], v[124:127], v[174:177], v[8:11]
	v_mfma_f32_16x16x32_bf16 v[8:11], v[162:165], v[170:173], v[28:31]
	v_mfma_f32_16x16x32_bf16 v[170:173], v[166:169], v[174:177], v[8:11]
	v_mfma_f32_16x16x32_bf16 v[8:11], v[120:123], v[178:181], v[60:63]
	v_mfma_f32_16x16x32_bf16 v[174:177], v[124:127], v[182:185], v[8:11]
	v_mfma_f32_16x16x32_bf16 v[8:11], v[162:165], v[178:181], v[100:103]
	v_mfma_f32_16x16x32_bf16 v[178:181], v[166:169], v[182:185], v[8:11]
	v_mfma_f32_16x16x32_bf16 v[8:11], v[120:123], v[186:189], v[16:19]
	v_mfma_f32_16x16x32_bf16 v[182:185], v[124:127], v[190:193], v[8:11]
	v_mfma_f32_16x16x32_bf16 v[8:11], v[162:165], v[186:189], v[20:23]
	v_mfma_f32_16x16x32_bf16 v[162:165], v[166:169], v[190:193], v[8:11]
	s_barrier
	s_nop 4
	ds_read_b128 v[8:11], v218
	ds_read_b128 v[12:15], v218 offset:1024
	ds_read_b128 v[16:19], v218 offset:2048
	ds_read_b128 v[20:23], v218 offset:3072
	ds_read_b128 v[166:169], v219
	ds_read_b128 v[186:189], v219 offset:1024
	ds_read_b128 v[190:193], v219 offset:2048
	ds_read_b128 v[218:221], v219 offset:3072
	s_add_u32 s6, s42, 0x40000
	s_addc_u32 s7, s43, 0
	s_mov_b32 m0, s28
	v_lshl_add_u64 v[88:89], s[6:7], 0, v[132:133]
	ds_read_b128 v[24:27], v139 offset:32768
	ds_read_b128 v[28:31], v139 offset:33792
	ds_read_b128 v[60:63], v139 offset:34816
	ds_read_b128 v[222:225], v139 offset:35840
	ds_read_b128 v[226:229], v139 offset:36864
	ds_read_b128 v[230:233], v139 offset:37888
	ds_read_b128 v[234:237], v139 offset:38912
	ds_read_b128 v[238:241], v139 offset:39936
	global_load_lds_dwordx4 v[88:89], off
	v_lshl_add_u64 v[88:89], s[6:7], 0, v[130:131]
	s_mov_b32 m0, s29
	s_nop 0
	global_load_lds_dwordx4 v[88:89], off
	s_waitcnt vmcnt(8)
	s_waitcnt lgkmcnt(0)
	s_barrier
	v_mfma_f32_16x16x32_bf16 v[64:67], v[8:11], v[24:27], v[64:67]
	v_mfma_f32_16x16x32_bf16 v[120:123], v[12:15], v[28:31], v[64:67]
	v_mfma_f32_16x16x32_bf16 v[64:67], v[16:19], v[24:27], v[68:71]
	v_mfma_f32_16x16x32_bf16 v[124:127], v[20:23], v[28:31], v[64:67]
	v_mfma_f32_16x16x32_bf16 v[64:67], v[8:11], v[60:63], v[72:75]
	v_mfma_f32_16x16x32_bf16 v[104:107], v[12:15], v[222:225], v[64:67]
	v_mfma_f32_16x16x32_bf16 v[64:67], v[16:19], v[60:63], v[76:79]
	v_mfma_f32_16x16x32_bf16 v[108:111], v[20:23], v[222:225], v[64:67]
	v_mfma_f32_16x16x32_bf16 v[64:67], v[8:11], v[226:229], v[80:83]
	v_mfma_f32_16x16x32_bf16 v[88:91], v[12:15], v[230:233], v[64:67]
	v_mfma_f32_16x16x32_bf16 v[64:67], v[16:19], v[226:229], v[84:87]
	v_mfma_f32_16x16x32_bf16 v[92:95], v[20:23], v[230:233], v[64:67]
	v_mfma_f32_16x16x32_bf16 v[64:67], v[8:11], v[234:237], v[206:209]
	v_mfma_f32_16x16x32_bf16 v[72:75], v[12:15], v[238:241], v[64:67]
	v_mfma_f32_16x16x32_bf16 v[64:67], v[16:19], v[234:237], v[210:213]
	v_mfma_f32_16x16x32_bf16 v[76:79], v[20:23], v[238:241], v[64:67]
	v_mfma_f32_16x16x32_bf16 v[64:67], v[166:169], v[24:27], v[96:99]
	v_mfma_f32_16x16x32_bf16 v[24:27], v[190:193], v[24:27], v[32:35]
	v_mfma_f32_16x16x32_bf16 v[112:115], v[218:221], v[28:31], v[24:27]
	v_mfma_f32_16x16x32_bf16 v[24:27], v[166:169], v[60:63], v[36:39]
	v_mfma_f32_16x16x32_bf16 v[100:103], v[186:189], v[222:225], v[24:27]
	v_mfma_f32_16x16x32_bf16 v[24:27], v[190:193], v[60:63], v[40:43]
	v_mfma_f32_16x16x32_bf16 v[96:99], v[218:221], v[222:225], v[24:27]
	v_mfma_f32_16x16x32_bf16 v[24:27], v[166:169], v[226:229], v[44:47]
	v_mfma_f32_16x16x32_bf16 v[84:87], v[186:189], v[230:233], v[24:27]
	v_mfma_f32_16x16x32_bf16 v[24:27], v[190:193], v[226:229], v[48:51]
	v_mfma_f32_16x16x32_bf16 v[80:83], v[218:221], v[230:233], v[24:27]
	v_mfma_f32_16x16x32_bf16 v[24:27], v[166:169], v[234:237], v[52:55]
	v_mfma_f32_16x16x32_bf16 v[68:71], v[186:189], v[238:241], v[24:27]
	v_mfma_f32_16x16x32_bf16 v[24:27], v[190:193], v[234:237], v[56:59]
	v_mfma_f32_16x16x32_bf16 v[116:119], v[186:189], v[28:31], v[64:67]
	v_mfma_f32_16x16x32_bf16 v[64:67], v[218:221], v[238:241], v[24:27]
	s_barrier
	s_mov_b32 m0, s74
	s_nop 2
	v_lshl_add_u64 v[24:25], v[198:199], 0, s[36:37]
	s_add_u32 s6, s10, 0x10080
	ds_read_b128 v[32:35], v139 offset:49152
	ds_read_b128 v[36:39], v139 offset:50176
	ds_read_b128 v[206:209], v139 offset:51200
	ds_read_b128 v[210:213], v139 offset:52224
	ds_read_b128 v[222:225], v139 offset:53248
	ds_read_b128 v[226:229], v139 offset:54272
	ds_read_b128 v[230:233], v139 offset:55296
	ds_read_b128 v[234:237], v139 offset:56320
	global_load_lds_dwordx4 v[24:25], off
	v_lshl_add_u64 v[24:25], v[204:205], 0, s[36:37]
	s_mov_b32 m0, s60
	s_addc_u32 s7, s11, 0
	global_load_lds_dwordx4 v[24:25], off
	v_lshl_add_u64 v[24:25], s[6:7], 0, v[140:141]
	s_mov_b32 m0, s8
	s_nop 0
	global_load_lds_dwordx4 v[24:25], off
	v_lshl_add_u64 v[24:25], s[6:7], 0, v[128:129]
	s_mov_b32 m0, s9
	s_nop 0
	global_load_lds_dwordx4 v[24:25], off
	v_lshl_add_u64 v[24:25], v[242:243], 0, s[36:37]
	s_mov_b32 m0, s58
	s_nop 0
	global_load_lds_dwordx4 v[24:25], off
	v_lshl_add_u64 v[24:25], v[244:245], 0, s[36:37]
	s_mov_b32 m0, s59
	s_nop 0
	global_load_lds_dwordx4 v[24:25], off
	s_waitcnt vmcnt(8)
	s_waitcnt lgkmcnt(0)
	s_barrier
	v_mfma_f32_16x16x32_bf16 v[24:27], v[8:11], v[32:35], v[134:137]
	v_mfma_f32_16x16x32_bf16 v[56:59], v[12:15], v[36:39], v[24:27]
	v_mfma_f32_16x16x32_bf16 v[24:27], v[16:19], v[32:35], v[142:145]
	v_mfma_f32_16x16x32_bf16 v[60:63], v[20:23], v[36:39], v[24:27]
	v_mfma_f32_16x16x32_bf16 v[24:27], v[8:11], v[206:209], v[146:149]
	v_mfma_f32_16x16x32_bf16 v[40:43], v[12:15], v[210:213], v[24:27]
	v_mfma_f32_16x16x32_bf16 v[24:27], v[16:19], v[206:209], v[150:153]
	v_mfma_f32_16x16x32_bf16 v[0:3], v[8:11], v[230:233], v[0:3]
	v_mfma_f32_16x16x32_bf16 v[44:47], v[20:23], v[210:213], v[24:27]
	v_mfma_f32_16x16x32_bf16 v[24:27], v[8:11], v[222:225], v[154:157]
	v_mfma_f32_16x16x32_bf16 v[28:31], v[16:19], v[222:225], v[158:161]
	v_mfma_f32_16x16x32_bf16 v[8:11], v[12:15], v[234:237], v[0:3]
	v_mfma_f32_16x16x32_bf16 v[0:3], v[16:19], v[230:233], v[4:7]
	v_mfma_f32_16x16x32_bf16 v[24:27], v[12:15], v[226:229], v[24:27]
	v_mfma_f32_16x16x32_bf16 v[28:31], v[20:23], v[226:229], v[28:31]
	v_mfma_f32_16x16x32_bf16 v[12:15], v[20:23], v[234:237], v[0:3]
	v_mfma_f32_16x16x32_bf16 v[0:3], v[166:169], v[32:35], v[194:197]
	v_mfma_f32_16x16x32_bf16 v[52:55], v[186:189], v[36:39], v[0:3]
	v_mfma_f32_16x16x32_bf16 v[0:3], v[190:193], v[32:35], v[200:203]
	v_mfma_f32_16x16x32_bf16 v[48:51], v[218:221], v[36:39], v[0:3]
	v_mfma_f32_16x16x32_bf16 v[0:3], v[166:169], v[206:209], v[214:217]
	v_mfma_f32_16x16x32_bf16 v[36:39], v[186:189], v[210:213], v[0:3]
	v_mfma_f32_16x16x32_bf16 v[0:3], v[190:193], v[206:209], v[170:173]
	v_mfma_f32_16x16x32_bf16 v[32:35], v[218:221], v[210:213], v[0:3]
	v_mfma_f32_16x16x32_bf16 v[0:3], v[166:169], v[222:225], v[174:177]
	v_mfma_f32_16x16x32_bf16 v[20:23], v[186:189], v[226:229], v[0:3]
	v_mfma_f32_16x16x32_bf16 v[0:3], v[190:193], v[222:225], v[178:181]
	v_mfma_f32_16x16x32_bf16 v[16:19], v[218:221], v[226:229], v[0:3]
	v_mfma_f32_16x16x32_bf16 v[0:3], v[166:169], v[230:233], v[182:185]
	v_mfma_f32_16x16x32_bf16 v[4:7], v[186:189], v[234:237], v[0:3]
	v_mfma_f32_16x16x32_bf16 v[0:3], v[190:193], v[230:233], v[162:165]
	v_mfma_f32_16x16x32_bf16 v[0:3], v[218:221], v[234:237], v[0:3]
	s_barrier
	s_andn2_b64 vcc, exec, s[48:49]
	s_cbranch_vccnz .LBB0_459
	s_barrier

.LBB0_552:
	s_add_u32 s8, s6, 0xfffc0080
	s_addc_u32 s9, s7, -1
	s_add_i32 s35, 0, 0x10000
	s_cmp_eq_u32 s56, 12
	s_cselect_b32 s11, s4, s9
	s_cselect_b32 s10, s5, s8
	v_add_u32_e32 v140, s35, v165
	s_cselect_b32 s9, s24, s51
	s_cselect_b32 s8, s38, s47
	s_add_i32 s57, 0, 0x14000
	ds_read_b128 v[158:161], v140
	ds_read_b128 v[168:171], v140 offset:1024
	ds_read_b128 v[172:175], v140 offset:2048
	ds_read_b128 v[176:179], v140 offset:3072
	v_add_u32_e32 v140, s57, v165
	ds_read_b128 v[180:183], v140
	ds_read_b128 v[184:187], v140 offset:1024
	ds_read_b128 v[206:209], v140 offset:2048
	ds_read_b128 v[210:213], v140 offset:3072
	v_lshl_add_u64 v[142:143], s[6:7], 0, v[136:137]
	s_add_i32 m0, s66, 0xc000
	ds_read_b128 v[214:217], v166
	ds_read_b128 v[218:221], v166 offset:1024
	ds_read_b128 v[222:225], v166 offset:2048
	ds_read_b128 v[226:229], v166 offset:3072
	ds_read_b128 v[230:233], v166 offset:4096
	ds_read_b128 v[234:237], v166 offset:5120
	ds_read_b128 v[238:241], v166 offset:6144
	ds_read_b128 v[242:245], v166 offset:7168
	global_load_lds_dwordx4 v[142:143], off
	v_lshl_add_u64 v[142:143], s[6:7], 0, v[138:139]
	s_add_i32 m0, s66, 0xe000
	s_nop 0
	global_load_lds_dwordx4 v[142:143], off
	s_waitcnt vmcnt(8)
	s_waitcnt lgkmcnt(0)
	s_barrier
	v_mfma_f32_16x16x32_bf16 v[124:127], v[158:161], v[214:217], v[124:127]
	v_mfma_f32_16x16x32_bf16 v[120:123], v[172:175], v[214:217], v[120:123]
	v_mfma_f32_16x16x32_bf16 v[108:111], v[158:161], v[222:225], v[108:111]
	v_mfma_f32_16x16x32_bf16 v[104:107], v[172:175], v[222:225], v[104:107]
	v_mfma_f32_16x16x32_bf16 v[92:95], v[158:161], v[230:233], v[92:95]
	v_mfma_f32_16x16x32_bf16 v[88:91], v[172:175], v[230:233], v[88:91]
	v_mfma_f32_16x16x32_bf16 v[76:79], v[158:161], v[238:241], v[76:79]
	v_mfma_f32_16x16x32_bf16 v[72:75], v[172:175], v[238:241], v[72:75]
	v_mfma_f32_16x16x32_bf16 v[124:127], v[168:171], v[218:221], v[124:127]
	v_mfma_f32_16x16x32_bf16 v[120:123], v[176:179], v[218:221], v[120:123]
	v_mfma_f32_16x16x32_bf16 v[108:111], v[168:171], v[226:229], v[108:111]
	v_mfma_f32_16x16x32_bf16 v[104:107], v[176:179], v[226:229], v[104:107]
	v_mfma_f32_16x16x32_bf16 v[92:95], v[168:171], v[234:237], v[92:95]
	v_mfma_f32_16x16x32_bf16 v[88:91], v[176:179], v[234:237], v[88:91]
	v_mfma_f32_16x16x32_bf16 v[76:79], v[168:171], v[242:245], v[76:79]
	v_mfma_f32_16x16x32_bf16 v[72:75], v[176:179], v[242:245], v[72:75]
	v_mfma_f32_16x16x32_bf16 v[116:119], v[180:183], v[214:217], v[116:119]
	v_mfma_f32_16x16x32_bf16 v[112:115], v[206:209], v[214:217], v[112:115]
	v_mfma_f32_16x16x32_bf16 v[100:103], v[180:183], v[222:225], v[100:103]
	v_mfma_f32_16x16x32_bf16 v[96:99], v[206:209], v[222:225], v[96:99]
	v_mfma_f32_16x16x32_bf16 v[84:87], v[180:183], v[230:233], v[84:87]
	v_mfma_f32_16x16x32_bf16 v[80:83], v[206:209], v[230:233], v[80:83]
	v_mfma_f32_16x16x32_bf16 v[68:71], v[180:183], v[238:241], v[68:71]
	v_mfma_f32_16x16x32_bf16 v[64:67], v[206:209], v[238:241], v[64:67]
	v_mfma_f32_16x16x32_bf16 v[116:119], v[184:187], v[218:221], v[116:119]
	v_mfma_f32_16x16x32_bf16 v[112:115], v[210:213], v[218:221], v[112:115]
	v_mfma_f32_16x16x32_bf16 v[100:103], v[184:187], v[226:229], v[100:103]
	v_mfma_f32_16x16x32_bf16 v[96:99], v[210:213], v[226:229], v[96:99]
	v_mfma_f32_16x16x32_bf16 v[84:87], v[184:187], v[234:237], v[84:87]
	v_mfma_f32_16x16x32_bf16 v[80:83], v[210:213], v[234:237], v[80:83]
	v_mfma_f32_16x16x32_bf16 v[68:71], v[184:187], v[242:245], v[68:71]
	v_mfma_f32_16x16x32_bf16 v[64:67], v[210:213], v[242:245], v[64:67]
	s_barrier
	s_add_i32 s35, s35, s12
	v_lshl_add_u64 v[142:143], s[8:9], 0, v[132:133]
	s_mov_b32 m0, s35
	ds_read_b128 v[214:217], v166 offset:16384
	ds_read_b128 v[218:221], v166 offset:17408
	ds_read_b128 v[222:225], v166 offset:18432
	ds_read_b128 v[226:229], v166 offset:19456
	ds_read_b128 v[230:233], v166 offset:20480
	ds_read_b128 v[234:237], v166 offset:21504
	ds_read_b128 v[238:241], v166 offset:22528
	ds_read_b128 v[242:245], v166 offset:23552
	global_load_lds_dwordx4 v[142:143], off
	s_add_i32 m0, s35, 0x2000
	s_add_u32 s58, s8, 0x40000
	v_lshl_add_u64 v[144:145], s[8:9], 0, v[128:129]
	s_addc_u32 s59, s9, 0
	s_add_i32 s35, s57, s12
	global_load_lds_dwordx4 v[144:145], off
	v_lshl_add_u64 v[146:147], s[58:59], 0, v[132:133]
	s_mov_b32 m0, s35
	v_lshl_add_u64 v[148:149], s[10:11], 0, v[130:131]
	global_load_lds_dwordx4 v[146:147], off
	v_lshl_add_u64 v[146:147], s[58:59], 0, v[128:129]
	s_add_i32 m0, s35, 0x2000
	s_nop 0
	global_load_lds_dwordx4 v[146:147], off
	v_lshl_add_u64 v[146:147], s[10:11], 0, v[134:135]
	s_mov_b32 m0, s66
	s_nop 0
	global_load_lds_dwordx4 v[146:147], off
	s_mov_b32 m0, s67
	s_nop 0
	global_load_lds_dwordx4 v[148:149], off
	s_waitcnt vmcnt(8)
	s_waitcnt lgkmcnt(0)
	s_barrier
	v_mfma_f32_16x16x32_bf16 v[60:63], v[158:161], v[214:217], v[60:63]
	v_mfma_f32_16x16x32_bf16 v[56:59], v[172:175], v[214:217], v[56:59]
	v_mfma_f32_16x16x32_bf16 v[44:47], v[158:161], v[222:225], v[44:47]
	v_mfma_f32_16x16x32_bf16 v[40:43], v[172:175], v[222:225], v[40:43]
	v_mfma_f32_16x16x32_bf16 v[28:31], v[158:161], v[230:233], v[28:31]
	v_mfma_f32_16x16x32_bf16 v[24:27], v[172:175], v[230:233], v[24:27]
	v_mfma_f32_16x16x32_bf16 v[12:15], v[158:161], v[238:241], v[12:15]
	v_mfma_f32_16x16x32_bf16 v[8:11], v[172:175], v[238:241], v[8:11]
	v_mfma_f32_16x16x32_bf16 v[60:63], v[168:171], v[218:221], v[60:63]
	v_mfma_f32_16x16x32_bf16 v[56:59], v[176:179], v[218:221], v[56:59]
	v_mfma_f32_16x16x32_bf16 v[44:47], v[168:171], v[226:229], v[44:47]
	v_mfma_f32_16x16x32_bf16 v[40:43], v[176:179], v[226:229], v[40:43]
	v_mfma_f32_16x16x32_bf16 v[28:31], v[168:171], v[234:237], v[28:31]
	v_mfma_f32_16x16x32_bf16 v[24:27], v[176:179], v[234:237], v[24:27]
	v_mfma_f32_16x16x32_bf16 v[12:15], v[168:171], v[242:245], v[12:15]
	v_mfma_f32_16x16x32_bf16 v[8:11], v[176:179], v[242:245], v[8:11]
	v_mfma_f32_16x16x32_bf16 v[52:55], v[180:183], v[214:217], v[52:55]
	v_mfma_f32_16x16x32_bf16 v[48:51], v[206:209], v[214:217], v[48:51]
	v_mfma_f32_16x16x32_bf16 v[36:39], v[180:183], v[222:225], v[36:39]
	v_mfma_f32_16x16x32_bf16 v[32:35], v[206:209], v[222:225], v[32:35]
	v_mfma_f32_16x16x32_bf16 v[20:23], v[180:183], v[230:233], v[20:23]
	v_mfma_f32_16x16x32_bf16 v[16:19], v[206:209], v[230:233], v[16:19]
	v_mfma_f32_16x16x32_bf16 v[4:7], v[180:183], v[238:241], v[4:7]
	v_mfma_f32_16x16x32_bf16 v[0:3], v[206:209], v[238:241], v[0:3]
	v_mfma_f32_16x16x32_bf16 v[52:55], v[184:187], v[218:221], v[52:55]
	v_mfma_f32_16x16x32_bf16 v[48:51], v[210:213], v[218:221], v[48:51]
	v_mfma_f32_16x16x32_bf16 v[36:39], v[184:187], v[226:229], v[36:39]
	v_mfma_f32_16x16x32_bf16 v[32:35], v[210:213], v[226:229], v[32:35]
	v_mfma_f32_16x16x32_bf16 v[20:23], v[184:187], v[234:237], v[20:23]
	v_mfma_f32_16x16x32_bf16 v[16:19], v[210:213], v[234:237], v[16:19]
	v_mfma_f32_16x16x32_bf16 v[4:7], v[184:187], v[242:245], v[4:7]
	v_mfma_f32_16x16x32_bf16 v[0:3], v[210:213], v[242:245], v[0:3]
	s_barrier
	s_add_i32 s35, 0, 0x18000
	v_add_u32_e32 v140, s35, v165
	s_add_i32 s57, 0, 0x1c000
	ds_read_b128 v[158:161], v140
	ds_read_b128 v[168:171], v140 offset:1024
	ds_read_b128 v[172:175], v140 offset:2048
	ds_read_b128 v[176:179], v140 offset:3072
	v_add_u32_e32 v140, s57, v165
	ds_read_b128 v[180:183], v140
	ds_read_b128 v[184:187], v140 offset:1024
	ds_read_b128 v[206:209], v140 offset:2048
	ds_read_b128 v[210:213], v140 offset:3072
	s_add_u32 s10, s10, 0x40000
	s_addc_u32 s11, s11, 0
	s_mov_b32 m0, s74
	v_lshl_add_u64 v[150:151], s[10:11], 0, v[134:135]
	ds_read_b128 v[214:217], v166 offset:32768
	ds_read_b128 v[218:221], v166 offset:33792
	ds_read_b128 v[222:225], v166 offset:34816
	ds_read_b128 v[226:229], v166 offset:35840
	ds_read_b128 v[230:233], v166 offset:36864
	ds_read_b128 v[234:237], v166 offset:37888
	ds_read_b128 v[238:241], v166 offset:38912
	ds_read_b128 v[242:245], v166 offset:39936
	global_load_lds_dwordx4 v[150:151], off
	v_lshl_add_u64 v[150:151], s[10:11], 0, v[130:131]
	s_mov_b32 m0, s75
	s_nop 0
	global_load_lds_dwordx4 v[150:151], off
	s_waitcnt vmcnt(8)
	s_waitcnt lgkmcnt(0)
	s_barrier
	v_mfma_f32_16x16x32_bf16 v[124:127], v[158:161], v[214:217], v[124:127]
	v_mfma_f32_16x16x32_bf16 v[120:123], v[172:175], v[214:217], v[120:123]
	v_mfma_f32_16x16x32_bf16 v[108:111], v[158:161], v[222:225], v[108:111]
	v_mfma_f32_16x16x32_bf16 v[104:107], v[172:175], v[222:225], v[104:107]
	v_mfma_f32_16x16x32_bf16 v[92:95], v[158:161], v[230:233], v[92:95]
	v_mfma_f32_16x16x32_bf16 v[88:91], v[172:175], v[230:233], v[88:91]
	v_mfma_f32_16x16x32_bf16 v[76:79], v[158:161], v[238:241], v[76:79]
	v_mfma_f32_16x16x32_bf16 v[72:75], v[172:175], v[238:241], v[72:75]
	v_mfma_f32_16x16x32_bf16 v[124:127], v[168:171], v[218:221], v[124:127]
	v_mfma_f32_16x16x32_bf16 v[120:123], v[176:179], v[218:221], v[120:123]
	v_mfma_f32_16x16x32_bf16 v[108:111], v[168:171], v[226:229], v[108:111]
	v_mfma_f32_16x16x32_bf16 v[104:107], v[176:179], v[226:229], v[104:107]
	v_mfma_f32_16x16x32_bf16 v[92:95], v[168:171], v[234:237], v[92:95]
	v_mfma_f32_16x16x32_bf16 v[88:91], v[176:179], v[234:237], v[88:91]
	v_mfma_f32_16x16x32_bf16 v[76:79], v[168:171], v[242:245], v[76:79]
	v_mfma_f32_16x16x32_bf16 v[72:75], v[176:179], v[242:245], v[72:75]
	v_mfma_f32_16x16x32_bf16 v[116:119], v[180:183], v[214:217], v[116:119]
	v_mfma_f32_16x16x32_bf16 v[112:115], v[206:209], v[214:217], v[112:115]
	v_mfma_f32_16x16x32_bf16 v[100:103], v[180:183], v[222:225], v[100:103]
	v_mfma_f32_16x16x32_bf16 v[96:99], v[206:209], v[222:225], v[96:99]
	v_mfma_f32_16x16x32_bf16 v[84:87], v[180:183], v[230:233], v[84:87]
	v_mfma_f32_16x16x32_bf16 v[80:83], v[206:209], v[230:233], v[80:83]
	v_mfma_f32_16x16x32_bf16 v[68:71], v[180:183], v[238:241], v[68:71]
	v_mfma_f32_16x16x32_bf16 v[64:67], v[206:209], v[238:241], v[64:67]
	v_mfma_f32_16x16x32_bf16 v[116:119], v[184:187], v[218:221], v[116:119]
	v_mfma_f32_16x16x32_bf16 v[112:115], v[210:213], v[218:221], v[112:115]
	v_mfma_f32_16x16x32_bf16 v[100:103], v[184:187], v[226:229], v[100:103]
	v_mfma_f32_16x16x32_bf16 v[96:99], v[210:213], v[226:229], v[96:99]
	v_mfma_f32_16x16x32_bf16 v[84:87], v[184:187], v[234:237], v[84:87]
	v_mfma_f32_16x16x32_bf16 v[80:83], v[210:213], v[234:237], v[80:83]
	v_mfma_f32_16x16x32_bf16 v[68:71], v[184:187], v[242:245], v[68:71]
	v_mfma_f32_16x16x32_bf16 v[64:67], v[210:213], v[242:245], v[64:67]
	s_barrier
	s_add_i32 s10, s35, s12
	v_lshl_add_u64 v[142:143], v[142:143], 0, s[36:37]
	s_mov_b32 m0, s10
	ds_read_b128 v[214:217], v166 offset:49152
	ds_read_b128 v[218:221], v166 offset:50176
	ds_read_b128 v[222:225], v166 offset:51200
	ds_read_b128 v[226:229], v166 offset:52224
	ds_read_b128 v[230:233], v166 offset:53248
	ds_read_b128 v[234:237], v166 offset:54272
	ds_read_b128 v[238:241], v166 offset:55296
	ds_read_b128 v[242:245], v166 offset:56320
	global_load_lds_dwordx4 v[142:143], off
	s_add_i32 m0, s10, 0x2000
	s_add_u32 s8, s8, 0x40080
	v_lshl_add_u64 v[142:143], v[144:145], 0, s[36:37]
	s_addc_u32 s9, s9, 0
	s_add_i32 s10, s57, s12
	global_load_lds_dwordx4 v[142:143], off
	v_lshl_add_u64 v[142:143], s[8:9], 0, v[132:133]
	s_mov_b32 m0, s10
	s_nop 0
	global_load_lds_dwordx4 v[142:143], off
	v_lshl_add_u64 v[142:143], s[8:9], 0, v[128:129]
	s_add_i32 m0, s10, 0x2000
	s_nop 0
	global_load_lds_dwordx4 v[142:143], off
	v_lshl_add_u64 v[142:143], v[146:147], 0, s[36:37]
	s_mov_b32 m0, s26
	s_nop 0
	global_load_lds_dwordx4 v[142:143], off
	v_lshl_add_u64 v[142:143], v[148:149], 0, s[36:37]
	s_mov_b32 m0, s27
	s_nop 0
	global_load_lds_dwordx4 v[142:143], off
	s_waitcnt vmcnt(8)
	s_waitcnt lgkmcnt(0)
	s_barrier
	v_mfma_f32_16x16x32_bf16 v[60:63], v[158:161], v[214:217], v[60:63]
	v_mfma_f32_16x16x32_bf16 v[56:59], v[172:175], v[214:217], v[56:59]
	v_mfma_f32_16x16x32_bf16 v[44:47], v[158:161], v[222:225], v[44:47]
	v_mfma_f32_16x16x32_bf16 v[40:43], v[172:175], v[222:225], v[40:43]
	v_mfma_f32_16x16x32_bf16 v[28:31], v[158:161], v[230:233], v[28:31]
	v_mfma_f32_16x16x32_bf16 v[24:27], v[172:175], v[230:233], v[24:27]
	v_mfma_f32_16x16x32_bf16 v[12:15], v[158:161], v[238:241], v[12:15]
	v_mfma_f32_16x16x32_bf16 v[8:11], v[172:175], v[238:241], v[8:11]
	v_mfma_f32_16x16x32_bf16 v[60:63], v[168:171], v[218:221], v[60:63]
	v_mfma_f32_16x16x32_bf16 v[56:59], v[176:179], v[218:221], v[56:59]
	v_mfma_f32_16x16x32_bf16 v[44:47], v[168:171], v[226:229], v[44:47]
	v_mfma_f32_16x16x32_bf16 v[40:43], v[176:179], v[226:229], v[40:43]
	v_mfma_f32_16x16x32_bf16 v[28:31], v[168:171], v[234:237], v[28:31]
	v_mfma_f32_16x16x32_bf16 v[24:27], v[176:179], v[234:237], v[24:27]
	v_mfma_f32_16x16x32_bf16 v[12:15], v[168:171], v[242:245], v[12:15]
	v_mfma_f32_16x16x32_bf16 v[8:11], v[176:179], v[242:245], v[8:11]
	v_mfma_f32_16x16x32_bf16 v[52:55], v[180:183], v[214:217], v[52:55]
	v_mfma_f32_16x16x32_bf16 v[48:51], v[206:209], v[214:217], v[48:51]
	v_mfma_f32_16x16x32_bf16 v[36:39], v[180:183], v[222:225], v[36:39]
	v_mfma_f32_16x16x32_bf16 v[32:35], v[206:209], v[222:225], v[32:35]
	v_mfma_f32_16x16x32_bf16 v[20:23], v[180:183], v[230:233], v[20:23]
	v_mfma_f32_16x16x32_bf16 v[16:19], v[206:209], v[230:233], v[16:19]
	v_mfma_f32_16x16x32_bf16 v[4:7], v[180:183], v[238:241], v[4:7]
	v_mfma_f32_16x16x32_bf16 v[0:3], v[206:209], v[238:241], v[0:3]
	v_mfma_f32_16x16x32_bf16 v[52:55], v[184:187], v[218:221], v[52:55]
	v_mfma_f32_16x16x32_bf16 v[48:51], v[210:213], v[218:221], v[48:51]
	v_mfma_f32_16x16x32_bf16 v[36:39], v[184:187], v[226:229], v[36:39]
	v_mfma_f32_16x16x32_bf16 v[32:35], v[210:213], v[226:229], v[32:35]
	v_mfma_f32_16x16x32_bf16 v[20:23], v[184:187], v[234:237], v[20:23]
	v_mfma_f32_16x16x32_bf16 v[16:19], v[210:213], v[234:237], v[16:19]
	v_mfma_f32_16x16x32_bf16 v[4:7], v[184:187], v[242:245], v[4:7]
	v_mfma_f32_16x16x32_bf16 v[0:3], v[210:213], v[242:245], v[0:3]
	s_barrier
	s_add_i32 s56, s56, 2
	s_add_u32 s6, s6, 0x100
	s_addc_u32 s7, s7, 0
	s_add_u32 s47, s47, 0x100
	s_addc_u32 s51, s51, 0
	s_cmp_gt_u32 s56, 13
	s_cbranch_scc0 .LBB0_552
	s_and_b64 vcc, exec, s[44:45]
	s_cbranch_vccz .LBB0_555
	s_barrier

.LBB0_676:
	s_lshl_b32 s12, s61, 22
	s_and_b32 s35, s12, 0x3c00000
	s_ashr_i32 s12, s61, 4
	s_ashr_i32 s13, s12, 31
	s_lshl_b64 s[12:13], s[12:13], 9
	s_add_u32 s35, s14, s35
	s_addc_u32 s53, s15, 0
	s_add_u32 s54, s35, s12
	s_addc_u32 s55, s53, s13
	s_and_b64 s[56:57], s[42:43], exec
	s_cselect_b32 s59, s55, s9
	s_cselect_b32 s58, s54, s8
	s_ashr_i32 s53, s52, 31
	s_lshl_b64 s[56:57], s[52:53], 19
	s_add_u32 s35, s26, s56
	s_addc_u32 s53, s27, s57
	s_add_u32 s56, s35, s12
	s_addc_u32 s57, s53, s13
	s_and_b64 s[12:13], s[42:43], exec
	s_cselect_b32 s13, s57, s11
	s_cselect_b32 s12, s56, s10
	s_add_i32 s70, 0, 0x10000
	s_add_i32 s71, 0, 0x14000
	v_add_u32_e32 v152, s70, v138
	v_add_u32_e32 v153, s71, v138
	ds_read_b128 v[0:3], v152
	ds_read_b128 v[4:7], v152 offset:1024
	ds_read_b128 v[8:11], v152 offset:2048
	ds_read_b128 v[12:15], v152 offset:3072
	ds_read_b128 v[16:19], v153
	ds_read_b128 v[20:23], v153 offset:1024
	ds_read_b128 v[24:27], v153 offset:2048
	ds_read_b128 v[28:31], v153 offset:3072
	v_mov_b32_e32 v204, 0x358637bd
	v_mov_b32_e32 v250, 0x260
	v_mov_b32_e32 v251, 0x3e124925
	s_add_u32 s68, s8, 0x200080
	s_addc_u32 s69, s9, 0
	s_add_i32 s72, s4, 0xc000
	v_lshl_add_u64 v[64:65], s[68:69], 0, v[132:133]
	s_mov_b32 m0, s72
	s_add_i32 s35, s4, 0xe000
	ds_read_b128 v[32:35], v139
	ds_read_b128 v[36:39], v139 offset:1024
	ds_read_b128 v[40:43], v139 offset:2048
	ds_read_b128 v[44:47], v139 offset:3072
	ds_read_b128 v[48:51], v139 offset:4096
	ds_read_b128 v[52:55], v139 offset:5120
	ds_read_b128 v[56:59], v139 offset:6144
	ds_read_b128 v[60:63], v139 offset:7168
	global_load_lds_dwordx4 v[64:65], off
	v_lshl_add_u64 v[64:65], s[68:69], 0, v[130:131]
	s_mov_b32 m0, s35
	s_nop 0
	global_load_lds_dwordx4 v[64:65], off
	s_waitcnt vmcnt(8)
	s_waitcnt lgkmcnt(0)
	s_barrier
	v_mfma_f32_16x16x32_bf16 v[64:67], v[0:3], v[32:35], 0
	v_mfma_f32_16x16x32_bf16 v[68:71], v[8:11], v[32:35], 0
	v_mfma_f32_16x16x32_bf16 v[72:75], v[0:3], v[40:43], 0
	v_mfma_f32_16x16x32_bf16 v[76:79], v[8:11], v[40:43], 0
	v_mfma_f32_16x16x32_bf16 v[80:83], v[0:3], v[48:51], 0
	v_mfma_f32_16x16x32_bf16 v[84:87], v[8:11], v[48:51], 0
	v_mfma_f32_16x16x32_bf16 v[88:91], v[0:3], v[56:59], 0
	v_mfma_f32_16x16x32_bf16 v[92:95], v[8:11], v[56:59], 0
	v_mfma_f32_16x16x32_bf16 v[64:67], v[4:7], v[36:39], v[64:67]
	v_mfma_f32_16x16x32_bf16 v[68:71], v[12:15], v[36:39], v[68:71]
	v_mfma_f32_16x16x32_bf16 v[72:75], v[4:7], v[44:47], v[72:75]
	v_mfma_f32_16x16x32_bf16 v[76:79], v[12:15], v[44:47], v[76:79]
	v_mfma_f32_16x16x32_bf16 v[80:83], v[4:7], v[52:55], v[80:83]
	v_mfma_f32_16x16x32_bf16 v[84:87], v[12:15], v[52:55], v[84:87]
	v_mfma_f32_16x16x32_bf16 v[88:91], v[4:7], v[60:63], v[88:91]
	v_mfma_f32_16x16x32_bf16 v[92:95], v[12:15], v[60:63], v[92:95]
	v_mfma_f32_16x16x32_bf16 v[96:99], v[16:19], v[32:35], 0
	v_mfma_f32_16x16x32_bf16 v[32:35], v[24:27], v[32:35], 0
	v_mfma_f32_16x16x32_bf16 v[96:99], v[20:23], v[36:39], v[96:99]
	v_mfma_f32_16x16x32_bf16 v[32:35], v[28:31], v[36:39], v[32:35]
	v_mfma_f32_16x16x32_bf16 v[36:39], v[16:19], v[40:43], 0
	v_mfma_f32_16x16x32_bf16 v[40:43], v[24:27], v[40:43], 0
	v_mfma_f32_16x16x32_bf16 v[36:39], v[20:23], v[44:47], v[36:39]
	v_mfma_f32_16x16x32_bf16 v[40:43], v[28:31], v[44:47], v[40:43]
	v_mfma_f32_16x16x32_bf16 v[44:47], v[16:19], v[48:51], 0
	v_mfma_f32_16x16x32_bf16 v[48:51], v[24:27], v[48:51], 0
	v_mfma_f32_16x16x32_bf16 v[44:47], v[20:23], v[52:55], v[44:47]
	v_mfma_f32_16x16x32_bf16 v[48:51], v[28:31], v[52:55], v[48:51]
	v_mfma_f32_16x16x32_bf16 v[52:55], v[16:19], v[56:59], 0
	v_mfma_f32_16x16x32_bf16 v[56:59], v[24:27], v[56:59], 0
	v_mfma_f32_16x16x32_bf16 v[52:55], v[20:23], v[60:63], v[52:55]
	v_mfma_f32_16x16x32_bf16 v[56:59], v[28:31], v[60:63], v[56:59]
	s_barrier
	s_add_i32 s70, s70, s28
	v_lshl_add_u64 v[142:143], s[10:11], 0, v[140:141]
	s_mov_b64 s[2:3], 0x100
	s_add_i32 s53, s70, 0x2000
	v_lshl_add_u64 v[134:135], v[142:143], 0, s[2:3]
	s_mov_b32 m0, s70
	v_lshl_add_u64 v[144:145], s[10:11], 0, v[128:129]
	s_add_u32 s74, s10, 0x40100
	ds_read_b128 v[60:63], v139 offset:16384
	ds_read_b128 v[100:103], v139 offset:17408
	ds_read_b128 v[104:107], v139 offset:18432
	ds_read_b128 v[108:111], v139 offset:19456
	ds_read_b128 v[112:115], v139 offset:20480
	ds_read_b128 v[116:119], v139 offset:21504
	ds_read_b128 v[120:123], v139 offset:22528
	ds_read_b128 v[124:127], v139 offset:23552
	global_load_lds_dwordx4 v[134:135], off
	v_lshl_add_u64 v[134:135], v[144:145], 0, s[2:3]
	s_mov_b32 m0, s53
	s_addc_u32 s75, s11, 0
	s_add_i32 s68, s71, s28
	global_load_lds_dwordx4 v[134:135], off
	v_lshl_add_u64 v[134:135], s[74:75], 0, v[140:141]
	s_mov_b32 m0, s68
	s_add_i32 s69, s68, 0x2000
	global_load_lds_dwordx4 v[134:135], off
	v_lshl_add_u64 v[134:135], s[74:75], 0, v[128:129]
	s_mov_b32 m0, s69
	v_lshl_add_u64 v[146:147], s[8:9], 0, v[132:133]
	global_load_lds_dwordx4 v[134:135], off
	v_lshl_add_u64 v[134:135], v[146:147], 0, s[2:3]
	s_mov_b32 m0, s4
	v_lshl_add_u64 v[148:149], s[8:9], 0, v[130:131]
	global_load_lds_dwordx4 v[134:135], off
	v_lshl_add_u64 v[134:135], v[148:149], 0, s[2:3]
	s_mov_b32 m0, s5
	s_nop 0
	global_load_lds_dwordx4 v[134:135], off
	s_waitcnt vmcnt(8)
	s_waitcnt lgkmcnt(0)
	s_barrier
	v_mfma_f32_16x16x32_bf16 v[134:137], v[0:3], v[60:63], 0
	v_mfma_f32_16x16x32_bf16 v[162:165], v[0:3], v[104:107], 0
	v_mfma_f32_16x16x32_bf16 v[170:173], v[0:3], v[112:115], 0
	v_mfma_f32_16x16x32_bf16 v[0:3], v[0:3], v[120:123], 0
	v_mfma_f32_16x16x32_bf16 v[134:137], v[4:7], v[100:103], v[134:137]
	v_mfma_f32_16x16x32_bf16 v[162:165], v[4:7], v[108:111], v[162:165]
	v_mfma_f32_16x16x32_bf16 v[170:173], v[4:7], v[116:119], v[170:173]
	v_mfma_f32_16x16x32_bf16 v[0:3], v[4:7], v[124:127], v[0:3]
	v_mfma_f32_16x16x32_bf16 v[4:7], v[8:11], v[120:123], 0
	v_mfma_f32_16x16x32_bf16 v[158:161], v[8:11], v[60:63], 0
	v_mfma_f32_16x16x32_bf16 v[166:169], v[8:11], v[104:107], 0
	v_mfma_f32_16x16x32_bf16 v[174:177], v[8:11], v[112:115], 0
	v_mfma_f32_16x16x32_bf16 v[4:7], v[12:15], v[124:127], v[4:7]
	v_mfma_f32_16x16x32_bf16 v[158:161], v[12:15], v[100:103], v[158:161]
	v_mfma_f32_16x16x32_bf16 v[166:169], v[12:15], v[108:111], v[166:169]
	v_mfma_f32_16x16x32_bf16 v[174:177], v[12:15], v[116:119], v[174:177]
	v_mfma_f32_16x16x32_bf16 v[8:11], v[16:19], v[60:63], 0
	v_mfma_f32_16x16x32_bf16 v[12:15], v[24:27], v[60:63], 0
	v_mfma_f32_16x16x32_bf16 v[8:11], v[20:23], v[100:103], v[8:11]
	v_mfma_f32_16x16x32_bf16 v[12:15], v[28:31], v[100:103], v[12:15]
	v_mfma_f32_16x16x32_bf16 v[60:63], v[16:19], v[104:107], 0
	v_mfma_f32_16x16x32_bf16 v[100:103], v[24:27], v[104:107], 0
	v_mfma_f32_16x16x32_bf16 v[104:107], v[16:19], v[112:115], 0
	v_mfma_f32_16x16x32_bf16 v[16:19], v[16:19], v[120:123], 0
	v_mfma_f32_16x16x32_bf16 v[60:63], v[20:23], v[108:111], v[60:63]
	v_mfma_f32_16x16x32_bf16 v[100:103], v[28:31], v[108:111], v[100:103]
	v_mfma_f32_16x16x32_bf16 v[104:107], v[20:23], v[116:119], v[104:107]
	v_mfma_f32_16x16x32_bf16 v[108:111], v[24:27], v[112:115], 0
	v_mfma_f32_16x16x32_bf16 v[16:19], v[20:23], v[124:127], v[16:19]
	v_mfma_f32_16x16x32_bf16 v[20:23], v[24:27], v[120:123], 0
	v_mfma_f32_16x16x32_bf16 v[108:111], v[28:31], v[116:119], v[108:111]
	v_mfma_f32_16x16x32_bf16 v[20:23], v[28:31], v[124:127], v[20:23]
	s_barrier
	s_add_i32 s73, 0, 0x18000
	s_add_i32 s76, 0, 0x1c000
	v_add_u32_e32 v154, s73, v138
	v_add_u32_e32 v155, s76, v138
	ds_read_b128 v[24:27], v154
	ds_read_b128 v[28:31], v154 offset:1024
	ds_read_b128 v[112:115], v154 offset:2048
	ds_read_b128 v[116:119], v154 offset:3072
	ds_read_b128 v[120:123], v155
	ds_read_b128 v[124:127], v155 offset:1024
	ds_read_b128 v[178:181], v155 offset:2048
	ds_read_b128 v[182:185], v155 offset:3072
	s_add_u32 s74, s8, 0x200100
	s_addc_u32 s75, s9, 0
	s_mov_b32 m0, s24
	v_lshl_add_u64 v[150:151], s[74:75], 0, v[132:133]
	ds_read_b128 v[206:209], v139 offset:32768
	ds_read_b128 v[210:213], v139 offset:33792
	ds_read_b128 v[214:217], v139 offset:34816
	ds_read_b128 v[218:221], v139 offset:35840
	ds_read_b128 v[222:225], v139 offset:36864
	ds_read_b128 v[226:229], v139 offset:37888
	ds_read_b128 v[230:233], v139 offset:38912
	ds_read_b128 v[234:237], v139 offset:39936
	global_load_lds_dwordx4 v[150:151], off
	v_lshl_add_u64 v[150:151], s[74:75], 0, v[130:131]
	s_mov_b32 m0, s29
	s_nop 0
	global_load_lds_dwordx4 v[150:151], off
	s_waitcnt vmcnt(8)
	s_waitcnt lgkmcnt(0)
	s_barrier
	v_mfma_f32_16x16x32_bf16 v[64:67], v[24:27], v[206:209], v[64:67]
	v_mfma_f32_16x16x32_bf16 v[68:71], v[112:115], v[206:209], v[68:71]
	v_mfma_f32_16x16x32_bf16 v[72:75], v[24:27], v[214:217], v[72:75]
	v_mfma_f32_16x16x32_bf16 v[76:79], v[112:115], v[214:217], v[76:79]
	v_mfma_f32_16x16x32_bf16 v[80:83], v[24:27], v[222:225], v[80:83]
	v_mfma_f32_16x16x32_bf16 v[84:87], v[112:115], v[222:225], v[84:87]
	v_mfma_f32_16x16x32_bf16 v[88:91], v[24:27], v[230:233], v[88:91]
	v_mfma_f32_16x16x32_bf16 v[92:95], v[112:115], v[230:233], v[92:95]
	v_mfma_f32_16x16x32_bf16 v[64:67], v[28:31], v[210:213], v[64:67]
	v_mfma_f32_16x16x32_bf16 v[68:71], v[116:119], v[210:213], v[68:71]
	v_mfma_f32_16x16x32_bf16 v[72:75], v[28:31], v[218:221], v[72:75]
	v_mfma_f32_16x16x32_bf16 v[76:79], v[116:119], v[218:221], v[76:79]
	v_mfma_f32_16x16x32_bf16 v[80:83], v[28:31], v[226:229], v[80:83]
	v_mfma_f32_16x16x32_bf16 v[84:87], v[116:119], v[226:229], v[84:87]
	v_mfma_f32_16x16x32_bf16 v[88:91], v[28:31], v[234:237], v[88:91]
	v_mfma_f32_16x16x32_bf16 v[92:95], v[116:119], v[234:237], v[92:95]
	v_mfma_f32_16x16x32_bf16 v[96:99], v[120:123], v[206:209], v[96:99]
	v_mfma_f32_16x16x32_bf16 v[32:35], v[178:181], v[206:209], v[32:35]
	v_mfma_f32_16x16x32_bf16 v[36:39], v[120:123], v[214:217], v[36:39]
	v_mfma_f32_16x16x32_bf16 v[40:43], v[178:181], v[214:217], v[40:43]
	v_mfma_f32_16x16x32_bf16 v[44:47], v[120:123], v[222:225], v[44:47]
	v_mfma_f32_16x16x32_bf16 v[48:51], v[178:181], v[222:225], v[48:51]
	v_mfma_f32_16x16x32_bf16 v[52:55], v[120:123], v[230:233], v[52:55]
	v_mfma_f32_16x16x32_bf16 v[56:59], v[178:181], v[230:233], v[56:59]
	v_mfma_f32_16x16x32_bf16 v[96:99], v[124:127], v[210:213], v[96:99]
	v_mfma_f32_16x16x32_bf16 v[32:35], v[182:185], v[210:213], v[32:35]
	v_mfma_f32_16x16x32_bf16 v[36:39], v[124:127], v[218:221], v[36:39]
	v_mfma_f32_16x16x32_bf16 v[40:43], v[182:185], v[218:221], v[40:43]
	v_mfma_f32_16x16x32_bf16 v[44:47], v[124:127], v[226:229], v[44:47]
	v_mfma_f32_16x16x32_bf16 v[48:51], v[182:185], v[226:229], v[48:51]
	v_mfma_f32_16x16x32_bf16 v[52:55], v[124:127], v[234:237], v[52:55]
	v_mfma_f32_16x16x32_bf16 v[56:59], v[182:185], v[234:237], v[56:59]
	s_barrier
	s_add_i32 s73, s73, s28
	s_mov_b64 s[2:3], 0x180
	s_add_i32 s71, s73, 0x2000
	v_lshl_add_u64 v[142:143], v[142:143], 0, s[2:3]
	s_mov_b32 m0, s73
	s_add_u32 s74, s10, 0x40180
	ds_read_b128 v[206:209], v139 offset:49152
	ds_read_b128 v[210:213], v139 offset:50176
	ds_read_b128 v[214:217], v139 offset:51200
	ds_read_b128 v[218:221], v139 offset:52224
	ds_read_b128 v[222:225], v139 offset:53248
	ds_read_b128 v[226:229], v139 offset:54272
	ds_read_b128 v[230:233], v139 offset:55296
	ds_read_b128 v[234:237], v139 offset:56320
	global_load_lds_dwordx4 v[142:143], off
	v_lshl_add_u64 v[142:143], v[144:145], 0, s[2:3]
	s_mov_b32 m0, s71
	s_addc_u32 s75, s11, 0
	s_add_i32 s10, s76, s28
	global_load_lds_dwordx4 v[142:143], off
	v_lshl_add_u64 v[142:143], s[74:75], 0, v[140:141]
	s_mov_b32 m0, s10
	s_add_i32 s11, s10, 0x2000
	global_load_lds_dwordx4 v[142:143], off
	v_lshl_add_u64 v[142:143], s[74:75], 0, v[128:129]
	s_mov_b32 m0, s11
	s_nop 0
	global_load_lds_dwordx4 v[142:143], off
	v_lshl_add_u64 v[142:143], v[146:147], 0, s[2:3]
	s_mov_b32 m0, s38
	s_nop 0
	global_load_lds_dwordx4 v[142:143], off
	v_lshl_add_u64 v[142:143], v[148:149], 0, s[2:3]
	s_mov_b32 m0, s60
	s_nop 0
	global_load_lds_dwordx4 v[142:143], off
	s_waitcnt vmcnt(8)
	s_waitcnt lgkmcnt(0)
	s_barrier
	v_mfma_f32_16x16x32_bf16 v[0:3], v[24:27], v[230:233], v[0:3]
	v_mfma_f32_16x16x32_bf16 v[4:7], v[112:115], v[230:233], v[4:7]
	v_mfma_f32_16x16x32_bf16 v[134:137], v[24:27], v[206:209], v[134:137]
	v_mfma_f32_16x16x32_bf16 v[158:161], v[112:115], v[206:209], v[158:161]
	v_mfma_f32_16x16x32_bf16 v[162:165], v[24:27], v[214:217], v[162:165]
	v_mfma_f32_16x16x32_bf16 v[166:169], v[112:115], v[214:217], v[166:169]
	v_mfma_f32_16x16x32_bf16 v[170:173], v[24:27], v[222:225], v[170:173]
	v_mfma_f32_16x16x32_bf16 v[174:177], v[112:115], v[222:225], v[174:177]
	v_mfma_f32_16x16x32_bf16 v[0:3], v[28:31], v[234:237], v[0:3]
	v_mfma_f32_16x16x32_bf16 v[4:7], v[116:119], v[234:237], v[4:7]
	v_mfma_f32_16x16x32_bf16 v[134:137], v[28:31], v[210:213], v[134:137]
	v_mfma_f32_16x16x32_bf16 v[158:161], v[116:119], v[210:213], v[158:161]
	v_mfma_f32_16x16x32_bf16 v[162:165], v[28:31], v[218:221], v[162:165]
	v_mfma_f32_16x16x32_bf16 v[166:169], v[116:119], v[218:221], v[166:169]
	v_mfma_f32_16x16x32_bf16 v[170:173], v[28:31], v[226:229], v[170:173]
	v_mfma_f32_16x16x32_bf16 v[174:177], v[116:119], v[226:229], v[174:177]
	v_mfma_f32_16x16x32_bf16 v[8:11], v[120:123], v[206:209], v[8:11]
	v_mfma_f32_16x16x32_bf16 v[12:15], v[178:181], v[206:209], v[12:15]
	v_mfma_f32_16x16x32_bf16 v[24:27], v[120:123], v[214:217], v[60:63]
	v_mfma_f32_16x16x32_bf16 v[28:31], v[178:181], v[214:217], v[100:103]
	v_mfma_f32_16x16x32_bf16 v[60:63], v[120:123], v[222:225], v[104:107]
	v_mfma_f32_16x16x32_bf16 v[100:103], v[178:181], v[222:225], v[108:111]
	v_mfma_f32_16x16x32_bf16 v[16:19], v[120:123], v[230:233], v[16:19]
	v_mfma_f32_16x16x32_bf16 v[20:23], v[178:181], v[230:233], v[20:23]
	v_mfma_f32_16x16x32_bf16 v[8:11], v[124:127], v[210:213], v[8:11]
	v_mfma_f32_16x16x32_bf16 v[12:15], v[182:185], v[210:213], v[12:15]
	v_mfma_f32_16x16x32_bf16 v[24:27], v[124:127], v[218:221], v[24:27]
	v_mfma_f32_16x16x32_bf16 v[28:31], v[182:185], v[218:221], v[28:31]
	v_mfma_f32_16x16x32_bf16 v[60:63], v[124:127], v[226:229], v[60:63]
	v_mfma_f32_16x16x32_bf16 v[100:103], v[182:185], v[226:229], v[100:103]
	v_mfma_f32_16x16x32_bf16 v[16:19], v[124:127], v[234:237], v[16:19]
	v_mfma_f32_16x16x32_bf16 v[20:23], v[182:185], v[234:237], v[20:23]
	s_barrier
	ds_read_b128 v[104:107], v152
	ds_read_b128 v[108:111], v152 offset:1024
	ds_read_b128 v[112:115], v152 offset:2048
	ds_read_b128 v[116:119], v152 offset:3072
	ds_read_b128 v[120:123], v153
	ds_read_b128 v[124:127], v153 offset:1024
	ds_read_b128 v[178:181], v153 offset:2048
	ds_read_b128 v[182:185], v153 offset:3072
	s_add_u32 s8, s8, 0x200180
	s_addc_u32 s9, s9, 0
	s_mov_b32 m0, s72
	v_lshl_add_u64 v[142:143], s[8:9], 0, v[132:133]
	ds_read_b128 v[206:209], v139
	ds_read_b128 v[210:213], v139 offset:1024
	ds_read_b128 v[214:217], v139 offset:2048
	ds_read_b128 v[218:221], v139 offset:3072
	ds_read_b128 v[222:225], v139 offset:4096
	ds_read_b128 v[226:229], v139 offset:5120
	ds_read_b128 v[230:233], v139 offset:6144
	ds_read_b128 v[234:237], v139 offset:7168
	global_load_lds_dwordx4 v[142:143], off
	v_lshl_add_u64 v[142:143], s[8:9], 0, v[130:131]
	s_mov_b32 m0, s35
	s_nop 0
	global_load_lds_dwordx4 v[142:143], off
	s_waitcnt vmcnt(8)
	s_waitcnt lgkmcnt(0)
	s_barrier
	v_mfma_f32_16x16x32_bf16 v[64:67], v[104:107], v[206:209], v[64:67]
	v_mfma_f32_16x16x32_bf16 v[68:71], v[112:115], v[206:209], v[68:71]
	v_mfma_f32_16x16x32_bf16 v[72:75], v[104:107], v[214:217], v[72:75]
	v_mfma_f32_16x16x32_bf16 v[76:79], v[112:115], v[214:217], v[76:79]
	v_mfma_f32_16x16x32_bf16 v[80:83], v[104:107], v[222:225], v[80:83]
	v_mfma_f32_16x16x32_bf16 v[84:87], v[112:115], v[222:225], v[84:87]
	v_mfma_f32_16x16x32_bf16 v[88:91], v[104:107], v[230:233], v[88:91]
	v_mfma_f32_16x16x32_bf16 v[64:67], v[108:111], v[210:213], v[64:67]
	v_mfma_f32_16x16x32_bf16 v[68:71], v[116:119], v[210:213], v[68:71]
	v_mfma_f32_16x16x32_bf16 v[72:75], v[108:111], v[218:221], v[72:75]
	v_mfma_f32_16x16x32_bf16 v[76:79], v[116:119], v[218:221], v[76:79]
	v_mfma_f32_16x16x32_bf16 v[80:83], v[108:111], v[226:229], v[80:83]
	v_mfma_f32_16x16x32_bf16 v[84:87], v[116:119], v[226:229], v[84:87]
	v_mfma_f32_16x16x32_bf16 v[238:241], v[108:111], v[234:237], v[88:91]
	v_mfma_f32_16x16x32_bf16 v[88:91], v[112:115], v[230:233], v[92:95]
	v_mfma_f32_16x16x32_bf16 v[242:245], v[116:119], v[234:237], v[88:91]
	v_mfma_f32_16x16x32_bf16 v[88:91], v[120:123], v[206:209], v[96:99]
	v_mfma_f32_16x16x32_bf16 v[32:35], v[178:181], v[206:209], v[32:35]
	v_mfma_f32_16x16x32_bf16 v[36:39], v[120:123], v[214:217], v[36:39]
	v_mfma_f32_16x16x32_bf16 v[40:43], v[178:181], v[214:217], v[40:43]
	v_mfma_f32_16x16x32_bf16 v[44:47], v[120:123], v[222:225], v[44:47]
	v_mfma_f32_16x16x32_bf16 v[48:51], v[178:181], v[222:225], v[48:51]
	v_mfma_f32_16x16x32_bf16 v[52:55], v[120:123], v[230:233], v[52:55]
	v_mfma_f32_16x16x32_bf16 v[56:59], v[178:181], v[230:233], v[56:59]
	v_mfma_f32_16x16x32_bf16 v[96:99], v[124:127], v[210:213], v[88:91]
	v_mfma_f32_16x16x32_bf16 v[32:35], v[182:185], v[210:213], v[32:35]
	v_mfma_f32_16x16x32_bf16 v[36:39], v[124:127], v[218:221], v[36:39]
	v_mfma_f32_16x16x32_bf16 v[40:43], v[182:185], v[218:221], v[40:43]
	v_mfma_f32_16x16x32_bf16 v[44:47], v[124:127], v[226:229], v[44:47]
	v_mfma_f32_16x16x32_bf16 v[48:51], v[182:185], v[226:229], v[48:51]
	v_mfma_f32_16x16x32_bf16 v[52:55], v[124:127], v[234:237], v[52:55]
	v_mfma_f32_16x16x32_bf16 v[56:59], v[182:185], v[234:237], v[56:59]
	s_barrier
	s_mov_b32 m0, s70
	v_lshl_add_u64 v[190:191], s[12:13], 0, v[140:141]
	s_add_u32 s8, s12, 0x40000
	ds_read_b128 v[88:91], v139 offset:16384
	ds_read_b128 v[92:95], v139 offset:17408
	ds_read_b128 v[206:209], v139 offset:18432
	ds_read_b128 v[210:213], v139 offset:19456
	ds_read_b128 v[214:217], v139 offset:20480
	ds_read_b128 v[218:221], v139 offset:21504
	ds_read_b128 v[222:225], v139 offset:22528
	ds_read_b128 v[226:229], v139 offset:23552
	global_load_lds_dwordx4 v[190:191], off
	v_lshl_add_u64 v[192:193], s[12:13], 0, v[128:129]
	s_mov_b32 m0, s53
	s_addc_u32 s9, s13, 0
	global_load_lds_dwordx4 v[192:193], off
	v_lshl_add_u64 v[142:143], s[8:9], 0, v[140:141]
	s_mov_b32 m0, s68
	v_lshl_add_u64 v[194:195], s[58:59], 0, v[132:133]
	global_load_lds_dwordx4 v[142:143], off
	v_lshl_add_u64 v[142:143], s[8:9], 0, v[128:129]
	s_mov_b32 m0, s69
	v_lshl_add_u64 v[196:197], s[58:59], 0, v[130:131]
	global_load_lds_dwordx4 v[142:143], off
	s_mov_b32 m0, s4
	s_nop 0
	global_load_lds_dwordx4 v[194:195], off
	s_mov_b32 m0, s5
	s_nop 0
	global_load_lds_dwordx4 v[196:197], off
	s_waitcnt vmcnt(8)
	s_waitcnt lgkmcnt(0)
	s_barrier
	v_mfma_f32_16x16x32_bf16 v[0:3], v[104:107], v[222:225], v[0:3]
	v_mfma_f32_16x16x32_bf16 v[4:7], v[112:115], v[222:225], v[4:7]
	v_mfma_f32_16x16x32_bf16 v[134:137], v[104:107], v[88:91], v[134:137]
	v_mfma_f32_16x16x32_bf16 v[158:161], v[112:115], v[88:91], v[158:161]
	v_mfma_f32_16x16x32_bf16 v[162:165], v[104:107], v[206:209], v[162:165]
	v_mfma_f32_16x16x32_bf16 v[166:169], v[112:115], v[206:209], v[166:169]
	v_mfma_f32_16x16x32_bf16 v[170:173], v[104:107], v[214:217], v[170:173]
	v_mfma_f32_16x16x32_bf16 v[174:177], v[112:115], v[214:217], v[174:177]
	v_mfma_f32_16x16x32_bf16 v[0:3], v[108:111], v[226:229], v[0:3]
	v_mfma_f32_16x16x32_bf16 v[4:7], v[116:119], v[226:229], v[4:7]
	v_mfma_f32_16x16x32_bf16 v[134:137], v[108:111], v[92:95], v[134:137]
	v_mfma_f32_16x16x32_bf16 v[158:161], v[116:119], v[92:95], v[158:161]
	v_mfma_f32_16x16x32_bf16 v[162:165], v[108:111], v[210:213], v[162:165]
	v_mfma_f32_16x16x32_bf16 v[166:169], v[116:119], v[210:213], v[166:169]
	v_mfma_f32_16x16x32_bf16 v[170:173], v[108:111], v[218:221], v[170:173]
	v_mfma_f32_16x16x32_bf16 v[174:177], v[116:119], v[218:221], v[174:177]
	v_mfma_f32_16x16x32_bf16 v[8:11], v[120:123], v[88:91], v[8:11]
	v_mfma_f32_16x16x32_bf16 v[230:233], v[124:127], v[92:95], v[8:11]
	v_mfma_f32_16x16x32_bf16 v[8:11], v[178:181], v[88:91], v[12:15]
	v_mfma_f32_16x16x32_bf16 v[234:237], v[182:185], v[92:95], v[8:11]
	v_mfma_f32_16x16x32_bf16 v[8:11], v[120:123], v[206:209], v[24:27]
	v_mfma_f32_16x16x32_bf16 v[246:249], v[124:127], v[210:213], v[8:11]
	v_mfma_f32_16x16x32_bf16 v[8:11], v[178:181], v[206:209], v[28:31]
	v_mfma_f32_16x16x32_bf16 v[206:209], v[182:185], v[210:213], v[8:11]
	v_mfma_f32_16x16x32_bf16 v[8:11], v[120:123], v[214:217], v[60:63]
	v_mfma_f32_16x16x32_bf16 v[210:213], v[124:127], v[218:221], v[8:11]
	v_mfma_f32_16x16x32_bf16 v[8:11], v[178:181], v[214:217], v[100:103]
	v_mfma_f32_16x16x32_bf16 v[214:217], v[182:185], v[218:221], v[8:11]
	v_mfma_f32_16x16x32_bf16 v[8:11], v[120:123], v[222:225], v[16:19]
	v_mfma_f32_16x16x32_bf16 v[218:221], v[124:127], v[226:229], v[8:11]
	v_mfma_f32_16x16x32_bf16 v[8:11], v[178:181], v[222:225], v[20:23]
	v_mfma_f32_16x16x32_bf16 v[178:181], v[182:185], v[226:229], v[8:11]
	s_barrier
	s_nop 4
	ds_read_b128 v[8:11], v154
	ds_read_b128 v[12:15], v154 offset:1024
	ds_read_b128 v[16:19], v154 offset:2048
	ds_read_b128 v[20:23], v154 offset:3072
	ds_read_b128 v[182:185], v155
	ds_read_b128 v[222:225], v155 offset:1024
	ds_read_b128 v[226:229], v155 offset:2048
	ds_read_b128 v[142:145], v155 offset:3072
	s_add_u32 s8, s58, 0x200000
	s_addc_u32 s9, s59, 0
	s_mov_b32 m0, s24
	v_lshl_add_u64 v[88:89], s[8:9], 0, v[132:133]
	ds_read_b128 v[24:27], v139 offset:32768
	ds_read_b128 v[28:31], v139 offset:33792
	ds_read_b128 v[60:63], v139 offset:34816
	ds_read_b128 v[146:149], v139 offset:35840
	ds_read_b128 v[150:153], v139 offset:36864
	ds_read_b128 v[154:157], v139 offset:37888
	ds_read_b128 v[200:203], v139 offset:38912
	ds_read_b128 v[186:189], v139 offset:39936
	global_load_lds_dwordx4 v[88:89], off
	v_lshl_add_u64 v[88:89], s[8:9], 0, v[130:131]
	s_mov_b32 m0, s29
	s_nop 0
	global_load_lds_dwordx4 v[88:89], off
	s_waitcnt vmcnt(8)
	s_waitcnt lgkmcnt(0)
	s_barrier
	v_mfma_f32_16x16x32_bf16 v[64:67], v[8:11], v[24:27], v[64:67]
	v_mfma_f32_16x16x32_bf16 v[124:127], v[12:15], v[28:31], v[64:67]
	v_mfma_f32_16x16x32_bf16 v[64:67], v[16:19], v[24:27], v[68:71]
	v_mfma_f32_16x16x32_bf16 v[120:123], v[20:23], v[28:31], v[64:67]
	v_mfma_f32_16x16x32_bf16 v[64:67], v[8:11], v[60:63], v[72:75]
	v_mfma_f32_16x16x32_bf16 v[108:111], v[12:15], v[146:149], v[64:67]
	v_mfma_f32_16x16x32_bf16 v[64:67], v[16:19], v[60:63], v[76:79]
	v_mfma_f32_16x16x32_bf16 v[104:107], v[20:23], v[146:149], v[64:67]
	v_mfma_f32_16x16x32_bf16 v[64:67], v[8:11], v[150:153], v[80:83]
	v_mfma_f32_16x16x32_bf16 v[92:95], v[12:15], v[154:157], v[64:67]
	v_mfma_f32_16x16x32_bf16 v[64:67], v[16:19], v[150:153], v[84:87]
	v_mfma_f32_16x16x32_bf16 v[88:91], v[20:23], v[154:157], v[64:67]
	v_mfma_f32_16x16x32_bf16 v[64:67], v[8:11], v[200:203], v[238:241]
	v_mfma_f32_16x16x32_bf16 v[68:71], v[12:15], v[186:189], v[64:67]
	v_mfma_f32_16x16x32_bf16 v[64:67], v[16:19], v[200:203], v[242:245]
	v_mfma_f32_16x16x32_bf16 v[64:67], v[20:23], v[186:189], v[64:67]
	v_mfma_f32_16x16x32_bf16 v[72:75], v[182:185], v[24:27], v[96:99]
	v_mfma_f32_16x16x32_bf16 v[24:27], v[226:229], v[24:27], v[32:35]
	v_mfma_f32_16x16x32_bf16 v[112:115], v[142:145], v[28:31], v[24:27]
	v_mfma_f32_16x16x32_bf16 v[24:27], v[182:185], v[60:63], v[36:39]
	v_mfma_f32_16x16x32_bf16 v[100:103], v[222:225], v[146:149], v[24:27]
	v_mfma_f32_16x16x32_bf16 v[24:27], v[226:229], v[60:63], v[40:43]
	v_mfma_f32_16x16x32_bf16 v[96:99], v[142:145], v[146:149], v[24:27]
	v_mfma_f32_16x16x32_bf16 v[24:27], v[182:185], v[150:153], v[44:47]
	v_mfma_f32_16x16x32_bf16 v[84:87], v[222:225], v[154:157], v[24:27]
	v_mfma_f32_16x16x32_bf16 v[24:27], v[226:229], v[150:153], v[48:51]
	v_mfma_f32_16x16x32_bf16 v[80:83], v[142:145], v[154:157], v[24:27]
	v_mfma_f32_16x16x32_bf16 v[24:27], v[182:185], v[200:203], v[52:55]
	v_mfma_f32_16x16x32_bf16 v[52:55], v[222:225], v[186:189], v[24:27]
	v_mfma_f32_16x16x32_bf16 v[24:27], v[226:229], v[200:203], v[56:59]
	v_mfma_f32_16x16x32_bf16 v[116:119], v[222:225], v[28:31], v[72:75]
	v_mfma_f32_16x16x32_bf16 v[48:51], v[142:145], v[186:189], v[24:27]
	s_barrier
	s_mov_b32 m0, s73
	s_nop 2
	v_lshl_add_u64 v[24:25], v[190:191], 0, s[36:37]
	s_add_u32 s8, s12, 0x40080
	ds_read_b128 v[32:35], v139 offset:49152
	ds_read_b128 v[36:39], v139 offset:50176
	ds_read_b128 v[146:149], v139 offset:51200
	ds_read_b128 v[150:153], v139 offset:52224
	ds_read_b128 v[154:157], v139 offset:53248
	ds_read_b128 v[186:189], v139 offset:54272
	ds_read_b128 v[200:203], v139 offset:55296
	ds_read_b128 v[238:241], v139 offset:56320
	global_load_lds_dwordx4 v[24:25], off
	v_lshl_add_u64 v[24:25], v[192:193], 0, s[36:37]
	s_mov_b32 m0, s71
	s_addc_u32 s9, s13, 0
	global_load_lds_dwordx4 v[24:25], off
	v_lshl_add_u64 v[24:25], s[8:9], 0, v[140:141]
	s_mov_b32 m0, s10
	s_nop 0
	global_load_lds_dwordx4 v[24:25], off
	v_lshl_add_u64 v[24:25], s[8:9], 0, v[128:129]
	s_mov_b32 m0, s11
	s_nop 0
	global_load_lds_dwordx4 v[24:25], off
	v_lshl_add_u64 v[24:25], v[194:195], 0, s[36:37]
	s_mov_b32 m0, s38
	s_nop 0
	global_load_lds_dwordx4 v[24:25], off
	v_lshl_add_u64 v[24:25], v[196:197], 0, s[36:37]
	s_mov_b32 m0, s60
	s_nop 0
	global_load_lds_dwordx4 v[24:25], off
	s_waitcnt vmcnt(8)
	s_waitcnt lgkmcnt(0)
	s_barrier
	v_mfma_f32_16x16x32_bf16 v[24:27], v[8:11], v[32:35], v[134:137]
	v_mfma_f32_16x16x32_bf16 v[76:79], v[12:15], v[36:39], v[24:27]
	v_mfma_f32_16x16x32_bf16 v[24:27], v[16:19], v[32:35], v[158:161]
	v_mfma_f32_16x16x32_bf16 v[72:75], v[20:23], v[36:39], v[24:27]
	v_mfma_f32_16x16x32_bf16 v[24:27], v[8:11], v[146:149], v[162:165]
	v_mfma_f32_16x16x32_bf16 v[44:47], v[12:15], v[150:153], v[24:27]
	v_mfma_f32_16x16x32_bf16 v[24:27], v[16:19], v[146:149], v[166:169]
	v_mfma_f32_16x16x32_bf16 v[40:43], v[20:23], v[150:153], v[24:27]
	v_mfma_f32_16x16x32_bf16 v[24:27], v[8:11], v[154:157], v[170:173]
	v_mfma_f32_16x16x32_bf16 v[0:3], v[8:11], v[200:203], v[0:3]
	v_mfma_f32_16x16x32_bf16 v[28:31], v[12:15], v[186:189], v[24:27]
	v_mfma_f32_16x16x32_bf16 v[24:27], v[16:19], v[154:157], v[174:177]
	v_mfma_f32_16x16x32_bf16 v[12:15], v[12:15], v[238:241], v[0:3]
	v_mfma_f32_16x16x32_bf16 v[0:3], v[16:19], v[200:203], v[4:7]
	v_mfma_f32_16x16x32_bf16 v[24:27], v[20:23], v[186:189], v[24:27]
	v_mfma_f32_16x16x32_bf16 v[8:11], v[20:23], v[238:241], v[0:3]
	v_mfma_f32_16x16x32_bf16 v[0:3], v[182:185], v[32:35], v[230:233]
	v_mfma_f32_16x16x32_bf16 v[60:63], v[222:225], v[36:39], v[0:3]
	v_mfma_f32_16x16x32_bf16 v[0:3], v[226:229], v[32:35], v[234:237]
	v_mfma_f32_16x16x32_bf16 v[56:59], v[142:145], v[36:39], v[0:3]
	v_mfma_f32_16x16x32_bf16 v[0:3], v[182:185], v[146:149], v[246:249]
	v_mfma_f32_16x16x32_bf16 v[36:39], v[222:225], v[150:153], v[0:3]
	v_mfma_f32_16x16x32_bf16 v[0:3], v[226:229], v[146:149], v[206:209]
	v_mfma_f32_16x16x32_bf16 v[32:35], v[142:145], v[150:153], v[0:3]
	v_mfma_f32_16x16x32_bf16 v[0:3], v[182:185], v[154:157], v[210:213]
	v_mfma_f32_16x16x32_bf16 v[20:23], v[222:225], v[186:189], v[0:3]
	v_mfma_f32_16x16x32_bf16 v[0:3], v[226:229], v[154:157], v[214:217]
	v_mfma_f32_16x16x32_bf16 v[16:19], v[142:145], v[186:189], v[0:3]
	v_mfma_f32_16x16x32_bf16 v[0:3], v[182:185], v[200:203], v[218:221]
	v_mfma_f32_16x16x32_bf16 v[4:7], v[222:225], v[238:241], v[0:3]
	v_mfma_f32_16x16x32_bf16 v[0:3], v[226:229], v[200:203], v[178:181]
	v_mfma_f32_16x16x32_bf16 v[0:3], v[142:145], v[238:241], v[0:3]
	s_barrier
	s_andn2_b64 vcc, exec, s[48:49]
	s_cbranch_vccnz .LBB0_678
	s_barrier

.LBB0_694:
	s_ashr_i32 s48, s54, 4
	s_ashr_i32 s47, s46, 31
	s_ashr_i32 s49, s48, 31
	s_lshl_b64 s[12:13], s[46:47], 19
	s_lshl_b64 s[50:51], s[48:49], 9
	s_add_u32 s12, s4, s12
	s_addc_u32 s13, s5, s13
	s_add_u32 s48, s12, s50
	s_addc_u32 s49, s13, s51
	s_and_b64 s[12:13], s[40:41], exec
	s_cselect_b32 s53, s49, s9
	s_cselect_b32 s52, s48, s8
	s_lshl_b32 s12, s54, 22
	s_and_b32 s12, s12, 0x3c00000
	s_add_u32 s12, s14, s12
	s_addc_u32 s13, s15, 0
	s_add_u32 s50, s12, s50
	s_addc_u32 s51, s13, s51
	s_and_b64 s[12:13], s[40:41], exec
	s_cselect_b32 s13, s51, s11
	s_cselect_b32 s12, s50, s10
	s_add_i32 s47, 0, 0x10000
	s_add_i32 s57, 0, 0x14000
	v_add_u32_e32 v140, s47, v138
	v_add_u32_e32 v198, s57, v138
	ds_read_b128 v[0:3], v140
	ds_read_b128 v[4:7], v140 offset:1024
	ds_read_b128 v[8:11], v140 offset:2048
	ds_read_b128 v[12:15], v140 offset:3072
	ds_read_b128 v[16:19], v198
	ds_read_b128 v[20:23], v198 offset:1024
	ds_read_b128 v[24:27], v198 offset:2048
	ds_read_b128 v[28:31], v198 offset:3072
	v_mov_b32_e32 v252, 0x358637bd
	s_add_u32 s58, s8, 0x40080
	s_addc_u32 s59, s9, 0
	s_add_i32 s61, s25, 0xc000
	v_lshl_add_u64 v[64:65], s[58:59], 0, v[134:135]
	s_mov_b32 m0, s61
	s_add_i32 s35, s25, 0xe000
	ds_read_b128 v[32:35], v139
	ds_read_b128 v[36:39], v139 offset:1024
	ds_read_b128 v[40:43], v139 offset:2048
	ds_read_b128 v[44:47], v139 offset:3072
	ds_read_b128 v[48:51], v139 offset:4096
	ds_read_b128 v[52:55], v139 offset:5120
	ds_read_b128 v[56:59], v139 offset:6144
	ds_read_b128 v[60:63], v139 offset:7168
	global_load_lds_dwordx4 v[64:65], off
	v_lshl_add_u64 v[64:65], s[58:59], 0, v[130:131]
	s_mov_b32 m0, s35
	s_nop 0
	global_load_lds_dwordx4 v[64:65], off
	s_waitcnt vmcnt(8)
	s_waitcnt lgkmcnt(0)
	s_barrier
	v_mfma_f32_16x16x32_bf16 v[64:67], v[0:3], v[32:35], 0
	v_mfma_f32_16x16x32_bf16 v[68:71], v[8:11], v[32:35], 0
	v_mfma_f32_16x16x32_bf16 v[72:75], v[0:3], v[40:43], 0
	v_mfma_f32_16x16x32_bf16 v[76:79], v[8:11], v[40:43], 0
	v_mfma_f32_16x16x32_bf16 v[80:83], v[0:3], v[48:51], 0
	v_mfma_f32_16x16x32_bf16 v[84:87], v[8:11], v[48:51], 0
	v_mfma_f32_16x16x32_bf16 v[88:91], v[0:3], v[56:59], 0
	v_mfma_f32_16x16x32_bf16 v[92:95], v[8:11], v[56:59], 0
	v_mfma_f32_16x16x32_bf16 v[64:67], v[4:7], v[36:39], v[64:67]
	v_mfma_f32_16x16x32_bf16 v[68:71], v[12:15], v[36:39], v[68:71]
	v_mfma_f32_16x16x32_bf16 v[72:75], v[4:7], v[44:47], v[72:75]
	v_mfma_f32_16x16x32_bf16 v[76:79], v[12:15], v[44:47], v[76:79]
	v_mfma_f32_16x16x32_bf16 v[80:83], v[4:7], v[52:55], v[80:83]
	v_mfma_f32_16x16x32_bf16 v[84:87], v[12:15], v[52:55], v[84:87]
	v_mfma_f32_16x16x32_bf16 v[88:91], v[4:7], v[60:63], v[88:91]
	v_mfma_f32_16x16x32_bf16 v[92:95], v[12:15], v[60:63], v[92:95]
	v_mfma_f32_16x16x32_bf16 v[96:99], v[16:19], v[32:35], 0
	v_mfma_f32_16x16x32_bf16 v[32:35], v[24:27], v[32:35], 0
	v_mfma_f32_16x16x32_bf16 v[96:99], v[20:23], v[36:39], v[96:99]
	v_mfma_f32_16x16x32_bf16 v[32:35], v[28:31], v[36:39], v[32:35]
	v_mfma_f32_16x16x32_bf16 v[36:39], v[16:19], v[40:43], 0
	v_mfma_f32_16x16x32_bf16 v[40:43], v[24:27], v[40:43], 0
	v_mfma_f32_16x16x32_bf16 v[36:39], v[20:23], v[44:47], v[36:39]
	v_mfma_f32_16x16x32_bf16 v[40:43], v[28:31], v[44:47], v[40:43]
	v_mfma_f32_16x16x32_bf16 v[44:47], v[16:19], v[48:51], 0
	v_mfma_f32_16x16x32_bf16 v[48:51], v[24:27], v[48:51], 0
	v_mfma_f32_16x16x32_bf16 v[44:47], v[20:23], v[52:55], v[44:47]
	v_mfma_f32_16x16x32_bf16 v[48:51], v[28:31], v[52:55], v[48:51]
	v_mfma_f32_16x16x32_bf16 v[52:55], v[16:19], v[56:59], 0
	v_mfma_f32_16x16x32_bf16 v[56:59], v[24:27], v[56:59], 0
	v_mfma_f32_16x16x32_bf16 v[52:55], v[20:23], v[60:63], v[52:55]
	v_mfma_f32_16x16x32_bf16 v[56:59], v[28:31], v[60:63], v[56:59]
	s_barrier
	s_add_i32 s59, s47, s24
	v_lshl_add_u64 v[136:137], s[10:11], 0, v[132:133]
	s_mov_b64 s[68:69], 0x100
	s_add_i32 s47, s59, 0x2000
	v_lshl_add_u64 v[142:143], v[136:137], 0, s[68:69]
	s_mov_b32 m0, s59
	v_lshl_add_u64 v[190:191], s[10:11], 0, v[128:129]
	s_add_u32 s66, s10, 0x200100
	ds_read_b128 v[60:63], v139 offset:16384
	ds_read_b128 v[100:103], v139 offset:17408
	ds_read_b128 v[104:107], v139 offset:18432
	ds_read_b128 v[108:111], v139 offset:19456
	ds_read_b128 v[112:115], v139 offset:20480
	ds_read_b128 v[116:119], v139 offset:21504
	ds_read_b128 v[120:123], v139 offset:22528
	ds_read_b128 v[124:127], v139 offset:23552
	global_load_lds_dwordx4 v[142:143], off
	v_lshl_add_u64 v[142:143], v[190:191], 0, s[68:69]
	s_mov_b32 m0, s47
	s_addc_u32 s67, s11, 0
	s_add_i32 s57, s57, s24
	global_load_lds_dwordx4 v[142:143], off
	v_lshl_add_u64 v[142:143], s[66:67], 0, v[132:133]
	s_mov_b32 m0, s57
	s_add_i32 s58, s57, 0x2000
	global_load_lds_dwordx4 v[142:143], off
	v_lshl_add_u64 v[142:143], s[66:67], 0, v[128:129]
	s_mov_b32 m0, s58
	v_lshl_add_u64 v[192:193], s[8:9], 0, v[134:135]
	global_load_lds_dwordx4 v[142:143], off
	v_lshl_add_u64 v[142:143], v[192:193], 0, s[68:69]
	s_mov_b32 m0, s25
	v_lshl_add_u64 v[194:195], s[8:9], 0, v[130:131]
	global_load_lds_dwordx4 v[142:143], off
	v_lshl_add_u64 v[142:143], v[194:195], 0, s[68:69]
	s_mov_b32 m0, s26
	s_nop 0
	global_load_lds_dwordx4 v[142:143], off
	s_waitcnt vmcnt(8)
	s_waitcnt lgkmcnt(0)
	s_barrier
	v_mfma_f32_16x16x32_bf16 v[142:145], v[0:3], v[60:63], 0
	v_mfma_f32_16x16x32_bf16 v[150:153], v[0:3], v[104:107], 0
	v_mfma_f32_16x16x32_bf16 v[158:161], v[0:3], v[112:115], 0
	v_mfma_f32_16x16x32_bf16 v[0:3], v[0:3], v[120:123], 0
	v_mfma_f32_16x16x32_bf16 v[142:145], v[4:7], v[100:103], v[142:145]
	v_mfma_f32_16x16x32_bf16 v[150:153], v[4:7], v[108:111], v[150:153]
	v_mfma_f32_16x16x32_bf16 v[158:161], v[4:7], v[116:119], v[158:161]
	v_mfma_f32_16x16x32_bf16 v[0:3], v[4:7], v[124:127], v[0:3]
	v_mfma_f32_16x16x32_bf16 v[4:7], v[8:11], v[120:123], 0
	v_mfma_f32_16x16x32_bf16 v[146:149], v[8:11], v[60:63], 0
	v_mfma_f32_16x16x32_bf16 v[154:157], v[8:11], v[104:107], 0
	v_mfma_f32_16x16x32_bf16 v[162:165], v[8:11], v[112:115], 0
	v_mfma_f32_16x16x32_bf16 v[4:7], v[12:15], v[124:127], v[4:7]
	v_mfma_f32_16x16x32_bf16 v[146:149], v[12:15], v[100:103], v[146:149]
	v_mfma_f32_16x16x32_bf16 v[154:157], v[12:15], v[108:111], v[154:157]
	v_mfma_f32_16x16x32_bf16 v[162:165], v[12:15], v[116:119], v[162:165]
	v_mfma_f32_16x16x32_bf16 v[8:11], v[16:19], v[60:63], 0
	v_mfma_f32_16x16x32_bf16 v[12:15], v[24:27], v[60:63], 0
	v_mfma_f32_16x16x32_bf16 v[8:11], v[20:23], v[100:103], v[8:11]
	v_mfma_f32_16x16x32_bf16 v[12:15], v[28:31], v[100:103], v[12:15]
	v_mfma_f32_16x16x32_bf16 v[60:63], v[16:19], v[104:107], 0
	v_mfma_f32_16x16x32_bf16 v[100:103], v[24:27], v[104:107], 0
	v_mfma_f32_16x16x32_bf16 v[104:107], v[16:19], v[112:115], 0
	v_mfma_f32_16x16x32_bf16 v[16:19], v[16:19], v[120:123], 0
	v_mfma_f32_16x16x32_bf16 v[60:63], v[20:23], v[108:111], v[60:63]
	v_mfma_f32_16x16x32_bf16 v[100:103], v[28:31], v[108:111], v[100:103]
	v_mfma_f32_16x16x32_bf16 v[104:107], v[20:23], v[116:119], v[104:107]
	v_mfma_f32_16x16x32_bf16 v[108:111], v[24:27], v[112:115], 0
	v_mfma_f32_16x16x32_bf16 v[16:19], v[20:23], v[124:127], v[16:19]
	v_mfma_f32_16x16x32_bf16 v[20:23], v[24:27], v[120:123], 0
	v_mfma_f32_16x16x32_bf16 v[108:111], v[28:31], v[116:119], v[108:111]
	v_mfma_f32_16x16x32_bf16 v[20:23], v[28:31], v[124:127], v[20:23]
	s_barrier
	s_add_i32 s60, 0, 0x18000
	s_add_i32 s70, 0, 0x1c000
	v_add_u32_e32 v230, s60, v138
	v_add_u32_e32 v238, s70, v138
	ds_read_b128 v[24:27], v230
	ds_read_b128 v[28:31], v230 offset:1024
	ds_read_b128 v[112:115], v230 offset:2048
	ds_read_b128 v[116:119], v230 offset:3072
	ds_read_b128 v[120:123], v238
	ds_read_b128 v[124:127], v238 offset:1024
	ds_read_b128 v[166:169], v238 offset:2048
	ds_read_b128 v[170:173], v238 offset:3072
	s_add_u32 s66, s8, 0x40100
	s_addc_u32 s67, s9, 0
	s_mov_b32 m0, s27
	v_lshl_add_u64 v[196:197], s[66:67], 0, v[134:135]
	ds_read_b128 v[174:177], v139 offset:32768
	ds_read_b128 v[178:181], v139 offset:33792
	ds_read_b128 v[182:185], v139 offset:34816
	ds_read_b128 v[186:189], v139 offset:35840
	ds_read_b128 v[200:203], v139 offset:36864
	ds_read_b128 v[206:209], v139 offset:37888
	ds_read_b128 v[210:213], v139 offset:38912
	ds_read_b128 v[214:217], v139 offset:39936
	global_load_lds_dwordx4 v[196:197], off
	v_lshl_add_u64 v[196:197], s[66:67], 0, v[130:131]
	s_mov_b32 m0, s28
	s_nop 0
	global_load_lds_dwordx4 v[196:197], off
	s_waitcnt vmcnt(8)
	s_waitcnt lgkmcnt(0)
	s_barrier
	v_mfma_f32_16x16x32_bf16 v[64:67], v[24:27], v[174:177], v[64:67]
	v_mfma_f32_16x16x32_bf16 v[68:71], v[112:115], v[174:177], v[68:71]
	v_mfma_f32_16x16x32_bf16 v[72:75], v[24:27], v[182:185], v[72:75]
	v_mfma_f32_16x16x32_bf16 v[76:79], v[112:115], v[182:185], v[76:79]
	v_mfma_f32_16x16x32_bf16 v[80:83], v[24:27], v[200:203], v[80:83]
	v_mfma_f32_16x16x32_bf16 v[84:87], v[112:115], v[200:203], v[84:87]
	v_mfma_f32_16x16x32_bf16 v[88:91], v[24:27], v[210:213], v[88:91]
	v_mfma_f32_16x16x32_bf16 v[92:95], v[112:115], v[210:213], v[92:95]
	v_mfma_f32_16x16x32_bf16 v[64:67], v[28:31], v[178:181], v[64:67]
	v_mfma_f32_16x16x32_bf16 v[68:71], v[116:119], v[178:181], v[68:71]
	v_mfma_f32_16x16x32_bf16 v[72:75], v[28:31], v[186:189], v[72:75]
	v_mfma_f32_16x16x32_bf16 v[76:79], v[116:119], v[186:189], v[76:79]
	v_mfma_f32_16x16x32_bf16 v[80:83], v[28:31], v[206:209], v[80:83]
	v_mfma_f32_16x16x32_bf16 v[84:87], v[116:119], v[206:209], v[84:87]
	v_mfma_f32_16x16x32_bf16 v[88:91], v[28:31], v[214:217], v[88:91]
	v_mfma_f32_16x16x32_bf16 v[92:95], v[116:119], v[214:217], v[92:95]
	v_mfma_f32_16x16x32_bf16 v[96:99], v[120:123], v[174:177], v[96:99]
	v_mfma_f32_16x16x32_bf16 v[32:35], v[166:169], v[174:177], v[32:35]
	v_mfma_f32_16x16x32_bf16 v[36:39], v[120:123], v[182:185], v[36:39]
	v_mfma_f32_16x16x32_bf16 v[40:43], v[166:169], v[182:185], v[40:43]
	v_mfma_f32_16x16x32_bf16 v[44:47], v[120:123], v[200:203], v[44:47]
	v_mfma_f32_16x16x32_bf16 v[48:51], v[166:169], v[200:203], v[48:51]
	v_mfma_f32_16x16x32_bf16 v[52:55], v[120:123], v[210:213], v[52:55]
	v_mfma_f32_16x16x32_bf16 v[56:59], v[166:169], v[210:213], v[56:59]
	v_mfma_f32_16x16x32_bf16 v[96:99], v[124:127], v[178:181], v[96:99]
	v_mfma_f32_16x16x32_bf16 v[32:35], v[170:173], v[178:181], v[32:35]
	v_mfma_f32_16x16x32_bf16 v[36:39], v[124:127], v[186:189], v[36:39]
	v_mfma_f32_16x16x32_bf16 v[40:43], v[170:173], v[186:189], v[40:43]
	v_mfma_f32_16x16x32_bf16 v[44:47], v[124:127], v[206:209], v[44:47]
	v_mfma_f32_16x16x32_bf16 v[48:51], v[170:173], v[206:209], v[48:51]
	v_mfma_f32_16x16x32_bf16 v[52:55], v[124:127], v[214:217], v[52:55]
	v_mfma_f32_16x16x32_bf16 v[56:59], v[170:173], v[214:217], v[56:59]
	s_barrier
	s_add_i32 s66, s60, s24
	s_mov_b64 s[74:75], 0x180
	s_add_i32 s60, s66, 0x2000
	v_lshl_add_u64 v[136:137], v[136:137], 0, s[74:75]
	s_mov_b32 m0, s66
	s_add_u32 s68, s10, 0x200180
	ds_read_b128 v[174:177], v139 offset:49152
	ds_read_b128 v[178:181], v139 offset:50176
	ds_read_b128 v[182:185], v139 offset:51200
	ds_read_b128 v[186:189], v139 offset:52224
	ds_read_b128 v[200:203], v139 offset:53248
	ds_read_b128 v[206:209], v139 offset:54272
	ds_read_b128 v[210:213], v139 offset:55296
	ds_read_b128 v[214:217], v139 offset:56320
	global_load_lds_dwordx4 v[136:137], off
	v_lshl_add_u64 v[136:137], v[190:191], 0, s[74:75]
	s_mov_b32 m0, s60
	s_addc_u32 s69, s11, 0
	s_add_i32 s10, s70, s24
	global_load_lds_dwordx4 v[136:137], off
	v_lshl_add_u64 v[136:137], s[68:69], 0, v[132:133]
	s_mov_b32 m0, s10
	s_add_i32 s11, s10, 0x2000
	global_load_lds_dwordx4 v[136:137], off
	v_lshl_add_u64 v[136:137], s[68:69], 0, v[128:129]
	s_mov_b32 m0, s11
	s_nop 0
	global_load_lds_dwordx4 v[136:137], off
	v_lshl_add_u64 v[136:137], v[192:193], 0, s[74:75]
	s_mov_b32 m0, s29
	s_nop 0
	global_load_lds_dwordx4 v[136:137], off
	v_lshl_add_u64 v[136:137], v[194:195], 0, s[74:75]
	s_mov_b32 m0, s38
	s_nop 0
	global_load_lds_dwordx4 v[136:137], off
	s_waitcnt vmcnt(8)
	s_waitcnt lgkmcnt(0)
	s_barrier
	v_mfma_f32_16x16x32_bf16 v[0:3], v[24:27], v[210:213], v[0:3]
	v_mfma_f32_16x16x32_bf16 v[4:7], v[112:115], v[210:213], v[4:7]
	v_mfma_f32_16x16x32_bf16 v[142:145], v[24:27], v[174:177], v[142:145]
	v_mfma_f32_16x16x32_bf16 v[146:149], v[112:115], v[174:177], v[146:149]
	v_mfma_f32_16x16x32_bf16 v[150:153], v[24:27], v[182:185], v[150:153]
	v_mfma_f32_16x16x32_bf16 v[154:157], v[112:115], v[182:185], v[154:157]
	v_mfma_f32_16x16x32_bf16 v[158:161], v[24:27], v[200:203], v[158:161]
	v_mfma_f32_16x16x32_bf16 v[162:165], v[112:115], v[200:203], v[162:165]
	v_mfma_f32_16x16x32_bf16 v[0:3], v[28:31], v[214:217], v[0:3]
	v_mfma_f32_16x16x32_bf16 v[4:7], v[116:119], v[214:217], v[4:7]
	v_mfma_f32_16x16x32_bf16 v[142:145], v[28:31], v[178:181], v[142:145]
	v_mfma_f32_16x16x32_bf16 v[146:149], v[116:119], v[178:181], v[146:149]
	v_mfma_f32_16x16x32_bf16 v[150:153], v[28:31], v[186:189], v[150:153]
	v_mfma_f32_16x16x32_bf16 v[154:157], v[116:119], v[186:189], v[154:157]
	v_mfma_f32_16x16x32_bf16 v[158:161], v[28:31], v[206:209], v[158:161]
	v_mfma_f32_16x16x32_bf16 v[162:165], v[116:119], v[206:209], v[162:165]
	v_mfma_f32_16x16x32_bf16 v[8:11], v[120:123], v[174:177], v[8:11]
	v_mfma_f32_16x16x32_bf16 v[12:15], v[166:169], v[174:177], v[12:15]
	v_mfma_f32_16x16x32_bf16 v[24:27], v[120:123], v[182:185], v[60:63]
	v_mfma_f32_16x16x32_bf16 v[28:31], v[166:169], v[182:185], v[100:103]
	v_mfma_f32_16x16x32_bf16 v[60:63], v[120:123], v[200:203], v[104:107]
	v_mfma_f32_16x16x32_bf16 v[100:103], v[166:169], v[200:203], v[108:111]
	v_mfma_f32_16x16x32_bf16 v[16:19], v[120:123], v[210:213], v[16:19]
	v_mfma_f32_16x16x32_bf16 v[20:23], v[166:169], v[210:213], v[20:23]
	v_mfma_f32_16x16x32_bf16 v[8:11], v[124:127], v[178:181], v[8:11]
	v_mfma_f32_16x16x32_bf16 v[12:15], v[170:173], v[178:181], v[12:15]
	v_mfma_f32_16x16x32_bf16 v[24:27], v[124:127], v[186:189], v[24:27]
	v_mfma_f32_16x16x32_bf16 v[28:31], v[170:173], v[186:189], v[28:31]
	v_mfma_f32_16x16x32_bf16 v[60:63], v[124:127], v[206:209], v[60:63]
	v_mfma_f32_16x16x32_bf16 v[100:103], v[170:173], v[206:209], v[100:103]
	v_mfma_f32_16x16x32_bf16 v[16:19], v[124:127], v[214:217], v[16:19]
	v_mfma_f32_16x16x32_bf16 v[20:23], v[170:173], v[214:217], v[20:23]
	s_barrier
	ds_read_b128 v[104:107], v140
	ds_read_b128 v[108:111], v140 offset:1024
	ds_read_b128 v[112:115], v140 offset:2048
	ds_read_b128 v[116:119], v140 offset:3072
	ds_read_b128 v[120:123], v198
	ds_read_b128 v[124:127], v198 offset:1024
	ds_read_b128 v[166:169], v198 offset:2048
	ds_read_b128 v[170:173], v198 offset:3072
	s_add_u32 s8, s8, 0x40180
	s_addc_u32 s9, s9, 0
	s_mov_b32 m0, s61
	v_lshl_add_u64 v[136:137], s[8:9], 0, v[134:135]
	ds_read_b128 v[174:177], v139
	ds_read_b128 v[178:181], v139 offset:1024
	ds_read_b128 v[182:185], v139 offset:2048
	ds_read_b128 v[186:189], v139 offset:3072
	ds_read_b128 v[200:203], v139 offset:4096
	ds_read_b128 v[206:209], v139 offset:5120
	ds_read_b128 v[210:213], v139 offset:6144
	ds_read_b128 v[214:217], v139 offset:7168
	global_load_lds_dwordx4 v[136:137], off
	v_lshl_add_u64 v[136:137], s[8:9], 0, v[130:131]
	s_mov_b32 m0, s35
	s_nop 0
	global_load_lds_dwordx4 v[136:137], off
	s_waitcnt vmcnt(8)
	s_waitcnt lgkmcnt(0)
	s_barrier
	v_mfma_f32_16x16x32_bf16 v[88:91], v[104:107], v[210:213], v[88:91]
	v_mfma_f32_16x16x32_bf16 v[64:67], v[104:107], v[174:177], v[64:67]
	v_mfma_f32_16x16x32_bf16 v[68:71], v[112:115], v[174:177], v[68:71]
	v_mfma_f32_16x16x32_bf16 v[72:75], v[104:107], v[182:185], v[72:75]
	v_mfma_f32_16x16x32_bf16 v[76:79], v[112:115], v[182:185], v[76:79]
	v_mfma_f32_16x16x32_bf16 v[80:83], v[104:107], v[200:203], v[80:83]
	v_mfma_f32_16x16x32_bf16 v[84:87], v[112:115], v[200:203], v[84:87]
	v_mfma_f32_16x16x32_bf16 v[218:221], v[108:111], v[214:217], v[88:91]
	v_mfma_f32_16x16x32_bf16 v[88:91], v[112:115], v[210:213], v[92:95]
	v_mfma_f32_16x16x32_bf16 v[64:67], v[108:111], v[178:181], v[64:67]
	v_mfma_f32_16x16x32_bf16 v[68:71], v[116:119], v[178:181], v[68:71]
	v_mfma_f32_16x16x32_bf16 v[72:75], v[108:111], v[186:189], v[72:75]
	v_mfma_f32_16x16x32_bf16 v[76:79], v[116:119], v[186:189], v[76:79]
	v_mfma_f32_16x16x32_bf16 v[80:83], v[108:111], v[206:209], v[80:83]
	v_mfma_f32_16x16x32_bf16 v[84:87], v[116:119], v[206:209], v[84:87]
	v_mfma_f32_16x16x32_bf16 v[92:95], v[116:119], v[214:217], v[88:91]
	v_mfma_f32_16x16x32_bf16 v[48:51], v[166:169], v[200:203], v[48:51]
	v_mfma_f32_16x16x32_bf16 v[88:91], v[120:123], v[174:177], v[96:99]
	v_mfma_f32_16x16x32_bf16 v[32:35], v[166:169], v[174:177], v[32:35]
	v_mfma_f32_16x16x32_bf16 v[36:39], v[120:123], v[182:185], v[36:39]
	v_mfma_f32_16x16x32_bf16 v[40:43], v[166:169], v[182:185], v[40:43]
	v_mfma_f32_16x16x32_bf16 v[44:47], v[120:123], v[200:203], v[44:47]
	v_mfma_f32_16x16x32_bf16 v[174:177], v[170:173], v[206:209], v[48:51]
	v_mfma_f32_16x16x32_bf16 v[48:51], v[120:123], v[210:213], v[52:55]
	v_mfma_f32_16x16x32_bf16 v[32:35], v[170:173], v[178:181], v[32:35]
	v_mfma_f32_16x16x32_bf16 v[36:39], v[124:127], v[186:189], v[36:39]
	v_mfma_f32_16x16x32_bf16 v[40:43], v[170:173], v[186:189], v[40:43]
	v_mfma_f32_16x16x32_bf16 v[44:47], v[124:127], v[206:209], v[44:47]
	v_mfma_f32_16x16x32_bf16 v[52:55], v[124:127], v[214:217], v[48:51]
	v_mfma_f32_16x16x32_bf16 v[48:51], v[166:169], v[210:213], v[56:59]
	v_mfma_f32_16x16x32_bf16 v[222:225], v[124:127], v[178:181], v[88:91]
	v_mfma_f32_16x16x32_bf16 v[178:181], v[170:173], v[214:217], v[48:51]
	s_barrier
	s_mov_b32 m0, s59
	v_lshl_add_u64 v[136:137], s[12:13], 0, v[132:133]
	s_add_u32 s8, s12, 0x200000
	s_nop 0
	ds_read_b128 v[48:51], v139 offset:16384
	ds_read_b128 v[56:59], v139 offset:17408
	ds_read_b128 v[88:91], v139 offset:18432
	ds_read_b128 v[96:99], v139 offset:19456
	ds_read_b128 v[182:185], v139 offset:20480
	ds_read_b128 v[186:189], v139 offset:21504
	ds_read_b128 v[200:203], v139 offset:22528
	ds_read_b128 v[206:209], v139 offset:23552
	global_load_lds_dwordx4 v[136:137], off
	v_lshl_add_u64 v[204:205], s[12:13], 0, v[128:129]
	s_mov_b32 m0, s47
	s_addc_u32 s9, s13, 0
	global_load_lds_dwordx4 v[204:205], off
	v_lshl_add_u64 v[190:191], s[8:9], 0, v[132:133]
	s_mov_b32 m0, s57
	v_lshl_add_u64 v[250:251], s[52:53], 0, v[134:135]
	global_load_lds_dwordx4 v[190:191], off
	v_lshl_add_u64 v[190:191], s[8:9], 0, v[128:129]
	s_mov_b32 m0, s58
	v_lshl_add_u64 v[198:199], s[52:53], 0, v[130:131]
	global_load_lds_dwordx4 v[190:191], off
	s_mov_b32 m0, s25
	s_nop 0
	global_load_lds_dwordx4 v[250:251], off
	s_mov_b32 m0, s26
	s_nop 0
	global_load_lds_dwordx4 v[198:199], off
	s_waitcnt vmcnt(8)
	s_waitcnt lgkmcnt(0)
	s_barrier
	v_mfma_f32_16x16x32_bf16 v[0:3], v[104:107], v[200:203], v[0:3]
	v_mfma_f32_16x16x32_bf16 v[4:7], v[112:115], v[200:203], v[4:7]
	v_mfma_f32_16x16x32_bf16 v[142:145], v[104:107], v[48:51], v[142:145]
	v_mfma_f32_16x16x32_bf16 v[146:149], v[112:115], v[48:51], v[146:149]
	v_mfma_f32_16x16x32_bf16 v[150:153], v[104:107], v[88:91], v[150:153]
	v_mfma_f32_16x16x32_bf16 v[154:157], v[112:115], v[88:91], v[154:157]
	v_mfma_f32_16x16x32_bf16 v[158:161], v[104:107], v[182:185], v[158:161]
	v_mfma_f32_16x16x32_bf16 v[162:165], v[112:115], v[182:185], v[162:165]
	v_mfma_f32_16x16x32_bf16 v[0:3], v[108:111], v[206:209], v[0:3]
	v_mfma_f32_16x16x32_bf16 v[4:7], v[116:119], v[206:209], v[4:7]
	v_mfma_f32_16x16x32_bf16 v[142:145], v[108:111], v[56:59], v[142:145]
	v_mfma_f32_16x16x32_bf16 v[146:149], v[116:119], v[56:59], v[146:149]
	v_mfma_f32_16x16x32_bf16 v[150:153], v[108:111], v[96:99], v[150:153]
	v_mfma_f32_16x16x32_bf16 v[154:157], v[116:119], v[96:99], v[154:157]
	v_mfma_f32_16x16x32_bf16 v[158:161], v[108:111], v[186:189], v[158:161]
	v_mfma_f32_16x16x32_bf16 v[162:165], v[116:119], v[186:189], v[162:165]
	v_mfma_f32_16x16x32_bf16 v[12:15], v[166:169], v[48:51], v[12:15]
	v_mfma_f32_16x16x32_bf16 v[210:213], v[170:173], v[56:59], v[12:15]
	v_mfma_f32_16x16x32_bf16 v[12:15], v[120:123], v[88:91], v[24:27]
	v_mfma_f32_16x16x32_bf16 v[24:27], v[124:127], v[96:99], v[12:15]
	v_mfma_f32_16x16x32_bf16 v[12:15], v[166:169], v[88:91], v[28:31]
	v_mfma_f32_16x16x32_bf16 v[214:217], v[170:173], v[96:99], v[12:15]
	v_mfma_f32_16x16x32_bf16 v[12:15], v[120:123], v[182:185], v[60:63]
	v_mfma_f32_16x16x32_bf16 v[226:229], v[124:127], v[186:189], v[12:15]
	v_mfma_f32_16x16x32_bf16 v[12:15], v[166:169], v[182:185], v[100:103]
	v_mfma_f32_16x16x32_bf16 v[8:11], v[120:123], v[48:51], v[8:11]
	v_mfma_f32_16x16x32_bf16 v[182:185], v[170:173], v[186:189], v[12:15]
	v_mfma_f32_16x16x32_bf16 v[12:15], v[120:123], v[200:203], v[16:19]
	v_mfma_f32_16x16x32_bf16 v[8:11], v[124:127], v[56:59], v[8:11]
	v_mfma_f32_16x16x32_bf16 v[186:189], v[124:127], v[206:209], v[12:15]
	v_mfma_f32_16x16x32_bf16 v[12:15], v[166:169], v[200:203], v[20:23]
	v_mfma_f32_16x16x32_bf16 v[166:169], v[170:173], v[206:209], v[12:15]
	s_barrier
	s_nop 4
	ds_read_b128 v[12:15], v230
	ds_read_b128 v[16:19], v230 offset:1024
	ds_read_b128 v[170:173], v230 offset:2048
	ds_read_b128 v[200:203], v230 offset:3072
	ds_read_b128 v[206:209], v238
	ds_read_b128 v[230:233], v238 offset:1024
	ds_read_b128 v[234:237], v238 offset:2048
	ds_read_b128 v[238:241], v238 offset:3072
	s_add_u32 s8, s52, 0x40000
	s_addc_u32 s9, s53, 0
	s_mov_b32 m0, s27
	v_lshl_add_u64 v[48:49], s[8:9], 0, v[134:135]
	ds_read_b128 v[20:23], v139 offset:32768
	ds_read_b128 v[28:31], v139 offset:33792
	ds_read_b128 v[60:63], v139 offset:34816
	ds_read_b128 v[100:103], v139 offset:35840
	ds_read_b128 v[242:245], v139 offset:36864
	ds_read_b128 v[246:249], v139 offset:37888
	ds_read_b128 v[190:193], v139 offset:38912
	ds_read_b128 v[194:197], v139 offset:39936
	global_load_lds_dwordx4 v[48:49], off
	v_lshl_add_u64 v[48:49], s[8:9], 0, v[130:131]
	s_mov_b32 m0, s28
	s_nop 0
	global_load_lds_dwordx4 v[48:49], off
	s_waitcnt vmcnt(8)
	s_waitcnt lgkmcnt(0)
	s_barrier
	v_mfma_f32_16x16x32_bf16 v[48:51], v[12:15], v[20:23], v[64:67]
	v_mfma_f32_16x16x32_bf16 v[120:123], v[16:19], v[28:31], v[48:51]
	v_mfma_f32_16x16x32_bf16 v[48:51], v[170:173], v[20:23], v[68:71]
	v_mfma_f32_16x16x32_bf16 v[112:115], v[200:203], v[28:31], v[48:51]
	v_mfma_f32_16x16x32_bf16 v[48:51], v[12:15], v[60:63], v[72:75]
	v_mfma_f32_16x16x32_bf16 v[104:107], v[16:19], v[100:103], v[48:51]
	v_mfma_f32_16x16x32_bf16 v[48:51], v[170:173], v[60:63], v[76:79]
	v_mfma_f32_16x16x32_bf16 v[96:99], v[200:203], v[100:103], v[48:51]
	v_mfma_f32_16x16x32_bf16 v[48:51], v[12:15], v[242:245], v[80:83]
	v_mfma_f32_16x16x32_bf16 v[88:91], v[16:19], v[246:249], v[48:51]
	v_mfma_f32_16x16x32_bf16 v[48:51], v[170:173], v[242:245], v[84:87]
	v_mfma_f32_16x16x32_bf16 v[80:83], v[200:203], v[246:249], v[48:51]
	v_mfma_f32_16x16x32_bf16 v[48:51], v[12:15], v[190:193], v[218:221]
	v_mfma_f32_16x16x32_bf16 v[56:59], v[16:19], v[194:197], v[48:51]
	v_mfma_f32_16x16x32_bf16 v[48:51], v[170:173], v[190:193], v[92:95]
	v_mfma_f32_16x16x32_bf16 v[48:51], v[200:203], v[194:197], v[48:51]
	v_mfma_f32_16x16x32_bf16 v[64:67], v[206:209], v[20:23], v[222:225]
	v_mfma_f32_16x16x32_bf16 v[20:23], v[234:237], v[20:23], v[32:35]
	v_mfma_f32_16x16x32_bf16 v[116:119], v[238:241], v[28:31], v[20:23]
	v_mfma_f32_16x16x32_bf16 v[20:23], v[206:209], v[60:63], v[36:39]
	v_mfma_f32_16x16x32_bf16 v[108:111], v[230:233], v[100:103], v[20:23]
	v_mfma_f32_16x16x32_bf16 v[20:23], v[234:237], v[60:63], v[40:43]
	v_mfma_f32_16x16x32_bf16 v[100:103], v[238:241], v[100:103], v[20:23]
	v_mfma_f32_16x16x32_bf16 v[20:23], v[206:209], v[242:245], v[44:47]
	v_mfma_f32_16x16x32_bf16 v[92:95], v[230:233], v[246:249], v[20:23]
	v_mfma_f32_16x16x32_bf16 v[20:23], v[234:237], v[242:245], v[174:177]
	v_mfma_f32_16x16x32_bf16 v[84:87], v[238:241], v[246:249], v[20:23]
	v_mfma_f32_16x16x32_bf16 v[20:23], v[206:209], v[190:193], v[52:55]
	v_mfma_f32_16x16x32_bf16 v[60:63], v[230:233], v[194:197], v[20:23]
	v_mfma_f32_16x16x32_bf16 v[20:23], v[234:237], v[190:193], v[178:181]
	v_mfma_f32_16x16x32_bf16 v[124:127], v[230:233], v[28:31], v[64:67]
	v_mfma_f32_16x16x32_bf16 v[52:55], v[238:241], v[194:197], v[20:23]
	s_barrier
	s_mov_b32 m0, s66
	s_nop 2
	v_lshl_add_u64 v[20:21], v[136:137], 0, s[36:37]
	s_add_u32 s8, s12, 0x200080
	ds_read_b128 v[32:35], v139 offset:49152
	ds_read_b128 v[40:43], v139 offset:50176
	ds_read_b128 v[174:177], v139 offset:51200
	ds_read_b128 v[178:181], v139 offset:52224
	ds_read_b128 v[190:193], v139 offset:53248
	ds_read_b128 v[194:197], v139 offset:54272
	ds_read_b128 v[218:221], v139 offset:55296
	ds_read_b128 v[222:225], v139 offset:56320
	global_load_lds_dwordx4 v[20:21], off
	v_lshl_add_u64 v[20:21], v[204:205], 0, s[36:37]
	s_mov_b32 m0, s60
	s_addc_u32 s9, s13, 0
	global_load_lds_dwordx4 v[20:21], off
	v_lshl_add_u64 v[20:21], s[8:9], 0, v[132:133]
	s_mov_b32 m0, s10
	s_nop 0
	global_load_lds_dwordx4 v[20:21], off
	v_lshl_add_u64 v[20:21], s[8:9], 0, v[128:129]
	s_mov_b32 m0, s11
	s_nop 0
	global_load_lds_dwordx4 v[20:21], off
	v_lshl_add_u64 v[20:21], v[250:251], 0, s[36:37]
	s_mov_b32 m0, s29
	s_nop 0
	global_load_lds_dwordx4 v[20:21], off
	v_lshl_add_u64 v[20:21], v[198:199], 0, s[36:37]
	s_mov_b32 m0, s38
	s_nop 0
	global_load_lds_dwordx4 v[20:21], off
	s_waitcnt vmcnt(8)
	s_waitcnt lgkmcnt(0)
	s_barrier
	v_mfma_f32_16x16x32_bf16 v[20:23], v[12:15], v[32:35], v[142:145]
	v_mfma_f32_16x16x32_bf16 v[76:79], v[16:19], v[40:43], v[20:23]
	v_mfma_f32_16x16x32_bf16 v[20:23], v[170:173], v[32:35], v[146:149]
	v_mfma_f32_16x16x32_bf16 v[68:71], v[200:203], v[40:43], v[20:23]
	v_mfma_f32_16x16x32_bf16 v[20:23], v[12:15], v[174:177], v[150:153]
	v_mfma_f32_16x16x32_bf16 v[44:47], v[16:19], v[178:181], v[20:23]
	v_mfma_f32_16x16x32_bf16 v[20:23], v[170:173], v[174:177], v[154:157]
	v_mfma_f32_16x16x32_bf16 v[36:39], v[200:203], v[178:181], v[20:23]
	v_mfma_f32_16x16x32_bf16 v[20:23], v[12:15], v[190:193], v[158:161]
	v_mfma_f32_16x16x32_bf16 v[0:3], v[12:15], v[218:221], v[0:3]
	v_mfma_f32_16x16x32_bf16 v[28:31], v[16:19], v[194:197], v[20:23]
	v_mfma_f32_16x16x32_bf16 v[20:23], v[170:173], v[190:193], v[162:165]
	v_mfma_f32_16x16x32_bf16 v[12:15], v[16:19], v[222:225], v[0:3]
	v_mfma_f32_16x16x32_bf16 v[0:3], v[170:173], v[218:221], v[4:7]
	v_mfma_f32_16x16x32_bf16 v[20:23], v[200:203], v[194:197], v[20:23]
	v_mfma_f32_16x16x32_bf16 v[4:7], v[200:203], v[222:225], v[0:3]
	v_mfma_f32_16x16x32_bf16 v[0:3], v[206:209], v[32:35], v[8:11]
	v_mfma_f32_16x16x32_bf16 v[72:75], v[230:233], v[40:43], v[0:3]
	v_mfma_f32_16x16x32_bf16 v[0:3], v[234:237], v[32:35], v[210:213]
	v_mfma_f32_16x16x32_bf16 v[64:67], v[238:241], v[40:43], v[0:3]
	v_mfma_f32_16x16x32_bf16 v[0:3], v[206:209], v[174:177], v[24:27]
	v_mfma_f32_16x16x32_bf16 v[40:43], v[230:233], v[178:181], v[0:3]
	v_mfma_f32_16x16x32_bf16 v[0:3], v[234:237], v[174:177], v[214:217]
	v_mfma_f32_16x16x32_bf16 v[32:35], v[238:241], v[178:181], v[0:3]
	v_mfma_f32_16x16x32_bf16 v[0:3], v[206:209], v[190:193], v[226:229]
	v_mfma_f32_16x16x32_bf16 v[24:27], v[230:233], v[194:197], v[0:3]
	v_mfma_f32_16x16x32_bf16 v[0:3], v[234:237], v[190:193], v[182:185]
	v_mfma_f32_16x16x32_bf16 v[16:19], v[238:241], v[194:197], v[0:3]
	v_mfma_f32_16x16x32_bf16 v[0:3], v[206:209], v[218:221], v[186:189]
	v_mfma_f32_16x16x32_bf16 v[8:11], v[230:233], v[222:225], v[0:3]
	v_mfma_f32_16x16x32_bf16 v[0:3], v[234:237], v[218:221], v[166:169]
	v_mfma_f32_16x16x32_bf16 v[0:3], v[238:241], v[222:225], v[0:3]
	s_barrier
	s_andn2_b64 vcc, exec, s[42:43]
	s_cbranch_vccnz .LBB0_696
	s_barrier

.LBB0_714:
	s_add_u32 s8, s6, 0xfffc0080
	s_addc_u32 s9, s7, -1
	s_add_i32 s35, 0, 0x10000
	s_cmp_eq_u32 s59, 12
	s_cselect_b32 s11, s24, s9
	s_cselect_b32 s10, s51, s8
	v_add_u32_e32 v138, s35, v164
	s_cselect_b32 s9, s49, s58
	s_cselect_b32 s8, s56, s57
	s_add_i32 s66, 0, 0x14000
	ds_read_b128 v[158:161], v138
	ds_read_b128 v[166:169], v138 offset:1024
	ds_read_b128 v[170:173], v138 offset:2048
	ds_read_b128 v[174:177], v138 offset:3072
	v_add_u32_e32 v138, s66, v164
	ds_read_b128 v[178:181], v138
	ds_read_b128 v[182:185], v138 offset:1024
	ds_read_b128 v[206:209], v138 offset:2048
	ds_read_b128 v[210:213], v138 offset:3072
	v_lshl_add_u64 v[138:139], s[6:7], 0, v[134:135]
	s_add_i32 m0, s17, 0xc000
	ds_read_b128 v[214:217], v165
	ds_read_b128 v[218:221], v165 offset:1024
	ds_read_b128 v[222:225], v165 offset:2048
	ds_read_b128 v[226:229], v165 offset:3072
	ds_read_b128 v[230:233], v165 offset:4096
	ds_read_b128 v[234:237], v165 offset:5120
	ds_read_b128 v[238:241], v165 offset:6144
	ds_read_b128 v[242:245], v165 offset:7168
	global_load_lds_dwordx4 v[138:139], off
	v_lshl_add_u64 v[138:139], s[6:7], 0, v[136:137]
	s_add_i32 m0, s17, 0xe000
	s_nop 0
	global_load_lds_dwordx4 v[138:139], off
	s_waitcnt vmcnt(8)
	s_waitcnt lgkmcnt(0)
	s_barrier
	v_mfma_f32_16x16x32_bf16 v[124:127], v[158:161], v[214:217], v[124:127]
	v_mfma_f32_16x16x32_bf16 v[120:123], v[170:173], v[214:217], v[120:123]
	v_mfma_f32_16x16x32_bf16 v[108:111], v[158:161], v[222:225], v[108:111]
	v_mfma_f32_16x16x32_bf16 v[104:107], v[170:173], v[222:225], v[104:107]
	v_mfma_f32_16x16x32_bf16 v[92:95], v[158:161], v[230:233], v[92:95]
	v_mfma_f32_16x16x32_bf16 v[88:91], v[170:173], v[230:233], v[88:91]
	v_mfma_f32_16x16x32_bf16 v[76:79], v[158:161], v[238:241], v[76:79]
	v_mfma_f32_16x16x32_bf16 v[72:75], v[170:173], v[238:241], v[72:75]
	v_mfma_f32_16x16x32_bf16 v[124:127], v[166:169], v[218:221], v[124:127]
	v_mfma_f32_16x16x32_bf16 v[120:123], v[174:177], v[218:221], v[120:123]
	v_mfma_f32_16x16x32_bf16 v[108:111], v[166:169], v[226:229], v[108:111]
	v_mfma_f32_16x16x32_bf16 v[104:107], v[174:177], v[226:229], v[104:107]
	v_mfma_f32_16x16x32_bf16 v[92:95], v[166:169], v[234:237], v[92:95]
	v_mfma_f32_16x16x32_bf16 v[88:91], v[174:177], v[234:237], v[88:91]
	v_mfma_f32_16x16x32_bf16 v[76:79], v[166:169], v[242:245], v[76:79]
	v_mfma_f32_16x16x32_bf16 v[72:75], v[174:177], v[242:245], v[72:75]
	v_mfma_f32_16x16x32_bf16 v[116:119], v[178:181], v[214:217], v[116:119]
	v_mfma_f32_16x16x32_bf16 v[112:115], v[206:209], v[214:217], v[112:115]
	v_mfma_f32_16x16x32_bf16 v[100:103], v[178:181], v[222:225], v[100:103]
	v_mfma_f32_16x16x32_bf16 v[96:99], v[206:209], v[222:225], v[96:99]
	v_mfma_f32_16x16x32_bf16 v[84:87], v[178:181], v[230:233], v[84:87]
	v_mfma_f32_16x16x32_bf16 v[80:83], v[206:209], v[230:233], v[80:83]
	v_mfma_f32_16x16x32_bf16 v[68:71], v[178:181], v[238:241], v[68:71]
	v_mfma_f32_16x16x32_bf16 v[64:67], v[206:209], v[238:241], v[64:67]
	v_mfma_f32_16x16x32_bf16 v[116:119], v[182:185], v[218:221], v[116:119]
	v_mfma_f32_16x16x32_bf16 v[112:115], v[210:213], v[218:221], v[112:115]
	v_mfma_f32_16x16x32_bf16 v[100:103], v[182:185], v[226:229], v[100:103]
	v_mfma_f32_16x16x32_bf16 v[96:99], v[210:213], v[226:229], v[96:99]
	v_mfma_f32_16x16x32_bf16 v[84:87], v[182:185], v[234:237], v[84:87]
	v_mfma_f32_16x16x32_bf16 v[80:83], v[210:213], v[234:237], v[80:83]
	v_mfma_f32_16x16x32_bf16 v[68:71], v[182:185], v[242:245], v[68:71]
	v_mfma_f32_16x16x32_bf16 v[64:67], v[210:213], v[242:245], v[64:67]
	s_barrier
	s_add_i32 s35, s35, s14
	v_lshl_add_u64 v[138:139], s[8:9], 0, v[140:141]
	s_mov_b32 m0, s35
	ds_read_b128 v[214:217], v165 offset:16384
	ds_read_b128 v[218:221], v165 offset:17408
	ds_read_b128 v[222:225], v165 offset:18432
	ds_read_b128 v[226:229], v165 offset:19456
	ds_read_b128 v[230:233], v165 offset:20480
	ds_read_b128 v[234:237], v165 offset:21504
	ds_read_b128 v[238:241], v165 offset:22528
	ds_read_b128 v[242:245], v165 offset:23552
	global_load_lds_dwordx4 v[138:139], off
	s_add_i32 m0, s35, 0x2000
	s_add_u32 s60, s8, 0x40000
	v_lshl_add_u64 v[142:143], s[8:9], 0, v[128:129]
	s_addc_u32 s61, s9, 0
	s_add_i32 s35, s66, s14
	global_load_lds_dwordx4 v[142:143], off
	v_lshl_add_u64 v[144:145], s[60:61], 0, v[140:141]
	s_mov_b32 m0, s35
	v_lshl_add_u64 v[146:147], s[10:11], 0, v[130:131]
	global_load_lds_dwordx4 v[144:145], off
	v_lshl_add_u64 v[144:145], s[60:61], 0, v[128:129]
	s_add_i32 m0, s35, 0x2000
	s_nop 0
	global_load_lds_dwordx4 v[144:145], off
	v_lshl_add_u64 v[144:145], s[10:11], 0, v[132:133]
	s_mov_b32 m0, s17
	s_nop 0
	global_load_lds_dwordx4 v[144:145], off
	s_mov_b32 m0, s25
	s_nop 0
	global_load_lds_dwordx4 v[146:147], off
	s_waitcnt vmcnt(8)
	s_waitcnt lgkmcnt(0)
	s_barrier
	v_mfma_f32_16x16x32_bf16 v[60:63], v[158:161], v[214:217], v[60:63]
	v_mfma_f32_16x16x32_bf16 v[56:59], v[170:173], v[214:217], v[56:59]
	v_mfma_f32_16x16x32_bf16 v[44:47], v[158:161], v[222:225], v[44:47]
	v_mfma_f32_16x16x32_bf16 v[40:43], v[170:173], v[222:225], v[40:43]
	v_mfma_f32_16x16x32_bf16 v[28:31], v[158:161], v[230:233], v[28:31]
	v_mfma_f32_16x16x32_bf16 v[24:27], v[170:173], v[230:233], v[24:27]
	v_mfma_f32_16x16x32_bf16 v[12:15], v[158:161], v[238:241], v[12:15]
	v_mfma_f32_16x16x32_bf16 v[8:11], v[170:173], v[238:241], v[8:11]
	v_mfma_f32_16x16x32_bf16 v[60:63], v[166:169], v[218:221], v[60:63]
	v_mfma_f32_16x16x32_bf16 v[56:59], v[174:177], v[218:221], v[56:59]
	v_mfma_f32_16x16x32_bf16 v[44:47], v[166:169], v[226:229], v[44:47]
	v_mfma_f32_16x16x32_bf16 v[40:43], v[174:177], v[226:229], v[40:43]
	v_mfma_f32_16x16x32_bf16 v[28:31], v[166:169], v[234:237], v[28:31]
	v_mfma_f32_16x16x32_bf16 v[24:27], v[174:177], v[234:237], v[24:27]
	v_mfma_f32_16x16x32_bf16 v[12:15], v[166:169], v[242:245], v[12:15]
	v_mfma_f32_16x16x32_bf16 v[8:11], v[174:177], v[242:245], v[8:11]
	v_mfma_f32_16x16x32_bf16 v[52:55], v[178:181], v[214:217], v[52:55]
	v_mfma_f32_16x16x32_bf16 v[48:51], v[206:209], v[214:217], v[48:51]
	v_mfma_f32_16x16x32_bf16 v[36:39], v[178:181], v[222:225], v[36:39]
	v_mfma_f32_16x16x32_bf16 v[32:35], v[206:209], v[222:225], v[32:35]
	v_mfma_f32_16x16x32_bf16 v[20:23], v[178:181], v[230:233], v[20:23]
	v_mfma_f32_16x16x32_bf16 v[16:19], v[206:209], v[230:233], v[16:19]
	v_mfma_f32_16x16x32_bf16 v[4:7], v[178:181], v[238:241], v[4:7]
	v_mfma_f32_16x16x32_bf16 v[0:3], v[206:209], v[238:241], v[0:3]
	v_mfma_f32_16x16x32_bf16 v[52:55], v[182:185], v[218:221], v[52:55]
	v_mfma_f32_16x16x32_bf16 v[48:51], v[210:213], v[218:221], v[48:51]
	v_mfma_f32_16x16x32_bf16 v[36:39], v[182:185], v[226:229], v[36:39]
	v_mfma_f32_16x16x32_bf16 v[32:35], v[210:213], v[226:229], v[32:35]
	v_mfma_f32_16x16x32_bf16 v[20:23], v[182:185], v[234:237], v[20:23]
	v_mfma_f32_16x16x32_bf16 v[16:19], v[210:213], v[234:237], v[16:19]
	v_mfma_f32_16x16x32_bf16 v[4:7], v[182:185], v[242:245], v[4:7]
	v_mfma_f32_16x16x32_bf16 v[0:3], v[210:213], v[242:245], v[0:3]
	s_barrier
	s_add_i32 s35, 0, 0x18000
	v_add_u32_e32 v148, s35, v164
	s_add_i32 s60, 0, 0x1c000
	ds_read_b128 v[158:161], v148
	ds_read_b128 v[166:169], v148 offset:1024
	ds_read_b128 v[170:173], v148 offset:2048
	ds_read_b128 v[174:177], v148 offset:3072
	v_add_u32_e32 v148, s60, v164
	ds_read_b128 v[178:181], v148
	ds_read_b128 v[182:185], v148 offset:1024
	ds_read_b128 v[206:209], v148 offset:2048
	ds_read_b128 v[210:213], v148 offset:3072
	s_add_u32 s10, s10, 0x40000
	s_addc_u32 s11, s11, 0
	s_mov_b32 m0, s26
	v_lshl_add_u64 v[148:149], s[10:11], 0, v[132:133]
	ds_read_b128 v[214:217], v165 offset:32768
	ds_read_b128 v[218:221], v165 offset:33792
	ds_read_b128 v[222:225], v165 offset:34816
	ds_read_b128 v[226:229], v165 offset:35840
	ds_read_b128 v[230:233], v165 offset:36864
	ds_read_b128 v[234:237], v165 offset:37888
	ds_read_b128 v[238:241], v165 offset:38912
	ds_read_b128 v[242:245], v165 offset:39936
	global_load_lds_dwordx4 v[148:149], off
	v_lshl_add_u64 v[148:149], s[10:11], 0, v[130:131]
	s_mov_b32 m0, s27
	s_nop 0
	global_load_lds_dwordx4 v[148:149], off
	s_waitcnt vmcnt(8)
	s_waitcnt lgkmcnt(0)
	s_barrier
	v_mfma_f32_16x16x32_bf16 v[124:127], v[158:161], v[214:217], v[124:127]
	v_mfma_f32_16x16x32_bf16 v[120:123], v[170:173], v[214:217], v[120:123]
	v_mfma_f32_16x16x32_bf16 v[108:111], v[158:161], v[222:225], v[108:111]
	v_mfma_f32_16x16x32_bf16 v[104:107], v[170:173], v[222:225], v[104:107]
	v_mfma_f32_16x16x32_bf16 v[92:95], v[158:161], v[230:233], v[92:95]
	v_mfma_f32_16x16x32_bf16 v[88:91], v[170:173], v[230:233], v[88:91]
	v_mfma_f32_16x16x32_bf16 v[76:79], v[158:161], v[238:241], v[76:79]
	v_mfma_f32_16x16x32_bf16 v[72:75], v[170:173], v[238:241], v[72:75]
	v_mfma_f32_16x16x32_bf16 v[124:127], v[166:169], v[218:221], v[124:127]
	v_mfma_f32_16x16x32_bf16 v[120:123], v[174:177], v[218:221], v[120:123]
	v_mfma_f32_16x16x32_bf16 v[108:111], v[166:169], v[226:229], v[108:111]
	v_mfma_f32_16x16x32_bf16 v[104:107], v[174:177], v[226:229], v[104:107]
	v_mfma_f32_16x16x32_bf16 v[92:95], v[166:169], v[234:237], v[92:95]
	v_mfma_f32_16x16x32_bf16 v[88:91], v[174:177], v[234:237], v[88:91]
	v_mfma_f32_16x16x32_bf16 v[76:79], v[166:169], v[242:245], v[76:79]
	v_mfma_f32_16x16x32_bf16 v[72:75], v[174:177], v[242:245], v[72:75]
	v_mfma_f32_16x16x32_bf16 v[116:119], v[178:181], v[214:217], v[116:119]
	v_mfma_f32_16x16x32_bf16 v[112:115], v[206:209], v[214:217], v[112:115]
	v_mfma_f32_16x16x32_bf16 v[100:103], v[178:181], v[222:225], v[100:103]
	v_mfma_f32_16x16x32_bf16 v[96:99], v[206:209], v[222:225], v[96:99]
	v_mfma_f32_16x16x32_bf16 v[84:87], v[178:181], v[230:233], v[84:87]
	v_mfma_f32_16x16x32_bf16 v[80:83], v[206:209], v[230:233], v[80:83]
	v_mfma_f32_16x16x32_bf16 v[68:71], v[178:181], v[238:241], v[68:71]
	v_mfma_f32_16x16x32_bf16 v[64:67], v[206:209], v[238:241], v[64:67]
	v_mfma_f32_16x16x32_bf16 v[116:119], v[182:185], v[218:221], v[116:119]
	v_mfma_f32_16x16x32_bf16 v[112:115], v[210:213], v[218:221], v[112:115]
	v_mfma_f32_16x16x32_bf16 v[100:103], v[182:185], v[226:229], v[100:103]
	v_mfma_f32_16x16x32_bf16 v[96:99], v[210:213], v[226:229], v[96:99]
	v_mfma_f32_16x16x32_bf16 v[84:87], v[182:185], v[234:237], v[84:87]
	v_mfma_f32_16x16x32_bf16 v[80:83], v[210:213], v[234:237], v[80:83]
	v_mfma_f32_16x16x32_bf16 v[68:71], v[182:185], v[242:245], v[68:71]
	v_mfma_f32_16x16x32_bf16 v[64:67], v[210:213], v[242:245], v[64:67]
	s_barrier
	s_add_i32 s10, s35, s14
	v_lshl_add_u64 v[138:139], v[138:139], 0, s[36:37]
	s_mov_b32 m0, s10
	ds_read_b128 v[214:217], v165 offset:49152
	ds_read_b128 v[218:221], v165 offset:50176
	ds_read_b128 v[222:225], v165 offset:51200
	ds_read_b128 v[226:229], v165 offset:52224
	ds_read_b128 v[230:233], v165 offset:53248
	ds_read_b128 v[234:237], v165 offset:54272
	ds_read_b128 v[238:241], v165 offset:55296
	ds_read_b128 v[242:245], v165 offset:56320
	global_load_lds_dwordx4 v[138:139], off
	s_add_i32 m0, s10, 0x2000
	s_add_u32 s8, s8, 0x40080
	v_lshl_add_u64 v[138:139], v[142:143], 0, s[36:37]
	s_addc_u32 s9, s9, 0
	s_add_i32 s10, s60, s14
	global_load_lds_dwordx4 v[138:139], off
	v_lshl_add_u64 v[138:139], s[8:9], 0, v[140:141]
	s_mov_b32 m0, s10
	s_nop 0
	global_load_lds_dwordx4 v[138:139], off
	v_lshl_add_u64 v[138:139], s[8:9], 0, v[128:129]
	s_add_i32 m0, s10, 0x2000
	s_nop 0
	global_load_lds_dwordx4 v[138:139], off
	v_lshl_add_u64 v[138:139], v[144:145], 0, s[36:37]
	s_mov_b32 m0, s28
	s_nop 0
	global_load_lds_dwordx4 v[138:139], off
	v_lshl_add_u64 v[138:139], v[146:147], 0, s[36:37]
	s_mov_b32 m0, s29
	s_nop 0
	global_load_lds_dwordx4 v[138:139], off
	s_waitcnt vmcnt(8)
	s_waitcnt lgkmcnt(0)
	s_barrier
	v_mfma_f32_16x16x32_bf16 v[60:63], v[158:161], v[214:217], v[60:63]
	v_mfma_f32_16x16x32_bf16 v[56:59], v[170:173], v[214:217], v[56:59]
	v_mfma_f32_16x16x32_bf16 v[44:47], v[158:161], v[222:225], v[44:47]
	v_mfma_f32_16x16x32_bf16 v[40:43], v[170:173], v[222:225], v[40:43]
	v_mfma_f32_16x16x32_bf16 v[28:31], v[158:161], v[230:233], v[28:31]
	v_mfma_f32_16x16x32_bf16 v[24:27], v[170:173], v[230:233], v[24:27]
	v_mfma_f32_16x16x32_bf16 v[12:15], v[158:161], v[238:241], v[12:15]
	v_mfma_f32_16x16x32_bf16 v[8:11], v[170:173], v[238:241], v[8:11]
	v_mfma_f32_16x16x32_bf16 v[60:63], v[166:169], v[218:221], v[60:63]
	v_mfma_f32_16x16x32_bf16 v[56:59], v[174:177], v[218:221], v[56:59]
	v_mfma_f32_16x16x32_bf16 v[44:47], v[166:169], v[226:229], v[44:47]
	v_mfma_f32_16x16x32_bf16 v[40:43], v[174:177], v[226:229], v[40:43]
	v_mfma_f32_16x16x32_bf16 v[28:31], v[166:169], v[234:237], v[28:31]
	v_mfma_f32_16x16x32_bf16 v[24:27], v[174:177], v[234:237], v[24:27]
	v_mfma_f32_16x16x32_bf16 v[12:15], v[166:169], v[242:245], v[12:15]
	v_mfma_f32_16x16x32_bf16 v[8:11], v[174:177], v[242:245], v[8:11]
	v_mfma_f32_16x16x32_bf16 v[52:55], v[178:181], v[214:217], v[52:55]
	v_mfma_f32_16x16x32_bf16 v[48:51], v[206:209], v[214:217], v[48:51]
	v_mfma_f32_16x16x32_bf16 v[36:39], v[178:181], v[222:225], v[36:39]
	v_mfma_f32_16x16x32_bf16 v[32:35], v[206:209], v[222:225], v[32:35]
	v_mfma_f32_16x16x32_bf16 v[20:23], v[178:181], v[230:233], v[20:23]
	v_mfma_f32_16x16x32_bf16 v[16:19], v[206:209], v[230:233], v[16:19]
	v_mfma_f32_16x16x32_bf16 v[4:7], v[178:181], v[238:241], v[4:7]
	v_mfma_f32_16x16x32_bf16 v[0:3], v[206:209], v[238:241], v[0:3]
	v_mfma_f32_16x16x32_bf16 v[52:55], v[182:185], v[218:221], v[52:55]
	v_mfma_f32_16x16x32_bf16 v[48:51], v[210:213], v[218:221], v[48:51]
	v_mfma_f32_16x16x32_bf16 v[36:39], v[182:185], v[226:229], v[36:39]
	v_mfma_f32_16x16x32_bf16 v[32:35], v[210:213], v[226:229], v[32:35]
	v_mfma_f32_16x16x32_bf16 v[20:23], v[182:185], v[234:237], v[20:23]
	v_mfma_f32_16x16x32_bf16 v[16:19], v[210:213], v[234:237], v[16:19]
	v_mfma_f32_16x16x32_bf16 v[4:7], v[182:185], v[242:245], v[4:7]
	v_mfma_f32_16x16x32_bf16 v[0:3], v[210:213], v[242:245], v[0:3]
	s_barrier
	s_add_i32 s59, s59, 2
	s_add_u32 s6, s6, 0x100
	s_addc_u32 s7, s7, 0
	s_add_u32 s57, s57, 0x100
	s_addc_u32 s58, s58, 0
	s_cmp_gt_u32 s59, 13
	s_cbranch_scc0 .LBB0_714
	s_and_b64 vcc, exec, s[46:47]
	s_cbranch_vccz .LBB0_717
	s_barrier
